# P6 conv: copy propagation + dead v_mov elimination after the fma fusion (62 copies removed); P8: 9 packed square+add pairs to mul+fma
# speedup vs baseline: 1.0016x; 1.0016x over previous
; __device__ __forceinline__ float silu_f(float x) { return x * __builtin_amdgcn_rcpf(1.0f + __builtin_amdgcn_exp2f(-1.4426950408889634f * x)); }
; __device__ __forceinline__ float bflo(unsigned x) { return __uint_as_float(x << 16); }
; __device__ __forceinline__ float bfhi(unsigned x) { return __uint_as_float(x & 0xffff0000u); }
; __device__ __forceinline__ unsigned pk2(float lo, float hi) { return pg8::cvt_pk_bf16(lo, hi); }
; __device__ __forceinline__ float silu_f(float x) { return x * __builtin_amdgcn_rcpf(1.0f + __builtin_amdgcn_exp2f(-1.4426950408889634f * x)); }
; __device__ __forceinline__ void ph_conv(const bf16* XBC, const float* state_conv, const float* conv_w, const float* conv_b, bf16* XT, bf16* BN, bf16* CN, bf16* BT, int c_lo, int c_hi, int vcu, int G, int tid) {
;     ...
;         for (int t8 = 0; t8 < 2; ++t8) {
;             float y0[8], y1[8];
; #pragma unroll
;             for (int i = 0; i < 8; ++i) { const float x0 = bflo(raw[3 + t8 * 8 + i]), x1 = bfhi(raw[3 + t8 * 8 + i]);
;                 const float a0 = b0 + w0[0] * p0[0] + w0[1] * p0[1] + w0[2] * p0[2] + w0[3] * x0, a1 = b1 + w1[0] * p1[0] + w1[1] * p1[1] + w1[2] * p1[2] + w1[3] * x1;
;                 y0[i] = silu_f(a0); y1[i] = silu_f(a1); p0[0] = p0[1]; p0[1] = p0[2]; p0[2] = x0; p1[0] = p1[1]; p1[1] = p1[2]; p1[2] = x1; }
;             v4u t0, t1; t0.x = pk2(y0[0], y0[1]); t0.y = pk2(y0[2], y0[3]); t0.z = pk2(y0[4], y0[5]); t0.w = pk2(y0[6], y0[7]);
;             t1.x = pk2(y1[0], y1[1]); t1.y = pk2(y1[2], y1[3]); t1.z = pk2(y1[4], y1[5]); t1.w = pk2(y1[6], y1[7]);
;             const int tl = q * 16 + t8 * 8;
;             if (tid < 256) { const int h = ch >> 6, p = ch & 63; bf16* d = XT + ((size_t)(ci * 8 + h) * 64 + p) * 64 + tl; *(v4u*)d = t0; *(v4u*)(d + 64) = t1; }
.LBB0_801:
	v_lshlrev_b32_e32 v80, 16, v0
	v_and_b32_e32 v82, 0xffff0000, v0
	v_fma_f32 v0, v14, v6, v18
	v_mov_b32_e32 v81, v5
	v_fma_f32 v0, v15, v7, v0
	v_mov_b32_e32 v83, v1
	v_fma_f32 v0, v11, v81, v0
	v_fma_f32 v6, v10, v80, v0
	s_ashr_i32 s37, s22, 2
	v_fma_f32 v0, v36, v2, v19
	v_fma_f32 v0, v37, v3, v0
	v_lshl_add_u32 v38, s37, 1, v50
	v_fma_f32 v0, v33, v83, v0
	v_fma_f32 v2, v32, v82, v0
	v_mul_f32_e32 v0, 0xbfb8aa3b, v6
	v_exp_f32_e32 v0, v0
	v_mul_f32_e32 v4, 0xbfb8aa3b, v2
	v_exp_f32_e32 v4, v4
	v_ashrrev_i32_e32 v39, 31, v38
	v_add_f32_e32 v0, 1.0, v0
	v_rcp_f32_e32 v47, v0
	v_add_f32_e32 v0, 1.0, v4
	v_rcp_f32_e32 v49, v0
	v_fma_f32 v4, v14, v7, v18
	v_fma_f32 v79, v15, v5, v4
	v_lshlrev_b32_e32 v5, 16, v46
	v_mov_b32_e32 v0, v3
	v_mul_f32_e32 v48, v6, v47
	v_mov_b32_e32 v7, v80
	v_and_b32_e32 v3, 0xffff0000, v46
	v_mul_f32_e32 v49, v2, v49
	v_and_b32_e32 v2, 0xffff0000, v41
	v_fma_f32 v0, v36, v0, v19
	v_lshlrev_b32_e32 v4, 16, v41
	v_fma_f32 v41, v11, v7, v79
	v_fma_f32 v84, v37, v1, v0
	v_fma_f32 v41, v10, v5, v41
	v_fma_f32 v1, v35, v81, v18
	v_mul_f32_e32 v46, 0xbfb8aa3b, v41
	v_fma_f32 v81, v34, v80, v1
	v_exp_f32_e32 v79, v46
	v_fma_f32 v47, v11, v5, v81
	v_fma_f32 v46, v10, v4, v47
	v_mul_f32_e32 v47, 0xbfb8aa3b, v46
	v_exp_f32_e32 v47, v47
	v_fma_f32 v1, v31, v83, v19
	v_fma_f32 v81, v30, v82, v1
	v_add_f32_e32 v0, 1.0, v79
	v_rcp_f32_e32 v79, v0
	v_add_f32_e32 v0, 1.0, v47
	v_rcp_f32_e32 v47, v0
	v_mul_f32_e32 v80, v41, v79
	v_fma_f32 v7, v35, v7, v18
	v_fma_f32 v83, v34, v5, v7
	v_mov_b32_e32 v6, v3
	v_mov_b32_e32 v7, v82
	v_mul_f32_e32 v79, v46, v47
	v_pk_mul_f32 v[46:47], v[32:33], v[6:7]
	v_add_f32_e32 v41, v47, v84
	v_add_f32_e32 v41, v46, v41
	v_mul_f32_e32 v46, 0xbfb8aa3b, v41
	v_exp_f32_e32 v82, v46
	v_fma_f32 v7, v31, v7, v19
	v_fma_f32 v47, v33, v3, v81
	v_fma_f32 v81, v32, v2, v47
	v_mul_f32_e32 v46, 0xbfb8aa3b, v81
	v_exp_f32_e32 v84, v46
	v_fma_f32 v87, v30, v6, v7
	v_add_f32_e32 v82, 1.0, v82
	v_add_f32_e32 v84, 1.0, v84
	v_fma_f32 v7, v31, v3, v19
	v_rcp_f32_e32 v82, v82
	v_rcp_f32_e32 v85, v84
	v_fma_f32 v47, v35, v5, v18
	v_fma_f32 v88, v30, v2, v7
	v_lshlrev_b32_e32 v7, 16, v40
	v_fma_f32 v86, v34, v4, v47
	v_mul_f32_e32 v84, v41, v82
	v_fma_f32 v6, v12, v4, v83
	v_mul_f32_e32 v82, v81, v85
	v_fma_f32 v81, v13, v7, v6
	v_mul_f32_e32 v6, 0xbfb8aa3b, v81
	v_exp_f32_e32 v46, v6
	v_lshlrev_b32_e32 v6, 16, v45
	v_and_b32_e32 v0, 0xffff0000, v45
	v_pk_mov_b32 v[4:5], v[6:7], v[4:5] op_sel:[1,0]
	v_add_f32_e32 v45, 1.0, v46
	v_fma_f32 v47, v11, v7, v86
	v_fma_f32 v46, v10, v6, v47
	v_mul_f32_e32 v47, 0xbfb8aa3b, v46
	v_and_b32_e32 v41, 0xffff0000, v43
	v_lshlrev_b32_e32 v43, 16, v43
	v_exp_f32_e32 v47, v47
	v_fma_f32 v5, v35, v5, v18
	v_fma_f32 v83, v34, v4, v5
	v_add_f32_e32 v47, 1.0, v47
	v_fma_f32 v4, v12, v6, v83
	v_fma_f32 v4, v13, v43, v4
	v_mul_f32_e32 v5, 0xbfb8aa3b, v4
	v_rcp_f32_e32 v47, v47
	v_exp_f32_e32 v5, v5
	v_and_b32_e32 v1, 0xffff0000, v40
	v_rcp_f32_e32 v45, v45
	v_mul_f32_e32 v83, v46, v47
	v_add_f32_e32 v5, 1.0, v5
	v_rcp_f32_e32 v5, v5
	v_fma_f32 v46, v28, v2, v87
	v_fma_f32 v86, v29, v1, v46
	v_mul_f32_e32 v46, 0xbfb8aa3b, v86
	v_exp_f32_e32 v87, v46
	v_mul_f32_e32 v85, v81, v45
	v_mul_f32_e32 v81, v4, v5
	v_pk_mov_b32 v[2:3], v[0:1], v[2:3] op_sel:[1,0]
	v_and_b32_e32 v40, 0xffff0000, v42
	v_lshlrev_b32_e32 v42, 16, v42
	v_fma_f32 v5, v35, v7, v18
	v_fma_f32 v45, v34, v6, v5
	v_fma_f32 v3, v31, v3, v19
	v_fma_f32 v5, v11, v43, v45
	v_add_f32_e32 v45, 1.0, v87
	v_fma_f32 v87, v30, v2, v3
	v_fma_f32 v2, v28, v0, v87
	v_fma_f32 v47, v33, v1, v88
	v_fma_f32 v88, v29, v41, v2
	v_mul_f32_e32 v2, 0xbfb8aa3b, v88
	v_exp_f32_e32 v2, v2
	v_rcp_f32_e32 v45, v45
	v_fma_f32 v4, v10, v42, v5
	v_fma_f32 v46, v32, v0, v47
	v_add_f32_e32 v2, 1.0, v2
	v_rcp_f32_e32 v5, v2
	v_mul_f32_e32 v47, 0xbfb8aa3b, v46
	v_fma_f32 v3, v31, v1, v19
	v_mul_f32_e32 v90, v86, v45
	v_fma_f32 v45, v30, v0, v3
	v_exp_f32_e32 v47, v47
	v_fma_f32 v3, v33, v41, v45
	v_fma_f32 v89, v32, v40, v3
	v_mul_f32_e32 v2, 0xbfb8aa3b, v4
	v_exp_f32_e32 v2, v2
	v_mul_f32_e32 v3, 0xbfb8aa3b, v89
	v_exp_f32_e32 v3, v3
	v_add_f32_e32 v47, 1.0, v47
	v_rcp_f32_e32 v47, v47
	v_add_f32_e32 v2, 1.0, v2
	v_mul_f32_e32 v86, v88, v5
	v_rcp_f32_e32 v5, v2
	v_add_f32_e32 v88, 1.0, v3
	v_pk_mov_b32 v[2:3], v[42:43], v[6:7] op_sel:[1,0]
	v_mul_f32_e32 v87, v46, v47
	v_lshlrev_b32_e32 v47, 16, v44
	v_fma_f32 v3, v35, v3, v18
	v_pk_mov_b32 v[0:1], v[40:41], v[0:1] op_sel:[1,0]
	v_fma_f32 v6, v34, v2, v3
	v_and_b32_e32 v45, 0xffff0000, v44
	v_fma_f32 v2, v12, v42, v6
	v_fma_f32 v1, v31, v1, v19
	v_fma_f32 v2, v13, v47, v2
	v_fma_f32 v3, v30, v0, v1
	v_rcp_f32_e32 v6, v88
	v_fma_f32 v0, v28, v40, v3
	v_fma_f32 v0, v29, v45, v0
	v_mul_f32_e32 v1, 0xbfb8aa3b, v2
	v_mul_f32_e32 v3, 0xbfb8aa3b, v0
	v_exp_f32_e32 v1, v1
	v_exp_f32_e32 v3, v3
	s_lshl_b32 s18, s37, 6
	s_and_b32 s36, s33, 48
	v_add_f32_e32 v1, 1.0, v1
	v_add_f32_e32 v3, 1.0, v3
	v_rcp_f32_e32 v1, v1
	v_rcp_f32_e32 v3, v3
	v_lshlrev_b64 v[38:39], 14, v[38:39]
	s_or_b32 s22, s18, s36
	v_lshl_add_u64 v[38:39], v[24:25], 0, v[38:39]
	v_mul_f32_e32 v88, v4, v5
	v_mul_f32_e32 v89, v89, v6
	v_mul_f32_e32 v44, v2, v1
	v_mul_f32_e32 v46, v0, v3
	v_cvt_pk_bf16_f32 v0, v48, v80
	v_cvt_pk_bf16_f32 v1, v79, v85
	v_cvt_pk_bf16_f32 v2, v83, v81
	v_cvt_pk_bf16_f32 v3, v88, v44
	v_cvt_pk_bf16_f32 v4, v49, v84
	v_cvt_pk_bf16_f32 v5, v82, v90
	v_cvt_pk_bf16_f32 v6, v87, v86
	v_cvt_pk_bf16_f32 v7, v89, v46
	s_and_saveexec_b64 s[24:25], s[2:3]
	s_xor_b64 s[24:25], exec, s[24:25]
	s_cbranch_execz .LBB0_807
; __device__ __forceinline__ unsigned pk2(float lo, float hi) { return pg8::cvt_pk_bf16(lo, hi); }
; __device__ __forceinline__ void ph_conv(const bf16* XBC, const float* state_conv, const float* conv_w, const float* conv_b, bf16* XT, bf16* BN, bf16* CN, bf16* BT, int c_lo, int c_hi, int vcu, int G, int tid) {
;     ...
;             else if (tid < 384) { const int cb = ch - 512, g = cb >> 7, n = cb & 127;
; #pragma unroll
;                 for (int i = 0; i < 8; ++i) *(unsigned*)(BN + (size_t)(row0 + t8 * 8 + i) * 256 + cb) = pk2(y0[i], y1[i]);
;                 bf16* d = BT + ((size_t)(ci * 2 + g) * 128 + n) * 64 + tl; *(v4u*)d = t0; *(v4u*)(d + 64) = t1; }
;             else { const int cc = ch - 768;
; #pragma unroll
;                 for (int i = 0; i < 8; ++i) *(unsigned*)(CN + (size_t)(row0 + t8 * 8 + i) * 256 + cc) = pk2(y0[i], y1[i]); }
	s_ashr_i32 s23, s22, 31
	s_lshl_b64 s[26:27], s[22:23], 9
	s_and_saveexec_b64 s[28:29], s[4:5]
	s_xor_b64 s[28:29], exec, s[28:29]
	s_cbranch_execz .LBB0_804
	s_or_b32 s38, s22, 1
	s_ashr_i32 s39, s38, 31
	v_lshl_add_u64 v[0:1], v[20:21], 0, s[26:27]
	s_lshl_b64 s[38:39], s[38:39], 9
	v_cvt_pk_bf16_f32 v2, v48, v49
	global_store_dword v[0:1], v2, off offset:-1536
	v_lshl_add_u64 v[0:1], v[20:21], 0, s[38:39]
	s_or_b32 s38, s22, 2
	s_ashr_i32 s39, s38, 31
	s_lshl_b64 s[38:39], s[38:39], 9
	v_cvt_pk_bf16_f32 v2, v80, v84
	global_store_dword v[0:1], v2, off offset:-1536
	v_lshl_add_u64 v[0:1], v[20:21], 0, s[38:39]
	s_or_b32 s38, s22, 3
	s_ashr_i32 s39, s38, 31
	s_lshl_b64 s[38:39], s[38:39], 9
	v_cvt_pk_bf16_f32 v2, v79, v82
	global_store_dword v[0:1], v2, off offset:-1536
	v_lshl_add_u64 v[0:1], v[20:21], 0, s[38:39]
	s_or_b32 s38, s22, 4
	s_ashr_i32 s39, s38, 31
	s_lshl_b64 s[38:39], s[38:39], 9
	v_cvt_pk_bf16_f32 v2, v85, v90
	global_store_dword v[0:1], v2, off offset:-1536
	v_lshl_add_u64 v[0:1], v[20:21], 0, s[38:39]
	s_or_b32 s38, s22, 5
	s_ashr_i32 s39, s38, 31
	s_lshl_b64 s[38:39], s[38:39], 9
	v_cvt_pk_bf16_f32 v2, v83, v87
	global_store_dword v[0:1], v2, off offset:-1536
	v_lshl_add_u64 v[0:1], v[20:21], 0, s[38:39]
	s_or_b32 s38, s22, 6
	s_ashr_i32 s39, s38, 31
	s_lshl_b64 s[38:39], s[38:39], 9
	v_cvt_pk_bf16_f32 v2, v81, v86
	global_store_dword v[0:1], v2, off offset:-1536
	v_lshl_add_u64 v[0:1], v[20:21], 0, s[38:39]
	s_or_b32 s38, s22, 7
	s_ashr_i32 s39, s38, 31
	v_cvt_pk_bf16_f32 v2, v88, v89
	s_lshl_b64 s[38:39], s[38:39], 9
	global_store_dword v[0:1], v2, off offset:-1536
	v_cvt_pk_bf16_f32 v2, v44, v46
	v_lshl_add_u64 v[0:1], v[20:21], 0, s[38:39]
	global_store_dword v[0:1], v2, off offset:-1536

; __device__ __forceinline__ float silu_f(float x) { return x * __builtin_amdgcn_rcpf(1.0f + __builtin_amdgcn_exp2f(-1.4426950408889634f * x)); }
; __device__ __forceinline__ float bflo(unsigned x) { return __uint_as_float(x << 16); }
; __device__ __forceinline__ float bfhi(unsigned x) { return __uint_as_float(x & 0xffff0000u); }
; __device__ __forceinline__ unsigned pk2(float lo, float hi) { return pg8::cvt_pk_bf16(lo, hi); }
; __device__ __forceinline__ float silu_f(float x) { return x * __builtin_amdgcn_rcpf(1.0f + __builtin_amdgcn_exp2f(-1.4426950408889634f * x)); }
; __device__ __forceinline__ void ph_conv(const bf16* XBC, const float* state_conv, const float* conv_w, const float* conv_b, bf16* XT, bf16* BN, bf16* CN, bf16* BT, int c_lo, int c_hi, int vcu, int G, int tid) {
;     ...
;         for (int t8 = 0; t8 < 2; ++t8) {
;             float y0[8], y1[8];
; #pragma unroll
;             for (int i = 0; i < 8; ++i) { const float x0 = bflo(raw[3 + t8 * 8 + i]), x1 = bfhi(raw[3 + t8 * 8 + i]);
;                 const float a0 = b0 + w0[0] * p0[0] + w0[1] * p0[1] + w0[2] * p0[2] + w0[3] * x0, a1 = b1 + w1[0] * p1[0] + w1[1] * p1[1] + w1[2] * p1[2] + w1[3] * x1;
;                 y0[i] = silu_f(a0); y1[i] = silu_f(a1); p0[0] = p0[1]; p0[1] = p0[2]; p0[2] = x0; p1[0] = p1[1]; p1[1] = p1[2]; p1[2] = x1; }
;             v4u t0, t1; t0.x = pk2(y0[0], y0[1]); t0.y = pk2(y0[2], y0[3]); t0.z = pk2(y0[4], y0[5]); t0.w = pk2(y0[6], y0[7]);
;             t1.x = pk2(y1[0], y1[1]); t1.y = pk2(y1[2], y1[3]); t1.z = pk2(y1[4], y1[5]); t1.w = pk2(y1[6], y1[7]);
.LBB0_809:
	s_or_b64 exec, exec, s[24:25]
	s_nop 0
	v_lshlrev_b32_e32 v1, 16, v78
	v_fma_f32 v0, v35, v43, v18
	v_fma_f32 v2, v34, v42, v0
	v_and_b32_e32 v3, 0xffff0000, v78
	v_fma_f32 v0, v12, v47, v2
	v_fma_f32 v0, v13, v1, v0
	v_fma_f32 v2, v31, v41, v19
	v_fma_f32 v6, v30, v40, v2
	v_fma_f32 v2, v28, v45, v6
	v_mul_f32_e32 v4, 0xbfb8aa3b, v0
	v_exp_f32_e32 v4, v4
	v_fma_f32 v2, v29, v3, v2
	v_mul_f32_e32 v5, 0xbfb8aa3b, v2
	v_exp_f32_e32 v5, v5
	v_add_f32_e32 v4, 1.0, v4
	v_rcp_f32_e32 v4, v4
	v_add_f32_e32 v5, 1.0, v5
	v_rcp_f32_e32 v5, v5
	v_mul_f32_e32 v41, v0, v4
	v_fma_f32 v0, v35, v42, v18
	v_fma_f32 v0, v34, v47, v0
	v_mul_f32_e32 v43, v2, v5
	v_fma_f32 v2, v31, v40, v19
	v_fma_f32 v2, v30, v45, v2
	v_mov_b32_e32 v44, v3
	v_fma_f32 v7, v35, v47, v18
	v_lshlrev_b32_e32 v47, 16, v77
	v_fma_f32 v40, v34, v1, v7
	v_pk_mul_f32 v[6:7], v[30:31], v[44:45]
	v_lshlrev_b32_e32 v46, 16, v76
	v_fma_f32 v0, v12, v1, v0
	v_fma_f32 v0, v13, v47, v0
	v_mul_f32_e32 v42, 0xbfb8aa3b, v0
	v_exp_f32_e32 v42, v42
	v_add_f32_e32 v7, v19, v7
	v_and_b32_e32 v5, 0xffff0000, v77
	v_fma_f32 v40, v11, v47, v40
	v_add_f32_e32 v45, v6, v7
	v_add_f32_e32 v6, 1.0, v42
	v_rcp_f32_e32 v42, v6
	v_fma_f32 v40, v10, v46, v40
	v_mul_f32_e32 v44, 0xbfb8aa3b, v40
	v_exp_f32_e32 v44, v44
	v_mul_f32_e32 v42, v0, v42
	v_add_f32_e32 v6, 1.0, v44
	v_fma_f32 v1, v35, v1, v18
	v_fma_f32 v77, v34, v47, v1
	v_rcp_f32_e32 v44, v6
	v_and_b32_e32 v4, 0xffff0000, v76
	v_fma_f32 v0, v28, v3, v2
	v_fma_f32 v2, v29, v5, v0
	v_mul_f32_e32 v0, 0xbfb8aa3b, v2
	v_mul_f32_e32 v40, v40, v44
	v_exp_f32_e32 v44, v0
	v_and_b32_e32 v7, 0xffff0000, v75
	v_fma_f32 v1, v33, v5, v45
	v_fma_f32 v45, v32, v4, v1
	v_mul_f32_e32 v0, 0xbfb8aa3b, v45
	v_exp_f32_e32 v76, v0
	v_add_f32_e32 v44, 1.0, v44
	v_rcp_f32_e32 v44, v44
	v_add_f32_e32 v76, 1.0, v76
	v_rcp_f32_e32 v78, v76
	v_fma_f32 v1, v35, v47, v18
	v_mul_f32_e32 v76, v2, v44
	v_mov_b32_e32 v2, v5
	v_fma_f32 v80, v34, v46, v1
	v_pk_mul_f32 v[0:1], v[30:31], v[2:3]
	v_lshlrev_b32_e32 v3, 16, v75
	v_mul_f32_e32 v44, v45, v78
	v_add_f32_e32 v1, v19, v1
	v_fma_f32 v2, v12, v46, v77
	v_fma_f32 v45, v13, v3, v2
	v_mul_f32_e32 v2, 0xbfb8aa3b, v45
	v_exp_f32_e32 v75, v2
	v_add_f32_e32 v81, v0, v1
	v_lshlrev_b32_e32 v2, 16, v74
	v_fma_f32 v1, v31, v5, v19
	v_fma_f32 v77, v30, v4, v1
	v_add_f32_e32 v0, 1.0, v75
	v_and_b32_e32 v6, 0xffff0000, v74
	v_rcp_f32_e32 v74, v0
	v_pk_mov_b32 v[46:47], v[2:3], v[46:47] op_sel:[1,0]
	v_fma_f32 v1, v11, v3, v80
	v_fma_f32 v79, v10, v2, v1
	v_mul_f32_e32 v0, 0xbfb8aa3b, v79
	v_exp_f32_e32 v75, v0
	v_mul_f32_e32 v45, v45, v74
	v_lshlrev_b32_e32 v78, 16, v73
	v_add_f32_e32 v74, 1.0, v75
	v_rcp_f32_e32 v80, v74
	v_fma_f32 v47, v35, v47, v18
	v_pk_mul_f32 v[74:75], v[34:35], v[2:3]
	v_mov_b32_e32 v3, v78
	v_fma_f32 v82, v34, v46, v47
	v_pk_mul_f32 v[46:47], v[12:13], v[2:3]
	v_and_b32_e32 v0, 0xffff0000, v73
	v_add_f32_e32 v3, v46, v82
	v_add_f32_e32 v3, v3, v47
	v_mul_f32_e32 v46, 0xbfb8aa3b, v3
	v_add_f32_e32 v73, v18, v75
	v_exp_f32_e32 v46, v46
	v_mul_f32_e32 v47, v79, v80
	v_add_f32_e32 v80, v74, v73
	v_add_f32_e32 v46, 1.0, v46
	v_fma_f32 v73, v28, v4, v81
	v_fma_f32 v81, v29, v7, v73
	v_mul_f32_e32 v73, 0xbfb8aa3b, v81
	v_rcp_f32_e32 v46, v46
	v_exp_f32_e32 v74, v73
	v_lshlrev_b32_e32 v79, 16, v72
	v_pk_mov_b32 v[4:5], v[6:7], v[4:5] op_sel:[1,0]
	v_mul_f32_e32 v46, v3, v46
	v_add_f32_e32 v3, 1.0, v74
	v_rcp_f32_e32 v3, v3
	v_fma_f32 v75, v33, v7, v77
	v_fma_f32 v77, v32, v6, v75
	v_mul_f32_e32 v74, 0xbfb8aa3b, v77
	v_exp_f32_e32 v74, v74
	v_and_b32_e32 v1, 0xffff0000, v72
	v_fma_f32 v72, v12, v78, v80
	v_fma_f32 v5, v31, v5, v19
	v_fma_f32 v82, v13, v79, v72
	v_fma_f32 v72, v30, v4, v5
	v_pk_mul_f32 v[4:5], v[30:31], v[6:7]
	v_mov_b32_e32 v7, v0
	v_mul_f32_e32 v73, v81, v3
	v_add_f32_e32 v3, 1.0, v74
	v_pk_mul_f32 v[74:75], v[28:29], v[6:7]
	v_rcp_f32_e32 v3, v3
	v_add_f32_e32 v7, v74, v72
	v_add_f32_e32 v7, v7, v75
	v_mul_f32_e32 v72, 0xbfb8aa3b, v7
	v_exp_f32_e32 v72, v72
	v_mul_f32_e32 v75, v77, v3
	v_add_f32_e32 v3, v19, v5
	v_add_f32_e32 v3, v4, v3
	v_add_f32_e32 v4, 1.0, v72
	v_rcp_f32_e32 v72, v4
	v_mov_b32_e32 v80, v78
	v_fma_f32 v3, v28, v0, v3
	v_fma_f32 v74, v29, v1, v3
	v_mul_f32_e32 v3, 0xbfb8aa3b, v82
	v_exp_f32_e32 v3, v3
	v_mul_f32_e32 v4, 0xbfb8aa3b, v74
	v_exp_f32_e32 v4, v4
	v_mov_b32_e32 v81, v2
	v_pk_mul_f32 v[80:81], v[34:35], v[80:81]
	v_add_f32_e32 v3, 1.0, v3
	v_add_f32_e32 v2, v18, v81
	v_mul_f32_e32 v72, v7, v72
	v_rcp_f32_e32 v7, v3
	v_add_f32_e32 v77, 1.0, v4
	v_lshlrev_b32_e32 v3, 16, v71
	v_add_f32_e32 v4, v80, v2
	v_and_b32_e32 v5, 0xffff0000, v71
	v_fma_f32 v2, v12, v79, v4
	v_fma_f32 v71, v13, v3, v2
	v_mov_b32_e32 v2, v0
	v_fma_f32 v0, v31, v6, v19
	v_fma_f32 v2, v30, v2, v0
	v_rcp_f32_e32 v3, v77
	v_fma_f32 v0, v28, v1, v2
	v_fma_f32 v0, v29, v5, v0
	v_mul_f32_e32 v1, 0xbfb8aa3b, v71
	v_mul_f32_e32 v2, 0xbfb8aa3b, v0
	v_exp_f32_e32 v1, v1
	v_exp_f32_e32 v2, v2
	v_mul_f32_e32 v77, v82, v7
	v_mul_f32_e32 v78, v74, v3
	v_add_f32_e32 v1, 1.0, v1
	v_add_f32_e32 v2, 1.0, v2
	v_rcp_f32_e32 v1, v1
	v_rcp_f32_e32 v2, v2
	v_mul_f32_e32 v71, v71, v1
	v_mul_f32_e32 v74, v0, v2
	v_cvt_pk_bf16_f32 v0, v41, v42
	v_cvt_pk_bf16_f32 v1, v40, v45
	v_cvt_pk_bf16_f32 v2, v47, v46
	v_cvt_pk_bf16_f32 v3, v77, v71
	v_cvt_pk_bf16_f32 v4, v43, v76
	v_cvt_pk_bf16_f32 v5, v44, v73
	v_cvt_pk_bf16_f32 v6, v75, v72
	v_cvt_pk_bf16_f32 v7, v78, v74
	s_and_saveexec_b64 s[24:25], s[2:3]
	s_xor_b64 s[24:25], exec, s[24:25]
	s_cbranch_execz .LBB0_815
; __device__ __forceinline__ unsigned pk2(float lo, float hi) { return pg8::cvt_pk_bf16(lo, hi); }
; __device__ __forceinline__ void ph_conv(const bf16* XBC, const float* state_conv, const float* conv_w, const float* conv_b, bf16* XT, bf16* BN, bf16* CN, bf16* BT, int c_lo, int c_hi, int vcu, int G, int tid) {
;     ...
;             else if (tid < 384) { const int cb = ch - 512, g = cb >> 7, n = cb & 127;
; #pragma unroll
;                 for (int i = 0; i < 8; ++i) *(unsigned*)(BN + (size_t)(row0 + t8 * 8 + i) * 256 + cb) = pk2(y0[i], y1[i]);
;                 bf16* d = BT + ((size_t)(ci * 2 + g) * 128 + n) * 64 + tl; *(v4u*)d = t0; *(v4u*)(d + 64) = t1; }
;             else { const int cc = ch - 768;
; #pragma unroll
;                 for (int i = 0; i < 8; ++i) *(unsigned*)(CN + (size_t)(row0 + t8 * 8 + i) * 256 + cc) = pk2(y0[i], y1[i]); }
	s_or_b32 s26, s22, 8
	s_ashr_i32 s27, s26, 31
	s_lshl_b64 s[26:27], s[26:27], 9
	s_and_saveexec_b64 s[28:29], s[4:5]
	s_xor_b64 s[28:29], exec, s[28:29]
	s_cbranch_execz .LBB0_812
	s_or_b32 s38, s22, 9
	s_ashr_i32 s39, s38, 31
	v_lshl_add_u64 v[0:1], v[20:21], 0, s[26:27]
	s_lshl_b64 s[38:39], s[38:39], 9
	v_cvt_pk_bf16_f32 v2, v41, v43
	global_store_dword v[0:1], v2, off offset:-1536
	v_lshl_add_u64 v[0:1], v[20:21], 0, s[38:39]
	s_or_b32 s38, s22, 10
	s_ashr_i32 s39, s38, 31
	s_lshl_b64 s[38:39], s[38:39], 9
	v_cvt_pk_bf16_f32 v2, v42, v76
	global_store_dword v[0:1], v2, off offset:-1536
	v_lshl_add_u64 v[0:1], v[20:21], 0, s[38:39]
	s_or_b32 s38, s22, 11
	s_ashr_i32 s39, s38, 31
	s_lshl_b64 s[38:39], s[38:39], 9
	v_cvt_pk_bf16_f32 v2, v40, v44
	global_store_dword v[0:1], v2, off offset:-1536
	v_lshl_add_u64 v[0:1], v[20:21], 0, s[38:39]
	s_or_b32 s38, s22, 12
	s_ashr_i32 s39, s38, 31
	s_lshl_b64 s[38:39], s[38:39], 9
	v_cvt_pk_bf16_f32 v2, v45, v73
	global_store_dword v[0:1], v2, off offset:-1536
	v_lshl_add_u64 v[0:1], v[20:21], 0, s[38:39]
	s_or_b32 s38, s22, 13
	s_ashr_i32 s39, s38, 31
	s_lshl_b64 s[38:39], s[38:39], 9
	v_cvt_pk_bf16_f32 v2, v47, v75
	global_store_dword v[0:1], v2, off offset:-1536
	v_lshl_add_u64 v[0:1], v[20:21], 0, s[38:39]
	s_or_b32 s38, s22, 14
	s_ashr_i32 s39, s38, 31
	s_lshl_b64 s[38:39], s[38:39], 9
	v_cvt_pk_bf16_f32 v2, v46, v72
	global_store_dword v[0:1], v2, off offset:-1536
	v_lshl_add_u64 v[0:1], v[20:21], 0, s[38:39]
	s_or_b32 s38, s22, 15
	s_ashr_i32 s39, s38, 31
	v_cvt_pk_bf16_f32 v2, v77, v78
	s_lshl_b64 s[38:39], s[38:39], 9
	global_store_dword v[0:1], v2, off offset:-1536
	v_cvt_pk_bf16_f32 v2, v71, v74
	v_lshl_add_u64 v[0:1], v[20:21], 0, s[38:39]
	global_store_dword v[0:1], v2, off offset:-1536

; __device__ __forceinline__ float silu_f(float x) { return x * __builtin_amdgcn_rcpf(1.0f + __builtin_amdgcn_exp2f(-1.4426950408889634f * x)); }
; __device__ __forceinline__ float bflo(unsigned x) { return __uint_as_float(x << 16); }
; __device__ __forceinline__ float bfhi(unsigned x) { return __uint_as_float(x & 0xffff0000u); }
; __device__ __forceinline__ unsigned pk2(float lo, float hi) { return pg8::cvt_pk_bf16(lo, hi); }
; __device__ __forceinline__ float silu_f(float x) { return x * __builtin_amdgcn_rcpf(1.0f + __builtin_amdgcn_exp2f(-1.4426950408889634f * x)); }
; __device__ __forceinline__ void ph_conv(const bf16* XBC, const float* state_conv, const float* conv_w, const float* conv_b, bf16* XT, bf16* BN, bf16* CN, bf16* BT, int c_lo, int c_hi, int vcu, int G, int tid) {
;     ...
;         for (int t8 = 0; t8 < 2; ++t8) {
;             float y0[8], y1[8];
; #pragma unroll
;             for (int i = 0; i < 8; ++i) { const float x0 = bflo(raw[3 + t8 * 8 + i]), x1 = bfhi(raw[3 + t8 * 8 + i]);
;                 const float a0 = b0 + w0[0] * p0[0] + w0[1] * p0[1] + w0[2] * p0[2] + w0[3] * x0, a1 = b1 + w1[0] * p1[0] + w1[1] * p1[1] + w1[2] * p1[2] + w1[3] * x1;
;                 y0[i] = silu_f(a0); y1[i] = silu_f(a1); p0[0] = p0[1]; p0[1] = p0[2]; p0[2] = x0; p1[0] = p1[1]; p1[1] = p1[2]; p1[2] = x1; }
;             v4u t0, t1; t0.x = pk2(y0[0], y0[1]); t0.y = pk2(y0[2], y0[3]); t0.z = pk2(y0[4], y0[5]); t0.w = pk2(y0[6], y0[7]);
;             t1.x = pk2(y1[0], y1[1]); t1.y = pk2(y1[2], y1[3]); t1.z = pk2(y1[4], y1[5]); t1.w = pk2(y1[6], y1[7]);
;             const int tl = q * 16 + t8 * 8;
;             if (tid < 256) { const int h = ch >> 6, p = ch & 63; bf16* d = XT + ((size_t)(ci * 8 + h) * 64 + p) * 64 + tl; *(v4u*)d = t0; *(v4u*)(d + 64) = t1; }
.LBB0_837:
	v_lshlrev_b32_e32 v82, 16, v4
	v_fma_f32 v0, v14, v0, v18
	v_mov_b32_e32 v83, v5
	v_fma_f32 v0, v15, v1, v0
	v_and_b32_e32 v84, 0xffff0000, v4
	v_fma_f32 v0, v11, v83, v0
	v_fma_f32 v0, v10, v82, v0
	v_mov_b32_e32 v85, v3
	v_fma_f32 v2, v38, v6, v19
	v_fma_f32 v2, v39, v7, v2
	v_lshl_add_u32 v40, s21, 1, v52
	v_fma_f32 v2, v35, v85, v2
	v_fma_f32 v6, v34, v84, v2
	v_mul_f32_e32 v2, 0xbfb8aa3b, v0
	v_exp_f32_e32 v2, v2
	v_mul_f32_e32 v4, 0xbfb8aa3b, v6
	v_exp_f32_e32 v4, v4
	v_ashrrev_i32_e32 v41, 31, v40
	v_add_f32_e32 v2, 1.0, v2
	v_rcp_f32_e32 v49, v2
	v_add_f32_e32 v2, 1.0, v4
	v_rcp_f32_e32 v51, v2
	v_mov_b32_e32 v2, v7
	v_fma_f32 v4, v14, v1, v18
	v_fma_f32 v81, v15, v5, v4
	v_lshlrev_b32_e32 v5, 16, v48
	v_mul_f32_e32 v51, v6, v51
	v_mov_b32_e32 v7, v82
	v_mul_f32_e32 v50, v0, v49
	v_and_b32_e32 v1, 0xffff0000, v48
	v_and_b32_e32 v0, 0xffff0000, v43
	v_fma_f32 v2, v38, v2, v19
	v_lshlrev_b32_e32 v4, 16, v43
	v_fma_f32 v43, v11, v7, v81
	v_fma_f32 v86, v39, v3, v2
	v_fma_f32 v43, v10, v5, v43
	v_fma_f32 v3, v37, v83, v18
	v_mul_f32_e32 v48, 0xbfb8aa3b, v43
	v_fma_f32 v83, v36, v82, v3
	v_exp_f32_e32 v81, v48
	v_fma_f32 v49, v11, v5, v83
	v_fma_f32 v48, v10, v4, v49
	v_mul_f32_e32 v49, 0xbfb8aa3b, v48
	v_exp_f32_e32 v49, v49
	v_fma_f32 v3, v33, v85, v19
	v_fma_f32 v83, v32, v84, v3
	v_add_f32_e32 v2, 1.0, v81
	v_rcp_f32_e32 v81, v2
	v_add_f32_e32 v2, 1.0, v49
	v_rcp_f32_e32 v49, v2
	v_mul_f32_e32 v82, v43, v81
	v_fma_f32 v7, v37, v7, v18
	v_fma_f32 v85, v36, v5, v7
	v_mov_b32_e32 v6, v1
	v_mov_b32_e32 v7, v84
	v_mul_f32_e32 v81, v48, v49
	v_pk_mul_f32 v[48:49], v[34:35], v[6:7]
	v_add_f32_e32 v43, v49, v86
	v_add_f32_e32 v43, v48, v43
	v_mul_f32_e32 v48, 0xbfb8aa3b, v43
	v_exp_f32_e32 v84, v48
	v_fma_f32 v7, v33, v7, v19
	v_fma_f32 v49, v35, v1, v83
	v_fma_f32 v83, v34, v0, v49
	v_mul_f32_e32 v48, 0xbfb8aa3b, v83
	v_exp_f32_e32 v86, v48
	v_fma_f32 v89, v32, v6, v7
	v_add_f32_e32 v84, 1.0, v84
	v_add_f32_e32 v86, 1.0, v86
	v_fma_f32 v7, v33, v1, v19
	v_rcp_f32_e32 v84, v84
	v_rcp_f32_e32 v87, v86
	v_fma_f32 v49, v37, v5, v18
	v_fma_f32 v90, v32, v0, v7
	v_lshlrev_b32_e32 v7, 16, v42
	v_fma_f32 v88, v36, v4, v49
	v_mul_f32_e32 v86, v43, v84
	v_fma_f32 v6, v12, v4, v85
	v_mul_f32_e32 v84, v83, v87
	v_fma_f32 v83, v13, v7, v6
	v_mul_f32_e32 v6, 0xbfb8aa3b, v83
	v_exp_f32_e32 v48, v6
	v_lshlrev_b32_e32 v6, 16, v47
	v_and_b32_e32 v2, 0xffff0000, v47
	v_pk_mov_b32 v[4:5], v[6:7], v[4:5] op_sel:[1,0]
	v_add_f32_e32 v47, 1.0, v48
	v_fma_f32 v49, v11, v7, v88
	v_fma_f32 v48, v10, v6, v49
	v_mul_f32_e32 v49, 0xbfb8aa3b, v48
	v_and_b32_e32 v43, 0xffff0000, v45
	v_lshlrev_b32_e32 v45, 16, v45
	v_exp_f32_e32 v49, v49
	v_fma_f32 v5, v37, v5, v18
	v_fma_f32 v85, v36, v4, v5
	v_add_f32_e32 v49, 1.0, v49
	v_fma_f32 v4, v12, v6, v85
	v_fma_f32 v4, v13, v45, v4
	v_mul_f32_e32 v5, 0xbfb8aa3b, v4
	v_rcp_f32_e32 v49, v49
	v_exp_f32_e32 v5, v5
	v_and_b32_e32 v3, 0xffff0000, v42
	v_rcp_f32_e32 v47, v47
	v_mul_f32_e32 v85, v48, v49
	v_add_f32_e32 v5, 1.0, v5
	v_rcp_f32_e32 v5, v5
	v_fma_f32 v48, v30, v0, v89
	v_fma_f32 v88, v31, v3, v48
	v_mul_f32_e32 v48, 0xbfb8aa3b, v88
	v_exp_f32_e32 v89, v48
	v_mul_f32_e32 v87, v83, v47
	v_mul_f32_e32 v83, v4, v5
	v_pk_mov_b32 v[0:1], v[2:3], v[0:1] op_sel:[1,0]
	v_and_b32_e32 v42, 0xffff0000, v44
	v_lshlrev_b32_e32 v44, 16, v44
	v_fma_f32 v5, v37, v7, v18
	v_fma_f32 v47, v36, v6, v5
	v_fma_f32 v1, v33, v1, v19
	v_fma_f32 v5, v11, v45, v47
	v_add_f32_e32 v47, 1.0, v89
	v_fma_f32 v89, v32, v0, v1
	v_fma_f32 v0, v30, v2, v89
	v_fma_f32 v49, v35, v3, v90
	v_fma_f32 v90, v31, v43, v0
	v_mul_f32_e32 v0, 0xbfb8aa3b, v90
	v_exp_f32_e32 v0, v0
	v_rcp_f32_e32 v47, v47
	v_fma_f32 v4, v10, v44, v5
	v_fma_f32 v48, v34, v2, v49
	v_add_f32_e32 v0, 1.0, v0
	v_rcp_f32_e32 v5, v0
	v_mul_f32_e32 v49, 0xbfb8aa3b, v48
	v_fma_f32 v1, v33, v3, v19
	v_mul_f32_e32 v92, v88, v47
	v_fma_f32 v47, v32, v2, v1
	v_exp_f32_e32 v49, v49
	v_fma_f32 v1, v35, v43, v47
	v_fma_f32 v91, v34, v42, v1
	v_mul_f32_e32 v0, 0xbfb8aa3b, v4
	v_exp_f32_e32 v0, v0
	v_mul_f32_e32 v1, 0xbfb8aa3b, v91
	v_exp_f32_e32 v1, v1
	v_add_f32_e32 v49, 1.0, v49
	v_rcp_f32_e32 v49, v49
	v_add_f32_e32 v0, 1.0, v0
	v_mul_f32_e32 v88, v90, v5
	v_rcp_f32_e32 v5, v0
	v_add_f32_e32 v90, 1.0, v1
	v_pk_mov_b32 v[0:1], v[44:45], v[6:7] op_sel:[1,0]
	v_mul_f32_e32 v89, v48, v49
	v_lshlrev_b32_e32 v49, 16, v46
	v_fma_f32 v1, v37, v1, v18
	v_fma_f32 v6, v36, v0, v1
	v_and_b32_e32 v47, 0xffff0000, v46
	v_fma_f32 v0, v12, v44, v6
	v_fma_f32 v6, v13, v49, v0
	v_pk_mov_b32 v[0:1], v[42:43], v[2:3] op_sel:[1,0]
	v_rcp_f32_e32 v3, v90
	v_fma_f32 v1, v33, v1, v19
	v_fma_f32 v2, v32, v0, v1
	s_lshl_b32 s4, s21, 6
	v_fma_f32 v0, v30, v42, v2
	v_fma_f32 v0, v31, v47, v0
	v_mul_f32_e32 v1, 0xbfb8aa3b, v6
	v_mul_f32_e32 v2, 0xbfb8aa3b, v0
	v_exp_f32_e32 v1, v1
	v_exp_f32_e32 v2, v2
	s_lshl_b32 s20, s12, 4
	v_lshlrev_b64 v[40:41], 14, v[40:41]
	v_add_f32_e32 v1, 1.0, v1
	v_add_f32_e32 v2, 1.0, v2
	v_rcp_f32_e32 v1, v1
	v_rcp_f32_e32 v2, v2
	s_or_b32 s10, s4, s20
	v_lshl_add_u64 v[40:41], v[26:27], 0, v[40:41]
	v_mul_f32_e32 v90, v4, v5
	v_mul_f32_e32 v91, v91, v3
	v_mul_f32_e32 v46, v6, v1
	v_mul_f32_e32 v48, v0, v2
	v_cvt_pk_bf16_f32 v0, v50, v82
	v_cvt_pk_bf16_f32 v1, v81, v87
	v_cvt_pk_bf16_f32 v2, v85, v83
	v_cvt_pk_bf16_f32 v3, v90, v46
	v_cvt_pk_bf16_f32 v4, v51, v86
	v_cvt_pk_bf16_f32 v5, v84, v92
	v_cvt_pk_bf16_f32 v6, v89, v88
	v_cvt_pk_bf16_f32 v7, v91, v48
	s_and_saveexec_b64 s[12:13], s[0:1]
	s_xor_b64 s[12:13], exec, s[12:13]
	s_cbranch_execz .LBB0_843
; __device__ __forceinline__ unsigned pk2(float lo, float hi) { return pg8::cvt_pk_bf16(lo, hi); }
; __device__ __forceinline__ void ph_conv(const bf16* XBC, const float* state_conv, const float* conv_w, const float* conv_b, bf16* XT, bf16* BN, bf16* CN, bf16* BT, int c_lo, int c_hi, int vcu, int G, int tid) {
;     ...
;             else if (tid < 384) { const int cb = ch - 512, g = cb >> 7, n = cb & 127;
; #pragma unroll
;                 for (int i = 0; i < 8; ++i) *(unsigned*)(BN + (size_t)(row0 + t8 * 8 + i) * 256 + cb) = pk2(y0[i], y1[i]);
;                 bf16* d = BT + ((size_t)(ci * 2 + g) * 128 + n) * 64 + tl; *(v4u*)d = t0; *(v4u*)(d + 64) = t1; }
;             else { const int cc = ch - 768;
; #pragma unroll
;                 for (int i = 0; i < 8; ++i) *(unsigned*)(CN + (size_t)(row0 + t8 * 8 + i) * 256 + cc) = pk2(y0[i], y1[i]); }
	s_ashr_i32 s11, s10, 31
	s_lshl_b64 s[14:15], s[10:11], 9
	s_and_saveexec_b64 s[16:17], s[2:3]
	s_xor_b64 s[16:17], exec, s[16:17]
	s_cbranch_execz .LBB0_840
	s_or_b32 s24, s10, 1
	s_ashr_i32 s25, s24, 31
	v_lshl_add_u64 v[0:1], v[22:23], 0, s[14:15]
	s_lshl_b64 s[24:25], s[24:25], 9
	v_cvt_pk_bf16_f32 v2, v50, v51
	global_store_dword v[0:1], v2, off offset:-1536
	v_lshl_add_u64 v[0:1], v[22:23], 0, s[24:25]
	s_or_b32 s24, s10, 2
	s_ashr_i32 s25, s24, 31
	s_lshl_b64 s[24:25], s[24:25], 9
	v_cvt_pk_bf16_f32 v2, v82, v86
	global_store_dword v[0:1], v2, off offset:-1536
	v_lshl_add_u64 v[0:1], v[22:23], 0, s[24:25]
	s_or_b32 s24, s10, 3
	s_ashr_i32 s25, s24, 31
	s_lshl_b64 s[24:25], s[24:25], 9
	v_cvt_pk_bf16_f32 v2, v81, v84
	global_store_dword v[0:1], v2, off offset:-1536
	v_lshl_add_u64 v[0:1], v[22:23], 0, s[24:25]
	s_or_b32 s24, s10, 4
	s_ashr_i32 s25, s24, 31
	s_lshl_b64 s[24:25], s[24:25], 9
	v_cvt_pk_bf16_f32 v2, v87, v92
	global_store_dword v[0:1], v2, off offset:-1536
	v_lshl_add_u64 v[0:1], v[22:23], 0, s[24:25]
	s_or_b32 s24, s10, 5
	s_ashr_i32 s25, s24, 31
	s_lshl_b64 s[24:25], s[24:25], 9
	v_cvt_pk_bf16_f32 v2, v85, v89
	global_store_dword v[0:1], v2, off offset:-1536
	v_lshl_add_u64 v[0:1], v[22:23], 0, s[24:25]
	s_or_b32 s24, s10, 6
	s_ashr_i32 s25, s24, 31
	s_lshl_b64 s[24:25], s[24:25], 9
	v_cvt_pk_bf16_f32 v2, v83, v88
	global_store_dword v[0:1], v2, off offset:-1536
	v_lshl_add_u64 v[0:1], v[22:23], 0, s[24:25]
	s_or_b32 s24, s10, 7
	s_ashr_i32 s25, s24, 31
	v_cvt_pk_bf16_f32 v2, v90, v91
	s_lshl_b64 s[24:25], s[24:25], 9
	global_store_dword v[0:1], v2, off offset:-1536
	v_cvt_pk_bf16_f32 v2, v46, v48
	v_lshl_add_u64 v[0:1], v[22:23], 0, s[24:25]
	global_store_dword v[0:1], v2, off offset:-1536

; __device__ __forceinline__ float silu_f(float x) { return x * __builtin_amdgcn_rcpf(1.0f + __builtin_amdgcn_exp2f(-1.4426950408889634f * x)); }
; __device__ __forceinline__ float bflo(unsigned x) { return __uint_as_float(x << 16); }
; __device__ __forceinline__ float bfhi(unsigned x) { return __uint_as_float(x & 0xffff0000u); }
; __device__ __forceinline__ unsigned pk2(float lo, float hi) { return pg8::cvt_pk_bf16(lo, hi); }
; __device__ __forceinline__ float silu_f(float x) { return x * __builtin_amdgcn_rcpf(1.0f + __builtin_amdgcn_exp2f(-1.4426950408889634f * x)); }
; __device__ __forceinline__ void ph_conv(const bf16* XBC, const float* state_conv, const float* conv_w, const float* conv_b, bf16* XT, bf16* BN, bf16* CN, bf16* BT, int c_lo, int c_hi, int vcu, int G, int tid) {
;     ...
;         for (int t8 = 0; t8 < 2; ++t8) {
;             float y0[8], y1[8];
; #pragma unroll
;             for (int i = 0; i < 8; ++i) { const float x0 = bflo(raw[3 + t8 * 8 + i]), x1 = bfhi(raw[3 + t8 * 8 + i]);
;                 const float a0 = b0 + w0[0] * p0[0] + w0[1] * p0[1] + w0[2] * p0[2] + w0[3] * x0, a1 = b1 + w1[0] * p1[0] + w1[1] * p1[1] + w1[2] * p1[2] + w1[3] * x1;
;                 y0[i] = silu_f(a0); y1[i] = silu_f(a1); p0[0] = p0[1]; p0[1] = p0[2]; p0[2] = x0; p1[0] = p1[1]; p1[1] = p1[2]; p1[2] = x1; }
;             v4u t0, t1; t0.x = pk2(y0[0], y0[1]); t0.y = pk2(y0[2], y0[3]); t0.z = pk2(y0[4], y0[5]); t0.w = pk2(y0[6], y0[7]);
;             t1.x = pk2(y1[0], y1[1]); t1.y = pk2(y1[2], y1[3]); t1.z = pk2(y1[4], y1[5]); t1.w = pk2(y1[6], y1[7]);
.LBB0_845:
	s_or_b64 exec, exec, s[12:13]
	s_nop 0
	v_lshlrev_b32_e32 v1, 16, v80
	v_fma_f32 v0, v37, v45, v18
	v_fma_f32 v2, v36, v44, v0
	v_and_b32_e32 v3, 0xffff0000, v80
	v_fma_f32 v0, v12, v49, v2
	v_fma_f32 v0, v13, v1, v0
	v_fma_f32 v2, v33, v43, v19
	v_fma_f32 v6, v32, v42, v2
	v_fma_f32 v2, v30, v47, v6
	v_mul_f32_e32 v4, 0xbfb8aa3b, v0
	v_exp_f32_e32 v4, v4
	v_fma_f32 v2, v31, v3, v2
	v_mul_f32_e32 v5, 0xbfb8aa3b, v2
	v_exp_f32_e32 v5, v5
	v_add_f32_e32 v4, 1.0, v4
	v_rcp_f32_e32 v4, v4
	v_add_f32_e32 v5, 1.0, v5
	v_rcp_f32_e32 v5, v5
	v_mul_f32_e32 v43, v0, v4
	v_fma_f32 v0, v37, v44, v18
	v_fma_f32 v0, v36, v49, v0
	v_mul_f32_e32 v45, v2, v5
	v_fma_f32 v2, v33, v42, v19
	v_fma_f32 v2, v32, v47, v2
	v_mov_b32_e32 v46, v3
	v_fma_f32 v7, v37, v49, v18
	v_lshlrev_b32_e32 v49, 16, v79
	v_fma_f32 v42, v36, v1, v7
	v_pk_mul_f32 v[6:7], v[32:33], v[46:47]
	v_lshlrev_b32_e32 v48, 16, v78
	v_fma_f32 v0, v12, v1, v0
	v_fma_f32 v0, v13, v49, v0
	v_mul_f32_e32 v44, 0xbfb8aa3b, v0
	v_exp_f32_e32 v44, v44
	v_add_f32_e32 v7, v19, v7
	v_and_b32_e32 v5, 0xffff0000, v79
	v_fma_f32 v42, v11, v49, v42
	v_add_f32_e32 v47, v6, v7
	v_add_f32_e32 v6, 1.0, v44
	v_rcp_f32_e32 v44, v6
	v_fma_f32 v42, v10, v48, v42
	v_mul_f32_e32 v46, 0xbfb8aa3b, v42
	v_exp_f32_e32 v46, v46
	v_mul_f32_e32 v44, v0, v44
	v_add_f32_e32 v6, 1.0, v46
	v_fma_f32 v1, v37, v1, v18
	v_fma_f32 v79, v36, v49, v1
	v_rcp_f32_e32 v46, v6
	v_and_b32_e32 v4, 0xffff0000, v78
	v_fma_f32 v0, v30, v3, v2
	v_fma_f32 v2, v31, v5, v0
	v_mul_f32_e32 v0, 0xbfb8aa3b, v2
	v_mul_f32_e32 v42, v42, v46
	v_exp_f32_e32 v46, v0
	v_and_b32_e32 v7, 0xffff0000, v77
	v_fma_f32 v1, v35, v5, v47
	v_fma_f32 v47, v34, v4, v1
	v_mul_f32_e32 v0, 0xbfb8aa3b, v47
	v_exp_f32_e32 v78, v0
	v_add_f32_e32 v46, 1.0, v46
	v_rcp_f32_e32 v46, v46
	v_add_f32_e32 v78, 1.0, v78
	v_rcp_f32_e32 v80, v78
	v_fma_f32 v1, v37, v49, v18
	v_mul_f32_e32 v78, v2, v46
	v_mov_b32_e32 v2, v5
	v_fma_f32 v82, v36, v48, v1
	v_pk_mul_f32 v[0:1], v[32:33], v[2:3]
	v_lshlrev_b32_e32 v3, 16, v77
	v_mul_f32_e32 v46, v47, v80
	v_add_f32_e32 v1, v19, v1
	v_fma_f32 v2, v12, v48, v79
	v_fma_f32 v47, v13, v3, v2
	v_mul_f32_e32 v2, 0xbfb8aa3b, v47
	v_exp_f32_e32 v77, v2
	v_add_f32_e32 v83, v0, v1
	v_lshlrev_b32_e32 v2, 16, v76
	v_fma_f32 v1, v33, v5, v19
	v_fma_f32 v79, v32, v4, v1
	v_add_f32_e32 v0, 1.0, v77
	v_and_b32_e32 v6, 0xffff0000, v76
	v_rcp_f32_e32 v76, v0
	v_pk_mov_b32 v[48:49], v[2:3], v[48:49] op_sel:[1,0]
	v_fma_f32 v1, v11, v3, v82
	v_fma_f32 v81, v10, v2, v1
	v_mul_f32_e32 v0, 0xbfb8aa3b, v81
	v_exp_f32_e32 v77, v0
	v_mul_f32_e32 v47, v47, v76
	v_lshlrev_b32_e32 v80, 16, v75
	v_add_f32_e32 v76, 1.0, v77
	v_rcp_f32_e32 v82, v76
	v_fma_f32 v49, v37, v49, v18
	v_pk_mul_f32 v[76:77], v[36:37], v[2:3]
	v_mov_b32_e32 v3, v80
	v_fma_f32 v84, v36, v48, v49
	v_pk_mul_f32 v[48:49], v[12:13], v[2:3]
	v_and_b32_e32 v0, 0xffff0000, v75
	v_add_f32_e32 v3, v48, v84
	v_add_f32_e32 v3, v3, v49
	v_mul_f32_e32 v48, 0xbfb8aa3b, v3
	v_add_f32_e32 v75, v18, v77
	v_exp_f32_e32 v48, v48
	v_mul_f32_e32 v49, v81, v82
	v_add_f32_e32 v82, v76, v75
	v_add_f32_e32 v48, 1.0, v48
	v_fma_f32 v75, v30, v4, v83
	v_fma_f32 v83, v31, v7, v75
	v_mul_f32_e32 v75, 0xbfb8aa3b, v83
	v_rcp_f32_e32 v48, v48
	v_exp_f32_e32 v76, v75
	v_lshlrev_b32_e32 v81, 16, v74
	v_pk_mov_b32 v[4:5], v[6:7], v[4:5] op_sel:[1,0]
	v_mul_f32_e32 v48, v3, v48
	v_add_f32_e32 v3, 1.0, v76
	v_rcp_f32_e32 v3, v3
	v_fma_f32 v77, v35, v7, v79
	v_fma_f32 v79, v34, v6, v77
	v_mul_f32_e32 v76, 0xbfb8aa3b, v79
	v_exp_f32_e32 v76, v76
	v_and_b32_e32 v1, 0xffff0000, v74
	v_fma_f32 v74, v12, v80, v82
	v_fma_f32 v5, v33, v5, v19
	v_fma_f32 v84, v13, v81, v74
	v_fma_f32 v74, v32, v4, v5
	v_pk_mul_f32 v[4:5], v[32:33], v[6:7]
	v_mov_b32_e32 v7, v0
	v_mul_f32_e32 v75, v83, v3
	v_add_f32_e32 v3, 1.0, v76
	v_pk_mul_f32 v[76:77], v[30:31], v[6:7]
	v_rcp_f32_e32 v3, v3
	v_add_f32_e32 v7, v76, v74
	v_add_f32_e32 v7, v7, v77
	v_mul_f32_e32 v74, 0xbfb8aa3b, v7
	v_exp_f32_e32 v74, v74
	v_mul_f32_e32 v77, v79, v3
	v_add_f32_e32 v3, v19, v5
	v_add_f32_e32 v3, v4, v3
	v_add_f32_e32 v4, 1.0, v74
	v_rcp_f32_e32 v74, v4
	v_mov_b32_e32 v82, v80
	v_fma_f32 v3, v30, v0, v3
	v_fma_f32 v76, v31, v1, v3
	v_mul_f32_e32 v3, 0xbfb8aa3b, v84
	v_exp_f32_e32 v3, v3
	v_mul_f32_e32 v4, 0xbfb8aa3b, v76
	v_exp_f32_e32 v4, v4
	v_mov_b32_e32 v83, v2
	v_pk_mul_f32 v[82:83], v[36:37], v[82:83]
	v_add_f32_e32 v3, 1.0, v3
	v_add_f32_e32 v2, v18, v83
	v_mul_f32_e32 v74, v7, v74
	v_rcp_f32_e32 v7, v3
	v_add_f32_e32 v79, 1.0, v4
	v_lshlrev_b32_e32 v3, 16, v73
	v_add_f32_e32 v4, v82, v2
	v_and_b32_e32 v5, 0xffff0000, v73
	v_fma_f32 v2, v12, v81, v4
	v_fma_f32 v73, v13, v3, v2
	v_mov_b32_e32 v2, v0
	v_fma_f32 v0, v33, v6, v19
	v_fma_f32 v2, v32, v2, v0
	v_rcp_f32_e32 v3, v79
	v_fma_f32 v0, v30, v1, v2
	v_fma_f32 v0, v31, v5, v0
	v_mul_f32_e32 v1, 0xbfb8aa3b, v73
	v_mul_f32_e32 v2, 0xbfb8aa3b, v0
	v_exp_f32_e32 v1, v1
	v_exp_f32_e32 v2, v2
	v_mul_f32_e32 v79, v84, v7
	v_mul_f32_e32 v80, v76, v3
	v_add_f32_e32 v1, 1.0, v1
	v_add_f32_e32 v2, 1.0, v2
	v_rcp_f32_e32 v1, v1
	v_rcp_f32_e32 v2, v2
	v_mul_f32_e32 v73, v73, v1
	v_mul_f32_e32 v76, v0, v2
	v_cvt_pk_bf16_f32 v0, v43, v44
	v_cvt_pk_bf16_f32 v1, v42, v47
	v_cvt_pk_bf16_f32 v2, v49, v48
	v_cvt_pk_bf16_f32 v3, v79, v73
	v_cvt_pk_bf16_f32 v4, v45, v78
	v_cvt_pk_bf16_f32 v5, v46, v75
	v_cvt_pk_bf16_f32 v6, v77, v74
	v_cvt_pk_bf16_f32 v7, v80, v76
	s_and_saveexec_b64 s[12:13], s[0:1]
	s_xor_b64 s[12:13], exec, s[12:13]
	s_cbranch_execz .LBB0_851
; __device__ __forceinline__ unsigned pk2(float lo, float hi) { return pg8::cvt_pk_bf16(lo, hi); }
; __device__ __forceinline__ void ph_conv(const bf16* XBC, const float* state_conv, const float* conv_w, const float* conv_b, bf16* XT, bf16* BN, bf16* CN, bf16* BT, int c_lo, int c_hi, int vcu, int G, int tid) {
;     ...
;             else if (tid < 384) { const int cb = ch - 512, g = cb >> 7, n = cb & 127;
; #pragma unroll
;                 for (int i = 0; i < 8; ++i) *(unsigned*)(BN + (size_t)(row0 + t8 * 8 + i) * 256 + cb) = pk2(y0[i], y1[i]);
;                 bf16* d = BT + ((size_t)(ci * 2 + g) * 128 + n) * 64 + tl; *(v4u*)d = t0; *(v4u*)(d + 64) = t1; }
;             else { const int cc = ch - 768;
; #pragma unroll
;                 for (int i = 0; i < 8; ++i) *(unsigned*)(CN + (size_t)(row0 + t8 * 8 + i) * 256 + cc) = pk2(y0[i], y1[i]); }
	s_or_b32 s14, s10, 8
	s_ashr_i32 s15, s14, 31
	s_lshl_b64 s[14:15], s[14:15], 9
	s_and_saveexec_b64 s[16:17], s[2:3]
	s_xor_b64 s[16:17], exec, s[16:17]
	s_cbranch_execz .LBB0_848
	s_or_b32 s24, s10, 9
	s_ashr_i32 s25, s24, 31
	v_lshl_add_u64 v[0:1], v[22:23], 0, s[14:15]
	s_lshl_b64 s[24:25], s[24:25], 9
	v_cvt_pk_bf16_f32 v2, v43, v45
	global_store_dword v[0:1], v2, off offset:-1536
	v_lshl_add_u64 v[0:1], v[22:23], 0, s[24:25]
	s_or_b32 s24, s10, 10
	s_ashr_i32 s25, s24, 31
	s_lshl_b64 s[24:25], s[24:25], 9
	v_cvt_pk_bf16_f32 v2, v44, v78
	global_store_dword v[0:1], v2, off offset:-1536
	v_lshl_add_u64 v[0:1], v[22:23], 0, s[24:25]
	s_or_b32 s24, s10, 11
	s_ashr_i32 s25, s24, 31
	s_lshl_b64 s[24:25], s[24:25], 9
	v_cvt_pk_bf16_f32 v2, v42, v46
	global_store_dword v[0:1], v2, off offset:-1536
	v_lshl_add_u64 v[0:1], v[22:23], 0, s[24:25]
	s_or_b32 s24, s10, 12
	s_ashr_i32 s25, s24, 31
	s_lshl_b64 s[24:25], s[24:25], 9
	v_cvt_pk_bf16_f32 v2, v47, v75
	global_store_dword v[0:1], v2, off offset:-1536
	v_lshl_add_u64 v[0:1], v[22:23], 0, s[24:25]
	s_or_b32 s24, s10, 13
	s_ashr_i32 s25, s24, 31
	s_lshl_b64 s[24:25], s[24:25], 9
	v_cvt_pk_bf16_f32 v2, v49, v77
	global_store_dword v[0:1], v2, off offset:-1536
	v_lshl_add_u64 v[0:1], v[22:23], 0, s[24:25]
	s_or_b32 s24, s10, 14
	s_ashr_i32 s25, s24, 31
	s_lshl_b64 s[24:25], s[24:25], 9
	v_cvt_pk_bf16_f32 v2, v48, v74
	global_store_dword v[0:1], v2, off offset:-1536
	v_lshl_add_u64 v[0:1], v[22:23], 0, s[24:25]
	s_or_b32 s24, s10, 15
	s_ashr_i32 s25, s24, 31
	v_cvt_pk_bf16_f32 v2, v79, v80
	s_lshl_b64 s[24:25], s[24:25], 9
	global_store_dword v[0:1], v2, off offset:-1536
	v_cvt_pk_bf16_f32 v2, v73, v76
	v_lshl_add_u64 v[0:1], v[22:23], 0, s[24:25]
	global_store_dword v[0:1], v2, off offset:-1536

; #define LAS __attribute__((address_space(3)))
; template <int NMT> __device__ __forceinline__ void ssd_out_item(const int ci, const int mt0, const float* DT, const bf16* XT, const bf16* BN, const bf16* CN, const bf16* HST, const bf16* Z, const float* ssd_norm, ...
;     ...
;         const int row0 = ci * 64;
;         { const float dtv = DT[(size_t)(row0 + lane) * 8 + h]; const float a = wave_incl_scan(dtv * A, lane); sAcs[h * 64 + lane] = a; sDt[h * 64 + lane] = dtv; }
;         if (NMT == 4 || (wave & 3) == 0) { const int mt = 0, mt0c = (NMT == 4) ? (wave & 3) : mt0; bf16x8 cf[4];
; #pragma unroll
;           for (int ks = 0; ks < 4; ++ks) cf[ks] = *(const bf16x8*)(CN + (size_t)(row0 + 16 * mt0c + fr) * 256 + g * 128 + 32 * ks + 8 * fq);
; #pragma unroll
;           for (int st = 0; st < 4; ++st) { f32x4 acc = (f32x4){0.f, 0.f, 0.f, 0.f};
; #pragma unroll
;               for (int ks = 0; ks < 4; ++ks) { const bf16x8 bfv = *(const bf16x8*)(BN + (size_t)(row0 + 16 * st + fr) * 256 + g * 128 + 32 * ks + 8 * fq); acc = __builtin_amdgcn_mfma_f32_16x16x32_bf16(bfv, cf[ks], acc, 0, 0, 0); }
;               *(LAS f32x4*)(sCB + (g * 64 + 16 * mt0c + fr) * 68 + 16 * st + 4 * fq) = acc; } }
;         __syncthreads();
.LBB0_1159:
	v_add_u32_e32 v104, s33, v139
	v_add_u32_e32 v0, s33, v133
	v_add_u32_e32 v102, 16, v104
	v_add_u32_e32 v100, 32, v104
	v_add_u32_e32 v108, 48, v104
	v_ashrrev_i32_e32 v1, 31, v0
	v_ashrrev_i32_e32 v105, 31, v104
	v_ashrrev_i32_e32 v103, 31, v102
	v_ashrrev_i32_e32 v101, 31, v100
	v_ashrrev_i32_e32 v109, 31, v108
	v_lshlrev_b64 v[0:1], 9, v[0:1]
	v_lshlrev_b64 v[70:71], 9, v[104:105]
	v_lshlrev_b64 v[66:67], 9, v[102:103]
	v_lshlrev_b64 v[64:65], 9, v[100:101]
	v_lshlrev_b64 v[16:17], 9, v[108:109]
	v_lshl_add_u64 v[56:57], v[86:87], 0, v[0:1]
	v_lshl_add_u64 v[58:59], v[88:89], 0, v[70:71]
	v_lshl_add_u64 v[60:61], v[88:89], 0, v[66:67]
	v_lshl_add_u64 v[62:63], v[88:89], 0, v[64:65]
	v_lshl_add_u64 v[72:73], v[88:89], 0, v[16:17]
	global_load_dwordx4 v[0:3], v[56:57], off
	global_load_dwordx4 v[4:7], v[58:59], off
	global_load_dwordx4 v[8:11], v[60:61], off
	global_load_dwordx4 v[12:15], v[62:63], off
	global_load_dwordx4 v[16:19], v[72:73], off
	v_add_u32_e32 v20, s33, v138
	v_ashrrev_i32_e32 v21, 31, v20
	v_lshlrev_b64 v[20:21], 5, v[20:21]
	v_lshl_add_u64 v[28:29], s[64:65], 0, v[20:21]
	global_load_dwordx4 v[20:23], v[58:59], off offset:64
	global_load_dwordx4 v[24:27], v[56:57], off offset:64
	global_load_dword v78, v[28:29], off
	s_nop 0
	global_load_dwordx4 v[28:31], v[56:57], off offset:192
	global_load_dwordx4 v[32:35], v[60:61], off offset:64
	global_load_dwordx4 v[36:39], v[58:59], off offset:192
	global_load_dwordx4 v[40:43], v[62:63], off offset:64
	global_load_dwordx4 v[44:47], v[60:61], off offset:192
	global_load_dwordx4 v[48:51], v[72:73], off offset:64
	global_load_dwordx4 v[52:55], v[62:63], off offset:192
	s_ashr_i32 s67, s66, 31
	s_lshl_b64 s[60:61], s[66:67], 6
	v_mov_b32_e32 v69, s61
	v_or_b32_e32 v68, s60, v80
	v_or_b32_e32 v74, 32, v68
	v_mov_b32_e32 v75, s61
	v_or_b32_e32 v76, 48, v68
	v_mov_b32_e32 v77, s61
	s_waitcnt vmcnt(13)
	v_mfma_f32_16x16x32_bf16 v[4:7], v[4:7], v[0:3], 0
	s_waitcnt vmcnt(12)
	v_mfma_f32_16x16x32_bf16 v[8:11], v[8:11], v[0:3], 0
	s_waitcnt vmcnt(11)
	v_mfma_f32_16x16x32_bf16 v[12:15], v[12:15], v[0:3], 0
	s_waitcnt vmcnt(10)
	v_mfma_f32_16x16x32_bf16 v[0:3], v[16:19], v[0:3], 0
	global_load_dwordx4 v[16:19], v[58:59], off offset:128
	s_nop 0
	global_load_dwordx4 v[56:59], v[56:57], off offset:128
	s_waitcnt vmcnt(10)
	v_mfma_f32_16x16x32_bf16 v[4:7], v[20:23], v[24:27], v[4:7]
	global_load_dwordx4 v[20:23], v[60:61], off offset:128
	s_waitcnt vmcnt(8)
	v_mfma_f32_16x16x32_bf16 v[8:11], v[32:35], v[24:27], v[8:11]
	global_load_dwordx4 v[32:35], v[62:63], off offset:128
	s_waitcnt vmcnt(7)
	v_mfma_f32_16x16x32_bf16 v[12:15], v[40:43], v[24:27], v[12:15]
	global_load_dwordx4 v[40:43], v[72:73], off offset:128
	s_waitcnt vmcnt(6)
	v_mfma_f32_16x16x32_bf16 v[0:3], v[48:51], v[24:27], v[0:3]
	global_load_dwordx4 v[24:27], v[72:73], off offset:192
	v_mul_f32_e64 v48, v78, -v111
	v_or_b32_e32 v72, 16, v68
	v_mov_b32_e32 v73, s61
	v_readlane_b32 s60, v253, 29
	v_readlane_b32 s61, v253, 30
	s_waitcnt vmcnt(4)
	v_mfma_f32_16x16x32_bf16 v[4:7], v[16:19], v[56:59], v[4:7]
	ds_bpermute_b32 v16, v114, v48
	s_waitcnt lgkmcnt(0)
	v_fma_f32 v16, v78, -v111, v16
	v_cndmask_b32_e64 v18, v16, v48, s[14:15]
	ds_bpermute_b32 v19, v115, v18
	v_lshlrev_b64 v[16:17], 7, v[68:69]
	v_lshl_add_u64 v[48:49], v[90:91], 0, v[16:17]
	s_waitcnt vmcnt(3)
	v_mfma_f32_16x16x32_bf16 v[8:11], v[20:23], v[56:59], v[8:11]
	v_lshlrev_b64 v[20:21], 7, v[76:77]
	s_waitcnt lgkmcnt(0)
	v_add_f32_e32 v19, v18, v19
	v_cndmask_b32_e64 v18, v19, v18, s[2:3]
	ds_bpermute_b32 v19, v116, v18
	s_waitcnt vmcnt(2)
	v_mfma_f32_16x16x32_bf16 v[12:15], v[32:35], v[56:59], v[12:15]
	v_lshl_add_u64 v[50:51], v[90:91], 0, v[20:21]
	s_waitcnt lgkmcnt(0)
	v_add_f32_e32 v19, v18, v19
	v_cndmask_b32_e64 v18, v19, v18, s[4:5]
	ds_bpermute_b32 v19, v117, v18
	s_waitcnt vmcnt(1)
	v_mfma_f32_16x16x32_bf16 v[0:3], v[40:43], v[56:59], v[0:3]
	s_waitcnt lgkmcnt(0)
	v_add_f32_e32 v16, v18, v19
	v_cndmask_b32_e64 v22, v16, v18, s[6:7]
	ds_bpermute_b32 v23, v118, v22
	v_mfma_f32_16x16x32_bf16 v[4:7], v[36:39], v[28:31], v[4:7]
	v_lshlrev_b64 v[16:17], 7, v[72:73]
	v_lshlrev_b64 v[18:19], 7, v[74:75]
	s_waitcnt lgkmcnt(0)
	v_add_f32_e32 v23, v22, v23
	v_cndmask_b32_e64 v22, v23, v22, s[8:9]
	ds_bpermute_b32 v23, v119, v22
	v_mfma_f32_16x16x32_bf16 v[8:11], v[44:47], v[28:31], v[8:11]
	v_mfma_f32_16x16x32_bf16 v[12:15], v[52:55], v[28:31], v[12:15]
	v_lshl_add_u64 v[54:55], v[90:91], 0, v[16:17]
	s_waitcnt lgkmcnt(0)
	v_add_f32_e32 v16, v22, v23
	v_cndmask_b32_e64 v16, v16, v22, s[10:11]
	s_waitcnt vmcnt(0)
	v_mfma_f32_16x16x32_bf16 v[0:3], v[24:27], v[28:31], v[0:3]
	v_lshl_add_u64 v[52:53], v[90:91], 0, v[18:19]
	ds_write2st64_b32 v120, v16, v78 offset0:136 offset1:144
	ds_write_b128 v134, v[4:7]
	ds_write_b128 v134, v[8:11] offset:64
	ds_write_b128 v134, v[12:15] offset:128
	s_nop 2
	ds_write_b128 v134, v[0:3] offset:192
	s_waitcnt lgkmcnt(0)
	s_barrier
; #define LAS __attribute__((address_space(3)))
; __device__ __forceinline__ unsigned pk2(float lo, float hi) { return pg8::cvt_pk_bf16(lo, hi); }
; template <int NMT> __device__ __forceinline__ void ssd_out_item(const int ci, const int mt0, const float* DT, const bf16* XT, const bf16* BN, const bf16* CN, const bf16* HST, const bf16* Z, const float* ssd_norm, ...
;     ...
;         for (int ks = 0; ks < 2; ++ks) {
;             bf16x8 xf[4];
; #pragma unroll
;             for (int nt = 0; nt < 4; ++nt) xf[nt] = *(const bf16x8*)(XT + ((size_t)(ci * 8 + h) * 64 + 16 * nt + fr) * 64 + 32 * ks + 8 * fq);
;             const int s0 = 32 * ks + 8 * fq;
;             const f32x4 as0 = *(const LAS f32x4*)(sAcs + h * 64 + s0), as1 = *(const LAS f32x4*)(sAcs + h * 64 + s0 + 4), d0 = *(const LAS f32x4*)(sDt + h * 64 + s0), d1 = *(const LAS f32x4*)(sDt + h * 64 + s0 + 4);
; #pragma unroll
;             for (int mt = 0; mt < NMT; ++mt) { const int l = 16 * (mt0 + mt) + fr; const float al = sAcs[h * 64 + l];
;                 const f32x4 c0 = *(const LAS f32x4*)(sCB + (g * 64 + l) * 68 + s0), c1 = *(const LAS f32x4*)(sCB + (g * 64 + l) * 68 + s0 + 4);
;                 float mv[8];
; #pragma unroll
;                 for (int j = 0; j < 4; ++j) { mv[j] = (s0 + j <= l) ? c0[j] * __expf(fminf(al - as0[j], 0.f)) * d0[j] : 0.f; mv[4 + j] = (s0 + 4 + j <= l) ? c1[j] * __expf(fminf(al - as1[j], 0.f)) * d1[j] : 0.f; }
; #pragma unroll
;                 for (int j = 0; j < 8; ++j) if (s0 + j == l) mv[j] += Dh;
;                 v4u mw; mw.x = pk2(mv[0], mv[1]); mw.y = pk2(mv[2], mv[3]); mw.z = pk2(mv[4], mv[5]); mw.w = pk2(mv[6], mv[7]);
;                 const bf16x8 mf = __builtin_bit_cast(bf16x8, mw);
; #pragma unroll
;                 for (int nt = 0; nt < 4; ++nt) acc[nt][mt] = __builtin_amdgcn_mfma_f32_16x16x32_bf16(xf[nt], mf, acc[nt][mt], 0, 0, 0); }
	global_load_dwordx4 v[12:15], v[48:49], off
	global_load_dwordx4 v[8:11], v[54:55], off
	global_load_dwordx4 v[4:7], v[52:53], off
	global_load_dwordx4 v[0:3], v[50:51], off
	ds_read_b128 v[28:31], v121 offset:34816
	ds_read_b128 v[24:27], v121 offset:34832
	ds_read_b32 v40, v123 offset:34816
	ds_read_b128 v[20:23], v121 offset:36864
	ds_read_b128 v[16:19], v121 offset:36880
	ds_read_b128 v[32:35], v135
	ds_read_b128 v[36:39], v135 offset:16
	s_waitcnt lgkmcnt(4)
	v_sub_f32_e32 v43, v40, v29
	v_sub_f32_e32 v41, v40, v28
	v_sub_f32_e32 v42, v40, v24
	v_sub_f32_e32 v44, v40, v25
	v_sub_f32_e32 v45, v40, v30
	v_sub_f32_e32 v46, v40, v26
	v_sub_f32_e32 v47, v40, v31
	v_sub_f32_e32 v40, v40, v27
	v_min_f32_e32 v43, 0, v43
	v_min_f32_e32 v41, 0, v41
	v_min_f32_e32 v42, 0, v42
	v_min_f32_e32 v44, 0, v44
	v_min_f32_e32 v45, 0, v45
	v_min_f32_e32 v46, 0, v46
	v_min_f32_e32 v40, 0, v40
	v_mul_f32_e32 v43, 0x3fb8aa3b, v43
	v_mul_f32_e32 v41, 0x3fb8aa3b, v41
	v_mul_f32_e32 v42, 0x3fb8aa3b, v42
	v_mul_f32_e32 v44, 0x3fb8aa3b, v44
	v_mul_f32_e32 v45, 0x3fb8aa3b, v45
	v_mul_f32_e32 v46, 0x3fb8aa3b, v46
	v_mul_f32_e32 v56, 0x3fb8aa3b, v40
	v_exp_f32_e32 v58, v43
	v_exp_f32_e32 v57, v41
	v_exp_f32_e32 v40, v42
	v_exp_f32_e32 v41, v44
	v_exp_f32_e32 v42, v45
	v_exp_f32_e32 v44, v46
	v_exp_f32_e32 v45, v56
	v_min_f32_e32 v47, 0, v47
	v_mul_f32_e32 v47, 0x3fb8aa3b, v47
	v_exp_f32_e32 v43, v47
	s_waitcnt lgkmcnt(1)
	v_mul_f32_e32 v47, v33, v58
	v_mul_f32_e32 v46, v32, v57
	s_waitcnt lgkmcnt(0)
	v_pk_mul_f32 v[32:33], v[36:37], v[40:41]
	v_pk_mul_f32 v[36:37], v[38:39], v[44:45]
	v_mul_f32_e32 v39, v21, v47
	v_cndmask_b32_e64 v39, 0, v39, s[60:61]
	v_readlane_b32 s60, v253, 27
	v_pk_mul_f32 v[32:33], v[16:17], v[32:33]
	v_readlane_b32 s61, v253, 28
	v_pk_mul_f32 v[34:35], v[34:35], v[42:43]
	v_pk_mul_f32 v[36:37], v[18:19], v[36:37]
	v_cndmask_b32_e64 v33, v33, 0, s[60:61]
	v_readlane_b32 s60, v253, 25
	v_readlane_b32 s61, v253, 26
	v_pk_mul_f32 v[34:35], v[22:23], v[34:35]
	v_add_f32_e32 v41, v81, v39
	v_cndmask_b32_e64 v32, v32, 0, s[60:61]
	v_readlane_b32 s60, v253, 23
	v_readlane_b32 s61, v253, 24
	v_add_f32_e32 v44, v81, v32
	v_add_f32_e32 v45, v81, v33
	v_cndmask_b32_e64 v35, v35, 0, s[60:61]
	v_readlane_b32 s60, v253, 21
	v_readlane_b32 s61, v253, 22
	v_add_f32_e32 v43, v81, v35
	v_mul_f32_e32 v38, v20, v46
	v_cndmask_b32_e64 v34, v34, 0, s[60:61]
	v_readlane_b32 s60, v253, 19
	v_readlane_b32 s61, v253, 20
	v_add_f32_e32 v42, v81, v34
	v_cndmask_b32_e64 v38, v38, 0, s[12:13]
	v_cndmask_b32_e64 v37, v37, 0, s[60:61]
	v_readlane_b32 s60, v253, 17
	v_readlane_b32 s61, v253, 18
	v_add_f32_e32 v40, v81, v38
	v_add_f32_e32 v47, v81, v37
	v_cndmask_b32_e64 v36, v36, 0, s[60:61]
	v_readlane_b32 s60, v253, 15
	v_readlane_b32 s61, v253, 16
	v_add_f32_e32 v46, v81, v36
	v_cndmask_b32_e64 v38, v38, v40, s[28:29]
	v_cndmask_b32_e64 v39, v39, v41, s[60:61]
	v_readlane_b32 s60, v253, 13
	v_readlane_b32 s61, v253, 14
	s_nop 1
	v_cndmask_b32_e64 v34, v34, v42, s[60:61]
	v_readlane_b32 s60, v253, 11
	v_readlane_b32 s61, v253, 12
	s_nop 1
	v_cndmask_b32_e64 v35, v35, v43, s[60:61]
	v_readlane_b32 s60, v253, 9
	v_readlane_b32 s61, v253, 10
	s_nop 1
	v_cndmask_b32_e64 v32, v32, v44, s[60:61]
	v_readlane_b32 s60, v253, 7
	v_readlane_b32 s61, v253, 8
	v_cvt_pk_bf16_f32 v44, v38, v39
	s_nop 1
	v_cndmask_b32_e64 v33, v33, v45, s[60:61]
	v_readlane_b32 s60, v253, 5
	v_readlane_b32 s61, v253, 6
	v_cvt_pk_bf16_f32 v45, v34, v35
	s_nop 1
	v_cndmask_b32_e64 v36, v36, v46, s[60:61]
	v_readlane_b32 s60, v253, 3
	v_readlane_b32 s61, v253, 4
	v_cvt_pk_bf16_f32 v46, v32, v33
	s_nop 1
	v_cndmask_b32_e64 v37, v37, v47, s[60:61]
	v_cvt_pk_bf16_f32 v47, v36, v37
	ds_read_b32 v106, v123 offset:34880
	ds_read_b128 v[56:59], v136
	ds_read_b128 v[60:63], v136 offset:16
	v_readlane_b32 s60, v253, 1
	v_readlane_b32 s61, v253, 2
	s_waitcnt lgkmcnt(2)
	v_sub_f32_e32 v32, v106, v28
	v_min_f32_e32 v32, 0, v32
	v_sub_f32_e32 v34, v106, v29
	v_mul_f32_e32 v40, 0x3fb8aa3b, v32
	v_min_f32_e32 v37, 0, v34
	v_exp_f32_e32 v107, v40
	v_sub_f32_e32 v33, v106, v24
	v_sub_f32_e32 v35, v106, v25
	v_mul_f32_e32 v42, 0x3fb8aa3b, v37
	v_min_f32_e32 v36, 0, v33
	v_min_f32_e32 v38, 0, v35
	v_exp_f32_e32 v140, v42
	v_mul_f32_e32 v41, 0x3fb8aa3b, v36
	v_mul_f32_e32 v79, 0x3fb8aa3b, v38
	v_exp_f32_e32 v78, v41
	s_waitcnt lgkmcnt(1)
	v_mul_f32_e32 v56, v56, v107
	v_exp_f32_e32 v79, v79
	v_mul_f32_e32 v56, v20, v56
	v_cndmask_b32_e64 v107, v56, 0, s[60:61]
	v_mul_f32_e32 v56, v57, v140
	v_readlane_b32 s60, v254, 63
	v_mul_f32_e32 v56, v21, v56
	v_readlane_b32 s61, v253, 0
	s_waitcnt vmcnt(3)
	v_mfma_f32_16x16x32_bf16 v[32:35], v[12:15], v[44:47], 0
	v_cndmask_b32_e64 v140, 0, v56, s[60:61]
	s_waitcnt lgkmcnt(0)
	v_pk_mul_f32 v[56:57], v[60:61], v[78:79]
	v_readlane_b32 s60, v254, 61
	v_pk_mul_f32 v[56:57], v[16:17], v[56:57]
	v_readlane_b32 s61, v254, 62
	v_sub_f32_e32 v60, v106, v26
	v_min_f32_e32 v60, 0, v60
	v_cndmask_b32_e64 v78, v57, 0, s[60:61]
	v_readlane_b32 s60, v254, 59
	v_readlane_b32 s61, v254, 60
	v_sub_f32_e32 v57, v106, v31
	v_min_f32_e32 v57, 0, v57
	v_cndmask_b32_e64 v79, v56, 0, s[60:61]
	v_sub_f32_e32 v56, v106, v30
	v_min_f32_e32 v56, 0, v56
	v_mul_f32_e32 v56, 0x3fb8aa3b, v56
	v_mul_f32_e32 v57, 0x3fb8aa3b, v57
	v_exp_f32_e32 v56, v56
	v_exp_f32_e32 v57, v57
	v_mul_f32_e32 v60, 0x3fb8aa3b, v60
	v_exp_f32_e32 v60, v60
	v_readlane_b32 s60, v254, 57
	v_pk_mul_f32 v[56:57], v[58:59], v[56:57]
	v_sub_f32_e32 v58, v106, v27
	v_min_f32_e32 v58, 0, v58
	v_mul_f32_e32 v58, 0x3fb8aa3b, v58
	v_exp_f32_e32 v61, v58
	v_pk_mul_f32 v[56:57], v[22:23], v[56:57]
	v_readlane_b32 s61, v254, 58
	s_waitcnt vmcnt(2)
; #define LAS __attribute__((address_space(3)))
; __device__ __forceinline__ unsigned pk2(float lo, float hi) { return pg8::cvt_pk_bf16(lo, hi); }
; template <int NMT> __device__ __forceinline__ void ssd_out_item(const int ci, const int mt0, const float* DT, const bf16* XT, const bf16* BN, const bf16* CN, const bf16* HST, const bf16* Z, const float* ssd_norm, ...
;     ...
;         for (int ks = 0; ks < 2; ++ks) {
;             bf16x8 xf[4];
; #pragma unroll
;             for (int nt = 0; nt < 4; ++nt) xf[nt] = *(const bf16x8*)(XT + ((size_t)(ci * 8 + h) * 64 + 16 * nt + fr) * 64 + 32 * ks + 8 * fq);
;             const int s0 = 32 * ks + 8 * fq;
;             const f32x4 as0 = *(const LAS f32x4*)(sAcs + h * 64 + s0), as1 = *(const LAS f32x4*)(sAcs + h * 64 + s0 + 4), d0 = *(const LAS f32x4*)(sDt + h * 64 + s0), d1 = *(const LAS f32x4*)(sDt + h * 64 + s0 + 4);
; #pragma unroll
;             for (int mt = 0; mt < NMT; ++mt) { const int l = 16 * (mt0 + mt) + fr; const float al = sAcs[h * 64 + l];
;                 const f32x4 c0 = *(const LAS f32x4*)(sCB + (g * 64 + l) * 68 + s0), c1 = *(const LAS f32x4*)(sCB + (g * 64 + l) * 68 + s0 + 4);
;                 float mv[8];
; #pragma unroll
;                 for (int j = 0; j < 4; ++j) { mv[j] = (s0 + j <= l) ? c0[j] * __expf(fminf(al - as0[j], 0.f)) * d0[j] : 0.f; mv[4 + j] = (s0 + 4 + j <= l) ? c1[j] * __expf(fminf(al - as1[j], 0.f)) * d1[j] : 0.f; }
; #pragma unroll
;                 for (int j = 0; j < 8; ++j) if (s0 + j == l) mv[j] += Dh;
;                 v4u mw; mw.x = pk2(mv[0], mv[1]); mw.y = pk2(mv[2], mv[3]); mw.z = pk2(mv[4], mv[5]); mw.w = pk2(mv[6], mv[7]);
;                 const bf16x8 mf = __builtin_bit_cast(bf16x8, mw);
; #pragma unroll
;                 for (int nt = 0; nt < 4; ++nt) acc[nt][mt] = __builtin_amdgcn_mfma_f32_16x16x32_bf16(xf[nt], mf, acc[nt][mt], 0, 0, 0); }
	v_mfma_f32_16x16x32_bf16 v[36:39], v[8:11], v[44:47], 0
	v_cndmask_b32_e64 v58, v57, 0, s[60:61]
	v_readlane_b32 s60, v254, 55
	v_readlane_b32 s61, v254, 56
	s_waitcnt vmcnt(1)
	v_mfma_f32_16x16x32_bf16 v[40:43], v[4:7], v[44:47], 0
	v_cndmask_b32_e64 v59, v56, 0, s[60:61]
	v_pk_mul_f32 v[56:57], v[62:63], v[60:61]
	v_readlane_b32 s60, v254, 53
	v_pk_mul_f32 v[56:57], v[18:19], v[56:57]
	v_readlane_b32 s61, v254, 54
	v_add_f32_e32 v60, v81, v107
	v_add_f32_e32 v61, v81, v140
	v_cndmask_b32_e64 v57, v57, 0, s[60:61]
	v_readlane_b32 s60, v254, 51
	v_readlane_b32 s61, v254, 52
	v_add_f32_e32 v62, v81, v59
	v_add_f32_e32 v63, v81, v78
	v_cndmask_b32_e64 v56, v56, 0, s[60:61]
	v_readlane_b32 s60, v254, 45
	v_readlane_b32 s61, v254, 46
	v_cndmask_b32_e64 v63, v78, v63, s[72:73]
	v_add_f32_e32 v78, v81, v56
	v_cndmask_b32_e64 v60, v107, v60, s[60:61]
	v_readlane_b32 s60, v254, 43
	v_readlane_b32 s61, v254, 44
	v_cndmask_b32_e64 v78, v56, v78, s[74:75]
	v_add_f32_e32 v56, v81, v57
	v_cndmask_b32_e64 v61, v140, v61, s[60:61]
	v_readlane_b32 s60, v254, 49
	v_readlane_b32 s61, v254, 50
	s_waitcnt vmcnt(0)
	v_mfma_f32_16x16x32_bf16 v[44:47], v[0:3], v[44:47], 0
	v_cndmask_b32_e64 v59, v59, v62, s[60:61]
	v_readlane_b32 s60, v254, 41
	v_add_f32_e32 v62, v81, v58
	v_readlane_b32 s61, v254, 42
	s_nop 1
	v_cndmask_b32_e64 v58, v58, v62, s[60:61]
	v_add_f32_e32 v62, v81, v79
	v_cndmask_b32_e64 v62, v79, v62, s[70:71]
	v_cndmask_b32_e64 v79, v57, v56, s[76:77]
	v_cvt_pk_bf16_f32 v56, v60, v61
	v_cvt_pk_bf16_f32 v57, v59, v58
	v_cvt_pk_bf16_f32 v58, v62, v63
	v_cvt_pk_bf16_f32 v59, v78, v79
	ds_read_b32 v78, v123 offset:34944
	v_add_u32_e32 v79, v122, v124
	v_mfma_f32_16x16x32_bf16 v[140:143], v[12:15], v[56:59], 0
	ds_read_b128 v[60:63], v79
	ds_read_b128 v[152:155], v79 offset:16
	s_waitcnt lgkmcnt(2)
	v_sub_f32_e32 v106, v78, v24
	v_mfma_f32_16x16x32_bf16 v[144:147], v[8:11], v[56:59], 0
	v_sub_f32_e32 v79, v78, v28
	v_min_f32_e32 v106, 0, v106
	v_min_f32_e32 v79, 0, v79
	v_mfma_f32_16x16x32_bf16 v[148:151], v[4:7], v[56:59], 0
	v_mul_f32_e32 v106, 0x3fb8aa3b, v106
	v_mul_f32_e32 v79, 0x3fb8aa3b, v79
	v_exp_f32_e32 v106, v106
	v_mfma_f32_16x16x32_bf16 v[156:159], v[0:3], v[56:59], 0
	v_sub_f32_e32 v58, v78, v29
	v_sub_f32_e32 v59, v78, v25
	v_min_f32_e32 v58, 0, v58
	v_min_f32_e32 v59, 0, v59
	v_mul_f32_e32 v58, 0x3fb8aa3b, v58
	v_mul_f32_e32 v59, 0x3fb8aa3b, v59
	v_exp_f32_e32 v79, v79
	v_exp_f32_e32 v58, v58
	v_exp_f32_e32 v59, v59
	s_waitcnt lgkmcnt(0)
	v_mul_f32_e32 v57, v152, v106
	v_mul_f32_e32 v56, v60, v79
	v_mul_f32_e32 v60, v16, v57
	v_mul_f32_e32 v57, v61, v58
	v_mul_f32_e32 v58, v153, v59
	v_sub_f32_e32 v59, v78, v30
	v_min_f32_e32 v59, 0, v59
	v_mul_f32_e32 v59, 0x3fb8aa3b, v59
	v_exp_f32_e32 v59, v59
	v_sub_f32_e32 v61, v78, v26
	v_min_f32_e32 v61, 0, v61
	v_mul_f32_e32 v61, 0x3fb8aa3b, v61
	v_mul_f32_e32 v59, v62, v59
	v_sub_f32_e32 v62, v78, v31
	v_sub_f32_e32 v78, v78, v27
	v_min_f32_e32 v62, 0, v62
	v_min_f32_e32 v78, 0, v78
	v_mul_f32_e32 v62, 0x3fb8aa3b, v62
	v_mul_f32_e32 v78, 0x3fb8aa3b, v78
	v_exp_f32_e32 v61, v61
	v_exp_f32_e32 v62, v62
	v_exp_f32_e32 v78, v78
	v_mul_f32_e32 v56, v20, v56
	v_mul_f32_e32 v57, v21, v57
	v_mul_f32_e32 v58, v17, v58
	v_mul_f32_e32 v59, v22, v59
	v_mul_f32_e32 v61, v154, v61
	v_mul_f32_e32 v62, v63, v62
	v_mul_f32_e32 v63, v155, v78
	v_mul_f32_e32 v61, v18, v61
	v_mul_f32_e32 v62, v23, v62
	v_mul_f32_e32 v63, v19, v63
	v_cvt_pk_bf16_f32 v56, v56, v57
	v_cvt_pk_bf16_f32 v57, v59, v62
	v_cvt_pk_bf16_f32 v58, v60, v58
	v_cvt_pk_bf16_f32 v59, v61, v63
	ds_read_b32 v78, v126 offset:34816
	v_add_u32_e32 v79, v122, v127
	ds_read_b128 v[60:63], v79
	ds_read_b128 v[168:171], v79 offset:16
	v_mfma_f32_16x16x32_bf16 v[152:155], v[12:15], v[56:59], 0
	s_waitcnt lgkmcnt(2)
	v_sub_f32_e32 v28, v78, v28
	v_min_f32_e32 v28, 0, v28
	v_mul_f32_e32 v28, 0x3fb8aa3b, v28
	v_exp_f32_e32 v28, v28
	v_sub_f32_e32 v24, v78, v24
	v_min_f32_e32 v24, 0, v24
	v_mul_f32_e32 v24, 0x3fb8aa3b, v24
	s_waitcnt lgkmcnt(1)
	v_mul_f32_e32 v28, v60, v28
	v_mul_f32_e32 v20, v20, v28
	v_sub_f32_e32 v28, v78, v29
	v_min_f32_e32 v28, 0, v28
	v_sub_f32_e32 v25, v78, v25
	v_exp_f32_e32 v24, v24
	v_mul_f32_e32 v28, 0x3fb8aa3b, v28
	v_min_f32_e32 v25, 0, v25
	v_exp_f32_e32 v28, v28
	v_mul_f32_e32 v25, 0x3fb8aa3b, v25
	v_exp_f32_e32 v25, v25
	s_waitcnt lgkmcnt(0)
	v_mul_f32_e32 v24, v168, v24
	v_mul_f32_e32 v24, v16, v24
	v_mul_f32_e32 v16, v61, v28
	v_mul_f32_e32 v16, v21, v16
	v_mul_f32_e32 v21, v169, v25
	v_sub_f32_e32 v25, v78, v30
	v_min_f32_e32 v25, 0, v25
	v_sub_f32_e32 v26, v78, v26
	v_mul_f32_e32 v25, 0x3fb8aa3b, v25
	v_min_f32_e32 v26, 0, v26
	v_exp_f32_e32 v25, v25
	v_mul_f32_e32 v26, 0x3fb8aa3b, v26
	v_exp_f32_e32 v26, v26
	v_mul_f32_e32 v21, v17, v21
	v_mul_f32_e32 v17, v62, v25
	v_sub_f32_e32 v25, v78, v31
	v_mul_f32_e32 v17, v22, v17
	v_mul_f32_e32 v22, v170, v26
	v_min_f32_e32 v25, 0, v25
	v_sub_f32_e32 v26, v78, v27
	v_mul_f32_e32 v25, 0x3fb8aa3b, v25
	v_min_f32_e32 v26, 0, v26
	v_exp_f32_e32 v25, v25
	v_mul_f32_e32 v26, 0x3fb8aa3b, v26
	v_exp_f32_e32 v26, v26
	v_mul_f32_e32 v22, v18, v22
	v_mul_f32_e32 v18, v63, v25
	v_mul_f32_e32 v18, v23, v18
	v_mul_f32_e32 v23, v171, v26
	v_mul_f32_e32 v19, v19, v23
	v_mfma_f32_16x16x32_bf16 v[160:163], v[8:11], v[56:59], 0
	v_cvt_pk_bf16_f32 v16, v20, v16
	v_cvt_pk_bf16_f32 v17, v17, v18
	v_cvt_pk_bf16_f32 v18, v24, v21
	v_mfma_f32_16x16x32_bf16 v[164:167], v[4:7], v[56:59], 0
	v_cvt_pk_bf16_f32 v19, v22, v19
	global_load_dwordx4 v[168:171], v[48:49], off offset:64
	global_load_dwordx4 v[180:183], v[54:55], off offset:64
	v_mfma_f32_16x16x32_bf16 v[172:175], v[0:3], v[56:59], 0
	global_load_dwordx4 v[56:59], v[52:53], off offset:64
	v_add_u32_e32 v78, v129, v127
	global_load_dwordx4 v[48:51], v[50:51], off offset:64
	v_mfma_f32_16x16x32_bf16 v[176:179], v[12:15], v[16:19], 0
	ds_read_b128 v[188:191], v128 offset:34816
	ds_read_b128 v[192:195], v128 offset:34832
	ds_read_b128 v[196:199], v128 offset:36864
	ds_read_b128 v[200:203], v128 offset:36880
	v_mfma_f32_16x16x32_bf16 v[184:187], v[8:11], v[16:19], 0
	v_mfma_f32_16x16x32_bf16 v[60:63], v[4:7], v[16:19], 0
	v_mfma_f32_16x16x32_bf16 v[52:55], v[0:3], v[16:19], 0
	v_cvt_pk_bf16_f32 v0, v85, v85
	v_cvt_pk_bf16_f32 v1, v85, v85
	v_cvt_pk_bf16_f32 v2, v85, v85
	v_cvt_pk_bf16_f32 v3, v85, v85
	v_cvt_pk_bf16_f32 v4, v85, v85
	v_cvt_pk_bf16_f32 v5, v85, v85
	v_cvt_pk_bf16_f32 v6, v85, v85
	v_cvt_pk_bf16_f32 v7, v85, v85
	s_waitcnt vmcnt(0)
; #define LAS __attribute__((address_space(3)))
; __device__ __forceinline__ unsigned pk2(float lo, float hi) { return pg8::cvt_pk_bf16(lo, hi); }
; template <int NMT> __device__ __forceinline__ void ssd_out_item(const int ci, const int mt0, const float* DT, const bf16* XT, const bf16* BN, const bf16* CN, const bf16* HST, const bf16* Z, const float* ssd_norm, ...
;     ...
;         for (int ks = 0; ks < 2; ++ks) {
;             bf16x8 xf[4];
; #pragma unroll
;             for (int nt = 0; nt < 4; ++nt) xf[nt] = *(const bf16x8*)(XT + ((size_t)(ci * 8 + h) * 64 + 16 * nt + fr) * 64 + 32 * ks + 8 * fq);
;             const int s0 = 32 * ks + 8 * fq;
;             const f32x4 as0 = *(const LAS f32x4*)(sAcs + h * 64 + s0), as1 = *(const LAS f32x4*)(sAcs + h * 64 + s0 + 4), d0 = *(const LAS f32x4*)(sDt + h * 64 + s0), d1 = *(const LAS f32x4*)(sDt + h * 64 + s0 + 4);
; #pragma unroll
;             for (int mt = 0; mt < NMT; ++mt) { const int l = 16 * (mt0 + mt) + fr; const float al = sAcs[h * 64 + l];
;                 const f32x4 c0 = *(const LAS f32x4*)(sCB + (g * 64 + l) * 68 + s0), c1 = *(const LAS f32x4*)(sCB + (g * 64 + l) * 68 + s0 + 4);
;                 float mv[8];
; #pragma unroll
;                 for (int j = 0; j < 4; ++j) { mv[j] = (s0 + j <= l) ? c0[j] * __expf(fminf(al - as0[j], 0.f)) * d0[j] : 0.f; mv[4 + j] = (s0 + 4 + j <= l) ? c1[j] * __expf(fminf(al - as1[j], 0.f)) * d1[j] : 0.f; }
; #pragma unroll
;                 for (int j = 0; j < 8; ++j) if (s0 + j == l) mv[j] += Dh;
;                 v4u mw; mw.x = pk2(mv[0], mv[1]); mw.y = pk2(mv[2], mv[3]); mw.z = pk2(mv[4], mv[5]); mw.w = pk2(mv[6], mv[7]);
;                 const bf16x8 mf = __builtin_bit_cast(bf16x8, mw);
; #pragma unroll
;                 for (int nt = 0; nt < 4; ++nt) acc[nt][mt] = __builtin_amdgcn_mfma_f32_16x16x32_bf16(xf[nt], mf, acc[nt][mt], 0, 0, 0); }
;         }
; #pragma unroll
;         for (int ks = 0; ks < 4; ++ks) {
;             bf16x8 hf[4];
; #pragma unroll
;             for (int nt = 0; nt < 4; ++nt) hf[nt] = *(const bf16x8*)(HST + ((size_t)(ci * 8 + h) * 64 + 16 * nt + fr) * 128 + 32 * ks + 8 * fq);
; #pragma unroll
;             for (int mt = 0; mt < NMT; ++mt) { const int l = 16 * (mt0 + mt) + fr; const float e = __expf(sAcs[h * 64 + l]);
;                 const v4u cw = *(const v4u*)(CN + (size_t)(row0 + l) * 256 + g * 128 + 32 * ks + 8 * fq); v4u o;
	v_mfma_f32_16x16x32_bf16 v[16:19], v[48:51], v[0:3], v[44:47]
	s_nop 2
	ds_read_b32 v44, v123 offset:34944
	v_mfma_f32_16x16x32_bf16 v[20:23], v[56:59], v[0:3], v[40:43]
	s_waitcnt lgkmcnt(0)
	s_nop 1
	v_sub_f32_e32 v40, v44, v188
	v_sub_f32_e32 v41, v44, v189
	v_min_f32_e32 v40, 0, v40
	v_min_f32_e32 v41, 0, v41
	v_mfma_f32_16x16x32_bf16 v[24:27], v[180:183], v[0:3], v[36:39]
	v_mul_f32_e32 v40, 0x3fb8aa3b, v40
	v_mul_f32_e32 v41, 0x3fb8aa3b, v41
	v_exp_f32_e32 v40, v40
	v_add_u32_e32 v36, v129, v124
	v_mfma_f32_16x16x32_bf16 v[28:31], v[168:171], v[0:3], v[32:35]
	s_nop 2
	ds_read_b128 v[32:35], v36
	ds_read_b128 v[36:39], v36 offset:16
	v_exp_f32_e32 v41, v41
	v_sub_f32_e32 v42, v44, v192
	v_min_f32_e32 v42, 0, v42
	v_mul_f32_e32 v42, 0x3fb8aa3b, v42
	s_waitcnt lgkmcnt(1)
	v_pk_mul_f32 v[32:33], v[32:33], v[40:41]
	v_sub_f32_e32 v40, v44, v193
	v_min_f32_e32 v40, 0, v40
	v_mul_f32_e32 v40, 0x3fb8aa3b, v40
	v_exp_f32_e32 v42, v42
	v_exp_f32_e32 v43, v40
	v_pk_mul_f32 v[32:33], v[196:197], v[32:33]
	v_mfma_f32_16x16x32_bf16 v[0:3], v[56:59], v[4:7], v[148:151]
	v_cndmask_b32_e64 v40, v33, 0, s[78:79]
	v_cndmask_b32_e64 v41, v32, 0, s[12:13]
	s_waitcnt lgkmcnt(0)
	v_pk_mul_f32 v[32:33], v[36:37], v[42:43]
	v_sub_f32_e32 v36, v44, v194
	v_pk_mul_f32 v[32:33], v[200:201], v[32:33]
	v_min_f32_e32 v36, 0, v36
	v_cndmask_b32_e64 v42, v33, 0, s[80:81]
	v_cndmask_b32_e64 v43, v32, 0, s[82:83]
	v_sub_f32_e32 v32, v44, v190
	v_sub_f32_e32 v33, v44, v191
	v_min_f32_e32 v32, 0, v32
	v_min_f32_e32 v33, 0, v33
	v_mul_f32_e32 v32, 0x3fb8aa3b, v32
	v_mul_f32_e32 v33, 0x3fb8aa3b, v33
	v_exp_f32_e32 v32, v32
	v_exp_f32_e32 v33, v33
	v_mul_f32_e32 v36, 0x3fb8aa3b, v36
	v_exp_f32_e32 v36, v36
	v_mfma_f32_16x16x32_bf16 v[8:11], v[180:183], v[4:7], v[144:147]
	v_mul_f32_e64 v32, v34, v32
	v_mul_f32_e64 v33, v35, v33
	v_sub_f32_e32 v34, v44, v195
	v_min_f32_e32 v34, 0, v34
	v_mul_f32_e32 v34, 0x3fb8aa3b, v34
	v_exp_f32_e32 v37, v34
	v_pk_mul_f32 v[32:33], v[198:199], v[32:33]
	v_mfma_f32_16x16x32_bf16 v[12:15], v[168:171], v[4:7], v[140:143]
	v_cndmask_b32_e64 v34, v33, 0, s[84:85]
	v_cndmask_b32_e64 v35, v32, 0, s[86:87]
	v_pk_mul_f32 v[32:33], v[38:39], v[36:37]
	v_add_f32_e32 v38, v81, v35
	v_pk_mul_f32 v[32:33], v[202:203], v[32:33]
	v_add_f32_e32 v37, v81, v40
	v_cndmask_b32_e64 v32, v32, 0, s[90:91]
	v_cndmask_b32_e64 v35, v35, v38, s[94:95]
	v_add_f32_e32 v38, v81, v34
	v_cndmask_b32_e64 v33, v33, 0, s[88:89]
	v_add_f32_e32 v36, v81, v41
	v_cndmask_b32_e64 v37, v40, v37, s[92:93]
	v_cndmask_b32_e64 v34, v34, v38, s[96:97]
	v_add_f32_e32 v38, v81, v43
	v_add_f32_e32 v39, v81, v42
	v_add_f32_e32 v40, v81, v32
	v_cndmask_b32_e64 v36, v41, v36, s[28:29]
	v_cndmask_b32_e64 v38, v43, v38, s[0:1]
	v_cndmask_b32_e64 v39, v42, v39, s[16:17]
	v_cndmask_b32_e64 v32, v32, v40, s[18:19]
	v_add_f32_e32 v40, v81, v33
	v_cndmask_b32_e64 v33, v33, v40, s[20:21]
	v_cvt_pk_bf16_f32 v36, v36, v37
	v_cvt_pk_bf16_f32 v37, v35, v34
	v_cvt_pk_bf16_f32 v38, v38, v39
	v_cvt_pk_bf16_f32 v39, v32, v33
	ds_read_b32 v148, v126 offset:34816
	ds_read_b128 v[44:47], v78
	ds_read_b128 v[144:147], v78 offset:16
	v_mfma_f32_16x16x32_bf16 v[4:7], v[48:51], v[4:7], v[156:159]
	s_waitcnt lgkmcnt(2)
	v_sub_f32_e32 v78, v148, v188
	v_sub_f32_e32 v79, v148, v189
	v_min_f32_e32 v78, 0, v78
	v_min_f32_e32 v79, 0, v79
	v_mul_f32_e32 v78, 0x3fb8aa3b, v78
	v_mul_f32_e32 v79, 0x3fb8aa3b, v79
	v_exp_f32_e32 v78, v78
	v_exp_f32_e32 v79, v79
	v_sub_f32_e32 v106, v148, v192
	v_min_f32_e32 v106, 0, v106
	v_mul_f32_e32 v106, 0x3fb8aa3b, v106
	s_waitcnt lgkmcnt(1)
	v_pk_mul_f32 v[44:45], v[44:45], v[78:79]
	v_sub_f32_e32 v78, v148, v193
	v_min_f32_e32 v78, 0, v78
	v_mul_f32_e32 v78, 0x3fb8aa3b, v78
	v_exp_f32_e32 v106, v106
	v_exp_f32_e32 v107, v78
	v_pk_mul_f32 v[44:45], v[196:197], v[44:45]
	v_sub_f32_e32 v78, v148, v194
	v_cndmask_b32_e64 v149, v45, 0, s[22:23]
	v_cndmask_b32_e64 v150, v44, 0, s[24:25]
	s_waitcnt lgkmcnt(0)
	v_pk_mul_f32 v[44:45], v[144:145], v[106:107]
	v_min_f32_e32 v78, 0, v78
	v_pk_mul_f32 v[44:45], v[200:201], v[44:45]
	v_mul_f32_e32 v78, 0x3fb8aa3b, v78
	v_cndmask_b32_e64 v106, v45, 0, s[26:27]
	v_cndmask_b32_e64 v107, v44, 0, s[30:31]
	v_sub_f32_e32 v44, v148, v190
	v_sub_f32_e32 v45, v148, v191
	v_min_f32_e32 v44, 0, v44
	v_min_f32_e32 v45, 0, v45
	v_mul_f32_e32 v44, 0x3fb8aa3b, v44
	v_mul_f32_e32 v45, 0x3fb8aa3b, v45
	v_exp_f32_e32 v44, v44
	v_exp_f32_e32 v45, v45
	v_exp_f32_e32 v78, v78
	v_mfma_f32_16x16x32_bf16 v[32:35], v[56:59], v[36:39], v[164:167]
	v_mul_f32_e64 v44, v46, v44
	v_mul_f32_e64 v45, v47, v45
	v_sub_f32_e32 v46, v148, v195
	v_min_f32_e32 v46, 0, v46
	v_mul_f32_e32 v46, 0x3fb8aa3b, v46
	v_exp_f32_e32 v79, v46
	v_pk_mul_f32 v[44:45], v[198:199], v[44:45]
	v_mfma_f32_16x16x32_bf16 v[140:143], v[168:171], v[36:39], v[152:155]
	v_cndmask_b32_e64 v47, v44, 0, s[36:37]
	v_cndmask_b32_e64 v46, v45, 0, s[34:35]
	v_add_f32_e32 v144, v81, v47
	v_pk_mul_f32 v[44:45], v[146:147], v[78:79]
	v_cndmask_b32_e64 v47, v47, v144, s[46:47]
	v_add_f32_e32 v144, v81, v46
	v_pk_mul_f32 v[44:45], v[202:203], v[44:45]
	v_cndmask_b32_e64 v46, v46, v144, s[48:49]
	v_add_f32_e32 v144, v81, v107
	v_cndmask_b32_e64 v44, v44, 0, s[40:41]
	v_cndmask_b32_e64 v107, v107, v144, s[50:51]
	v_add_f32_e32 v144, v81, v106
	v_cndmask_b32_e64 v45, v45, 0, s[38:39]
	v_cndmask_b32_e64 v106, v106, v144, s[52:53]
	v_add_f32_e32 v144, v81, v44
	v_cndmask_b32_e64 v44, v44, v144, s[54:55]
	v_add_f32_e32 v144, v81, v45
	v_add_f32_e32 v78, v81, v150
	v_add_f32_e32 v79, v81, v149
	v_cndmask_b32_e64 v45, v45, v144, s[56:57]
	v_cndmask_b32_e64 v78, v150, v78, s[42:43]
	v_cndmask_b32_e64 v79, v149, v79, s[44:45]
	v_cvt_pk_bf16_f32 v144, v78, v79
	v_cvt_pk_bf16_f32 v145, v47, v46
	v_cvt_pk_bf16_f32 v146, v107, v106
	v_cvt_pk_bf16_f32 v147, v44, v45
	v_lshl_add_u64 v[44:45], v[86:87], 0, v[70:71]
	global_load_dwordx4 v[156:159], v[44:45], off
	v_lshlrev_b64 v[46:47], 8, v[68:69]
	v_lshl_add_u64 v[46:47], v[94:95], 0, v[46:47]
	v_mfma_f32_16x16x32_bf16 v[56:59], v[56:59], v[144:147], v[60:63]
	s_nop 2
	global_load_dwordx4 v[60:63], v[46:47], off
	v_mfma_f32_16x16x32_bf16 v[68:71], v[48:51], v[144:147], v[52:55]
	s_waitcnt vmcnt(1)
; __device__ __forceinline__ float bflo(unsigned x) { return __uint_as_float(x << 16); }
; __device__ __forceinline__ float bfhi(unsigned x) { return __uint_as_float(x & 0xffff0000u); }
; __device__ __forceinline__ unsigned pk2(float lo, float hi) { return pg8::cvt_pk_bf16(lo, hi); }
; template <int NMT> __device__ __forceinline__ void ssd_out_item(const int ci, const int mt0, const float* DT, const bf16* XT, const bf16* BN, const bf16* CN, const bf16* HST, const bf16* Z, const float* ssd_norm, ...
;     ...
;         for (int ks = 0; ks < 4; ++ks) {
;             bf16x8 hf[4];
; #pragma unroll
;             for (int nt = 0; nt < 4; ++nt) hf[nt] = *(const bf16x8*)(HST + ((size_t)(ci * 8 + h) * 64 + 16 * nt + fr) * 128 + 32 * ks + 8 * fq);
; #pragma unroll
;             for (int mt = 0; mt < NMT; ++mt) { const int l = 16 * (mt0 + mt) + fr; const float e = __expf(sAcs[h * 64 + l]);
;                 const v4u cw = *(const v4u*)(CN + (size_t)(row0 + l) * 256 + g * 128 + 32 * ks + 8 * fq); v4u o;
; #pragma unroll
;                 for (int j = 0; j < 4; ++j) o[j] = pk2(bflo(cw[j]) * e, bfhi(cw[j]) * e);
;                 const bf16x8 cs = __builtin_bit_cast(bf16x8, o);
; #pragma unroll
;                 for (int nt = 0; nt < 4; ++nt) acc[nt][mt] = __builtin_amdgcn_mfma_f32_16x16x32_bf16(hf[nt], cs, acc[nt][mt], 0, 0, 0); }
;         }
	v_and_b32_e32 v106, 0xffff0000, v156
	s_nop 0
	ds_read_b32 v54, v123 offset:34816
	v_mfma_f32_16x16x32_bf16 v[40:43], v[180:183], v[36:39], v[160:163]
	v_lshlrev_b32_e32 v55, 16, v156
	v_lshlrev_b64 v[52:53], 8, v[76:77]
	v_lshl_add_u64 v[52:53], v[94:95], 0, v[52:53]
	s_waitcnt lgkmcnt(0)
	v_mul_f32_e32 v54, 0x3fb8aa3b, v54
	v_exp_f32_e32 v54, v54
	v_mfma_f32_16x16x32_bf16 v[36:39], v[48:51], v[36:39], v[172:175]
	v_lshlrev_b64 v[48:49], 8, v[72:73]
	v_lshlrev_b64 v[50:51], 8, v[74:75]
	v_lshl_add_u64 v[48:49], v[94:95], 0, v[48:49]
	v_lshl_add_u64 v[50:51], v[94:95], 0, v[50:51]
	v_mul_f32_e32 v55, v54, v55
	v_mul_f32_e32 v106, v54, v106
	v_mfma_f32_16x16x32_bf16 v[148:151], v[168:171], v[144:147], v[176:179]
	v_mfma_f32_16x16x32_bf16 v[152:155], v[180:183], v[144:147], v[184:187]
	global_load_dwordx4 v[144:147], v[48:49], off
	global_load_dwordx4 v[72:75], v[50:51], off
	global_load_dwordx4 v[76:79], v[52:53], off
	v_cvt_pk_bf16_f32 v156, v55, v106
	v_lshlrev_b32_e32 v55, 16, v157
	v_and_b32_e32 v106, 0xffff0000, v157
	v_mul_f32_e32 v55, v54, v55
	v_mul_f32_e32 v106, v54, v106
	v_cvt_pk_bf16_f32 v157, v55, v106
	v_lshlrev_b32_e32 v55, 16, v158
	v_and_b32_e32 v106, 0xffff0000, v158
	v_mul_f32_e32 v55, v54, v55
	v_mul_f32_e32 v106, v54, v106
	v_cvt_pk_bf16_f32 v158, v55, v106
	v_lshlrev_b32_e32 v55, 16, v159
	v_and_b32_e32 v106, 0xffff0000, v159
	v_mul_f32_e32 v55, v54, v55
	v_mul_f32_e32 v54, v54, v106
	v_cvt_pk_bf16_f32 v159, v55, v54
	v_add_u32_e32 v106, s33, v125
	s_waitcnt vmcnt(3)
	v_mfma_f32_16x16x32_bf16 v[160:163], v[60:63], v[156:159], v[28:31]
	v_ashrrev_i32_e32 v107, 31, v106
	s_nop 1
	v_lshl_add_u64 v[28:29], v[86:87], 0, v[66:67]
	global_load_dwordx4 v[164:167], v[28:29], off
	ds_read_b32 v30, v123 offset:34880
	s_waitcnt vmcnt(3)
	v_mfma_f32_16x16x32_bf16 v[24:27], v[144:147], v[156:159], v[24:27]
	s_waitcnt lgkmcnt(0)
	v_mul_f32_e32 v30, 0x3fb8aa3b, v30
	v_exp_f32_e32 v30, v30
	s_waitcnt vmcnt(0)
	v_lshlrev_b32_e32 v31, 16, v164
	v_and_b32_e32 v54, 0xffff0000, v164
	v_mul_f32_e32 v31, v30, v31
	v_mul_f32_e32 v54, v30, v54
	v_mfma_f32_16x16x32_bf16 v[20:23], v[72:75], v[156:159], v[20:23]
	v_mfma_f32_16x16x32_bf16 v[16:19], v[76:79], v[156:159], v[16:19]
	v_cvt_pk_bf16_f32 v156, v31, v54
	v_lshlrev_b32_e32 v31, 16, v165
	v_and_b32_e32 v54, 0xffff0000, v165
	v_mul_f32_e32 v31, v30, v31
	v_mul_f32_e32 v54, v30, v54
	v_cvt_pk_bf16_f32 v157, v31, v54
	v_lshlrev_b32_e32 v31, 16, v166
	v_and_b32_e32 v54, 0xffff0000, v166
	v_mul_f32_e32 v31, v30, v31
	v_mul_f32_e32 v54, v30, v54
	v_cvt_pk_bf16_f32 v158, v31, v54
	v_lshlrev_b32_e32 v31, 16, v167
	v_and_b32_e32 v54, 0xffff0000, v167
	v_mul_f32_e32 v31, v30, v31
	v_mul_f32_e32 v30, v30, v54
	v_cvt_pk_bf16_f32 v159, v31, v30
	s_nop 0
	v_mfma_f32_16x16x32_bf16 v[164:167], v[60:63], v[156:159], v[12:15]
	s_nop 2
	v_lshl_add_u64 v[14:15], v[86:87], 0, v[64:65]
	global_load_dwordx4 v[64:67], v[14:15], off
	ds_read_b32 v12, v123 offset:34944
	v_mfma_f32_16x16x32_bf16 v[8:11], v[144:147], v[156:159], v[8:11]
	s_waitcnt lgkmcnt(0)
	v_mul_f32_e32 v12, 0x3fb8aa3b, v12
	v_exp_f32_e32 v12, v12
	v_mfma_f32_16x16x32_bf16 v[0:3], v[72:75], v[156:159], v[0:3]
	s_waitcnt vmcnt(0)
	v_lshlrev_b32_e32 v13, 16, v64
	v_and_b32_e32 v30, 0xffff0000, v64
	v_mul_f32_e32 v13, v12, v13
	v_mul_f32_e32 v30, v12, v30
	v_cvt_pk_bf16_f32 v64, v13, v30
	v_lshlrev_b32_e32 v13, 16, v65
	v_and_b32_e32 v30, 0xffff0000, v65
	v_mul_f32_e32 v13, v12, v13
	v_mul_f32_e32 v30, v12, v30
	v_cvt_pk_bf16_f32 v65, v13, v30
	v_lshlrev_b32_e32 v13, 16, v66
	v_and_b32_e32 v30, 0xffff0000, v66
	v_mul_f32_e32 v13, v12, v13
	v_mul_f32_e32 v30, v12, v30
	v_cvt_pk_bf16_f32 v66, v13, v30
	v_lshlrev_b32_e32 v13, 16, v67
	v_and_b32_e32 v30, 0xffff0000, v67
	v_mul_f32_e32 v13, v12, v13
	v_mul_f32_e32 v12, v12, v30
	v_cvt_pk_bf16_f32 v67, v13, v12
	v_lshlrev_b64 v[12:13], 9, v[106:107]
	v_lshl_add_u64 v[12:13], v[86:87], 0, v[12:13]
	v_mfma_f32_16x16x32_bf16 v[4:7], v[76:79], v[156:159], v[4:7]
	global_load_dwordx4 v[156:159], v[12:13], off
	ds_read_b32 v54, v126 offset:34816
	v_mfma_f32_16x16x32_bf16 v[30:33], v[72:75], v[64:67], v[32:35]
	s_waitcnt lgkmcnt(0)
	s_nop 1
	v_mul_f32_e32 v34, 0x3fb8aa3b, v54
	v_exp_f32_e32 v54, v34
	v_mfma_f32_16x16x32_bf16 v[34:37], v[76:79], v[64:67], v[36:39]
	v_mfma_f32_16x16x32_bf16 v[140:143], v[60:63], v[64:67], v[140:143]
	s_waitcnt vmcnt(0)
	s_nop 0
	v_lshlrev_b32_e32 v38, 16, v156
	v_and_b32_e32 v39, 0xffff0000, v156
	v_mul_f32_e32 v38, v54, v38
	v_mul_f32_e32 v39, v54, v39
	v_mfma_f32_16x16x32_bf16 v[40:43], v[144:147], v[64:67], v[40:43]
	v_cvt_pk_bf16_f32 v64, v38, v39
	v_lshlrev_b32_e32 v38, 16, v157
	v_and_b32_e32 v39, 0xffff0000, v157
	v_mul_f32_e32 v38, v54, v38
	v_mul_f32_e32 v39, v54, v39
	v_cvt_pk_bf16_f32 v65, v38, v39
	v_lshlrev_b32_e32 v38, 16, v158
	v_and_b32_e32 v39, 0xffff0000, v158
	v_mul_f32_e32 v38, v54, v38
	v_mul_f32_e32 v39, v54, v39
	v_cvt_pk_bf16_f32 v66, v38, v39
	v_lshlrev_b32_e32 v38, 16, v159
	v_and_b32_e32 v39, 0xffff0000, v159
	v_mul_f32_e32 v38, v54, v38
	v_mul_f32_e32 v39, v54, v39
	v_cvt_pk_bf16_f32 v67, v38, v39
	ds_read_b32 v38, v123 offset:34816
	v_mfma_f32_16x16x32_bf16 v[60:63], v[60:63], v[64:67], v[148:151]
	s_waitcnt lgkmcnt(0)
	v_mul_f32_e32 v38, 0x3fb8aa3b, v38
	s_nop 0
	global_load_dwordx4 v[148:151], v[44:45], off offset:64
	v_mfma_f32_16x16x32_bf16 v[144:147], v[144:147], v[64:67], v[152:155]
	v_exp_f32_e32 v38, v38
	s_nop 1
	global_load_dwordx4 v[152:155], v[46:47], off offset:64
	v_mfma_f32_16x16x32_bf16 v[54:57], v[72:75], v[64:67], v[56:59]
	s_waitcnt vmcnt(1)
; __device__ __forceinline__ float bflo(unsigned x) { return __uint_as_float(x << 16); }
; __device__ __forceinline__ float bfhi(unsigned x) { return __uint_as_float(x & 0xffff0000u); }
; __device__ __forceinline__ unsigned pk2(float lo, float hi) { return pg8::cvt_pk_bf16(lo, hi); }
; template <int NMT> __device__ __forceinline__ void ssd_out_item(const int ci, const int mt0, const float* DT, const bf16* XT, const bf16* BN, const bf16* CN, const bf16* HST, const bf16* Z, const float* ssd_norm, ...
;     ...
;         for (int ks = 0; ks < 4; ++ks) {
;             bf16x8 hf[4];
; #pragma unroll
;             for (int nt = 0; nt < 4; ++nt) hf[nt] = *(const bf16x8*)(HST + ((size_t)(ci * 8 + h) * 64 + 16 * nt + fr) * 128 + 32 * ks + 8 * fq);
; #pragma unroll
;             for (int mt = 0; mt < NMT; ++mt) { const int l = 16 * (mt0 + mt) + fr; const float e = __expf(sAcs[h * 64 + l]);
;                 const v4u cw = *(const v4u*)(CN + (size_t)(row0 + l) * 256 + g * 128 + 32 * ks + 8 * fq); v4u o;
; #pragma unroll
;                 for (int j = 0; j < 4; ++j) o[j] = pk2(bflo(cw[j]) * e, bfhi(cw[j]) * e);
;                 const bf16x8 cs = __builtin_bit_cast(bf16x8, o);
; #pragma unroll
;                 for (int nt = 0; nt < 4; ++nt) acc[nt][mt] = __builtin_amdgcn_mfma_f32_16x16x32_bf16(hf[nt], cs, acc[nt][mt], 0, 0, 0); }
;         }
	v_lshlrev_b32_e32 v39, 16, v148
	s_nop 0
	v_and_b32_e32 v58, 0xffff0000, v148
	v_mul_f32_e32 v39, v38, v39
	v_mul_f32_e32 v58, v38, v58
	v_mfma_f32_16x16x32_bf16 v[64:67], v[76:79], v[64:67], v[68:71]
	s_nop 2
	global_load_dwordx4 v[68:71], v[48:49], off offset:64
	global_load_dwordx4 v[72:75], v[50:51], off offset:64
	global_load_dwordx4 v[76:79], v[52:53], off offset:64
	v_cvt_pk_bf16_f32 v148, v39, v58
	v_lshlrev_b32_e32 v39, 16, v149
	v_and_b32_e32 v58, 0xffff0000, v149
	v_mul_f32_e32 v39, v38, v39
	v_mul_f32_e32 v58, v38, v58
	v_cvt_pk_bf16_f32 v149, v39, v58
	v_lshlrev_b32_e32 v39, 16, v150
	v_and_b32_e32 v58, 0xffff0000, v150
	v_mul_f32_e32 v39, v38, v39
	v_mul_f32_e32 v58, v38, v58
	v_cvt_pk_bf16_f32 v150, v39, v58
	v_lshlrev_b32_e32 v39, 16, v151
	v_and_b32_e32 v58, 0xffff0000, v151
	v_mul_f32_e32 v39, v38, v39
	v_mul_f32_e32 v38, v38, v58
	v_cvt_pk_bf16_f32 v151, v39, v38
	ds_read_b32 v38, v123 offset:34880
	s_waitcnt vmcnt(3)
	v_mfma_f32_16x16x32_bf16 v[156:159], v[152:155], v[148:151], v[160:163]
	s_waitcnt lgkmcnt(0)
	v_mul_f32_e32 v38, 0x3fb8aa3b, v38
	s_nop 0
	global_load_dwordx4 v[160:163], v[28:29], off offset:64
	v_exp_f32_e32 v38, v38
	s_waitcnt vmcnt(3)
	v_mfma_f32_16x16x32_bf16 v[24:27], v[68:71], v[148:151], v[24:27]
	s_waitcnt vmcnt(0)
	v_lshlrev_b32_e32 v39, 16, v160
	v_and_b32_e32 v58, 0xffff0000, v160
	v_mul_f32_e32 v39, v38, v39
	v_mul_f32_e32 v58, v38, v58
	v_mfma_f32_16x16x32_bf16 v[20:23], v[72:75], v[148:151], v[20:23]
	v_mfma_f32_16x16x32_bf16 v[16:19], v[76:79], v[148:151], v[16:19]
	v_cvt_pk_bf16_f32 v148, v39, v58
	v_lshlrev_b32_e32 v39, 16, v161
	v_and_b32_e32 v58, 0xffff0000, v161
	v_mul_f32_e32 v39, v38, v39
	v_mul_f32_e32 v58, v38, v58
	v_cvt_pk_bf16_f32 v149, v39, v58
	v_lshlrev_b32_e32 v39, 16, v162
	v_and_b32_e32 v58, 0xffff0000, v162
	v_mul_f32_e32 v39, v38, v39
	v_mul_f32_e32 v58, v38, v58
	v_cvt_pk_bf16_f32 v150, v39, v58
	v_lshlrev_b32_e32 v39, 16, v163
	v_and_b32_e32 v58, 0xffff0000, v163
	v_mul_f32_e32 v39, v38, v39
	v_mul_f32_e32 v38, v38, v58
	v_cvt_pk_bf16_f32 v151, v39, v38
	ds_read_b32 v38, v123 offset:34944
	v_mfma_f32_16x16x32_bf16 v[160:163], v[152:155], v[148:151], v[164:167]
	s_waitcnt lgkmcnt(0)
	v_mul_f32_e32 v38, 0x3fb8aa3b, v38
	s_nop 0
	global_load_dwordx4 v[164:167], v[14:15], off offset:64
	v_exp_f32_e32 v38, v38
	v_mfma_f32_16x16x32_bf16 v[8:11], v[68:71], v[148:151], v[8:11]
	s_waitcnt vmcnt(0)
	v_lshlrev_b32_e32 v39, 16, v164
	v_mfma_f32_16x16x32_bf16 v[0:3], v[72:75], v[148:151], v[0:3]
	v_and_b32_e32 v58, 0xffff0000, v164
	v_lshlrev_b32_e32 v59, 16, v165
	v_and_b32_e32 v164, 0xffff0000, v167
	v_mfma_f32_16x16x32_bf16 v[4:7], v[76:79], v[148:151], v[4:7]
	v_and_b32_e32 v148, 0xffff0000, v165
	v_lshlrev_b32_e32 v149, 16, v166
	v_and_b32_e32 v150, 0xffff0000, v166
	v_lshlrev_b32_e32 v151, 16, v167
	v_mul_f32_e32 v165, v38, v148
	v_mul_f32_e32 v166, v38, v149
	v_mul_f32_e32 v150, v38, v150
	v_mul_f32_e32 v151, v38, v151
	v_mul_f32_e32 v39, v38, v39
	v_mul_f32_e32 v58, v38, v58
	v_mul_f32_e32 v59, v38, v59
	v_mul_f32_e32 v38, v38, v164
	v_cvt_pk_bf16_f32 v148, v39, v58
	v_cvt_pk_bf16_f32 v149, v59, v165
	v_cvt_pk_bf16_f32 v150, v166, v150
	v_cvt_pk_bf16_f32 v151, v151, v38
	global_load_dwordx4 v[164:167], v[12:13], off offset:64
	v_mfma_f32_16x16x32_bf16 v[38:41], v[68:71], v[148:151], v[40:43]
	s_waitcnt vmcnt(0)
	v_and_b32_e32 v58, 0xffff0000, v164
	s_nop 0
	ds_read_b32 v42, v126 offset:34816
	v_mfma_f32_16x16x32_bf16 v[140:143], v[152:155], v[148:151], v[140:143]
	v_lshlrev_b32_e32 v43, 16, v164
	v_lshlrev_b32_e32 v59, 16, v165
	v_and_b32_e32 v164, 0xffff0000, v167
	s_waitcnt lgkmcnt(0)
	v_mul_f32_e32 v42, 0x3fb8aa3b, v42
	v_exp_f32_e32 v42, v42
	v_mfma_f32_16x16x32_bf16 v[30:33], v[72:75], v[148:151], v[30:33]
	v_mul_f32_e32 v43, v42, v43
	v_mfma_f32_16x16x32_bf16 v[34:37], v[76:79], v[148:151], v[34:37]
	v_and_b32_e32 v148, 0xffff0000, v165
	v_lshlrev_b32_e32 v149, 16, v166
	v_and_b32_e32 v150, 0xffff0000, v166
	v_lshlrev_b32_e32 v151, 16, v167
	v_mul_f32_e32 v165, v42, v148
	v_mul_f32_e32 v166, v42, v149
	v_mul_f32_e32 v150, v42, v150
	v_mul_f32_e32 v151, v42, v151
	v_mul_f32_e32 v58, v42, v58
	v_mul_f32_e32 v59, v42, v59
	v_mul_f32_e32 v42, v42, v164
	v_cvt_pk_bf16_f32 v148, v43, v58
	v_cvt_pk_bf16_f32 v149, v59, v165
	v_cvt_pk_bf16_f32 v150, v166, v150
	v_cvt_pk_bf16_f32 v151, v151, v42
	global_load_dwordx4 v[164:167], v[44:45], off offset:128
	ds_read_b32 v42, v123 offset:34816
	v_mfma_f32_16x16x32_bf16 v[58:61], v[152:155], v[148:151], v[60:63]
	global_load_dwordx4 v[152:155], v[46:47], off offset:128
	s_waitcnt lgkmcnt(0)
	v_mul_f32_e32 v42, 0x3fb8aa3b, v42
	v_exp_f32_e32 v42, v42
	v_mfma_f32_16x16x32_bf16 v[68:71], v[68:71], v[148:151], v[144:147]
	s_waitcnt vmcnt(1)
	v_lshlrev_b32_e32 v43, 16, v164
	s_nop 0
	global_load_dwordx4 v[144:147], v[48:49], off offset:128
	v_mfma_f32_16x16x32_bf16 v[54:57], v[72:75], v[148:151], v[54:57]
	v_and_b32_e32 v74, 0xffff0000, v166
	v_lshlrev_b32_e32 v75, 16, v167
	v_and_b32_e32 v72, 0xffff0000, v165
	v_mfma_f32_16x16x32_bf16 v[62:65], v[76:79], v[148:151], v[64:67]
	v_lshlrev_b32_e32 v73, 16, v166
	v_and_b32_e32 v76, 0xffff0000, v167
	v_mul_f32_e32 v74, v42, v74
	v_and_b32_e32 v66, 0xffff0000, v164
	v_lshlrev_b32_e32 v67, 16, v165
	v_mul_f32_e32 v75, v42, v75
	global_load_dwordx4 v[168:171], v[50:51], off offset:128
	global_load_dwordx4 v[172:175], v[52:53], off offset:128
	v_mul_f32_e32 v43, v42, v43
	v_mul_f32_e32 v66, v42, v66
	v_mul_f32_e32 v67, v42, v67
	v_mul_f32_e32 v77, v42, v72
	v_mul_f32_e32 v78, v42, v73
	v_mul_f32_e32 v42, v42, v76
	v_cvt_pk_bf16_f32 v72, v43, v66
	v_cvt_pk_bf16_f32 v73, v67, v77
	v_cvt_pk_bf16_f32 v74, v78, v74
	v_cvt_pk_bf16_f32 v75, v75, v42
	global_load_dwordx4 v[148:151], v[28:29], off offset:128
	ds_read_b32 v42, v123 offset:34880
	s_waitcnt vmcnt(4)
; __device__ __forceinline__ float bflo(unsigned x) { return __uint_as_float(x << 16); }
; __device__ __forceinline__ float bfhi(unsigned x) { return __uint_as_float(x & 0xffff0000u); }
; __device__ __forceinline__ unsigned pk2(float lo, float hi) { return pg8::cvt_pk_bf16(lo, hi); }
; template <int NMT> __device__ __forceinline__ void ssd_out_item(const int ci, const int mt0, const float* DT, const bf16* XT, const bf16* BN, const bf16* CN, const bf16* HST, const bf16* Z, const float* ssd_norm, ...
;     ...
;         for (int ks = 0; ks < 4; ++ks) {
;             bf16x8 hf[4];
; #pragma unroll
;             for (int nt = 0; nt < 4; ++nt) hf[nt] = *(const bf16x8*)(HST + ((size_t)(ci * 8 + h) * 64 + 16 * nt + fr) * 128 + 32 * ks + 8 * fq);
; #pragma unroll
;             for (int mt = 0; mt < NMT; ++mt) { const int l = 16 * (mt0 + mt) + fr; const float e = __expf(sAcs[h * 64 + l]);
;                 const v4u cw = *(const v4u*)(CN + (size_t)(row0 + l) * 256 + g * 128 + 32 * ks + 8 * fq); v4u o;
; #pragma unroll
;                 for (int j = 0; j < 4; ++j) o[j] = pk2(bflo(cw[j]) * e, bfhi(cw[j]) * e);
;                 const bf16x8 cs = __builtin_bit_cast(bf16x8, o);
; #pragma unroll
;                 for (int nt = 0; nt < 4; ++nt) acc[nt][mt] = __builtin_amdgcn_mfma_f32_16x16x32_bf16(hf[nt], cs, acc[nt][mt], 0, 0, 0); }
	v_mfma_f32_16x16x32_bf16 v[76:79], v[152:155], v[72:75], v[156:159]
	s_waitcnt lgkmcnt(0)
	v_mul_f32_e32 v42, 0x3fb8aa3b, v42
	v_exp_f32_e32 v42, v42
	s_waitcnt vmcnt(3)
	v_mfma_f32_16x16x32_bf16 v[24:27], v[144:147], v[72:75], v[24:27]
	s_waitcnt vmcnt(0)
	v_lshlrev_b32_e32 v43, 16, v148
	v_mfma_f32_16x16x32_bf16 v[20:23], v[168:171], v[72:75], v[20:23]
	v_and_b32_e32 v66, 0xffff0000, v148
	v_lshlrev_b32_e32 v67, 16, v149
	v_and_b32_e32 v148, 0xffff0000, v151
	v_mfma_f32_16x16x32_bf16 v[16:19], v[172:175], v[72:75], v[16:19]
	v_and_b32_e32 v74, 0xffff0000, v150
	v_lshlrev_b32_e32 v75, 16, v151
	v_and_b32_e32 v72, 0xffff0000, v149
	v_lshlrev_b32_e32 v73, 16, v150
	v_mul_f32_e32 v74, v42, v74
	v_mul_f32_e32 v75, v42, v75
	v_mul_f32_e32 v43, v42, v43
	v_mul_f32_e32 v66, v42, v66
	v_mul_f32_e32 v67, v42, v67
	v_mul_f32_e32 v149, v42, v72
	v_mul_f32_e32 v150, v42, v73
	v_mul_f32_e32 v42, v42, v148
	v_cvt_pk_bf16_f32 v72, v43, v66
	v_cvt_pk_bf16_f32 v73, v67, v149
	v_cvt_pk_bf16_f32 v74, v150, v74
	v_cvt_pk_bf16_f32 v75, v75, v42
	s_nop 0
	v_mfma_f32_16x16x32_bf16 v[156:159], v[144:147], v[72:75], v[8:11]
	s_nop 2
	global_load_dwordx4 v[8:11], v[14:15], off offset:128
	v_mfma_f32_16x16x32_bf16 v[148:151], v[152:155], v[72:75], v[160:163]
	v_mfma_f32_16x16x32_bf16 v[160:163], v[168:171], v[72:75], v[0:3]
	s_nop 2
	ds_read_b32 v0, v123 offset:34944
	v_mfma_f32_16x16x32_bf16 v[164:167], v[172:175], v[72:75], v[4:7]
	s_waitcnt lgkmcnt(0)
	v_mul_f32_e32 v0, 0x3fb8aa3b, v0
	v_exp_f32_e32 v0, v0
	s_waitcnt vmcnt(0)
	v_lshlrev_b32_e32 v1, 16, v8
	v_and_b32_e32 v2, 0xffff0000, v8
	v_lshlrev_b32_e32 v3, 16, v9
	v_and_b32_e32 v4, 0xffff0000, v9
	v_lshlrev_b32_e32 v5, 16, v10
	v_and_b32_e32 v6, 0xffff0000, v10
	v_lshlrev_b32_e32 v7, 16, v11
	v_and_b32_e32 v8, 0xffff0000, v11
	v_mul_f32_e32 v1, v0, v1
	v_mul_f32_e32 v2, v0, v2
	v_mul_f32_e32 v3, v0, v3
	v_mul_f32_e32 v4, v0, v4
	v_mul_f32_e32 v5, v0, v5
	v_mul_f32_e32 v6, v0, v6
	v_mul_f32_e32 v7, v0, v7
	v_mul_f32_e32 v8, v0, v8
	v_cvt_pk_bf16_f32 v0, v1, v2
	v_cvt_pk_bf16_f32 v1, v3, v4
	v_cvt_pk_bf16_f32 v2, v5, v6
	v_cvt_pk_bf16_f32 v3, v7, v8
	global_load_dwordx4 v[4:7], v[12:13], off offset:128
	ds_read_b32 v8, v126 offset:34816
	v_mfma_f32_16x16x32_bf16 v[140:143], v[152:155], v[0:3], v[140:143]
	v_mfma_f32_16x16x32_bf16 v[176:179], v[144:147], v[0:3], v[38:41]
	v_mfma_f32_16x16x32_bf16 v[180:183], v[168:171], v[0:3], v[30:33]
	v_mfma_f32_16x16x32_bf16 v[184:187], v[172:175], v[0:3], v[34:37]
	s_waitcnt lgkmcnt(0)
	v_mul_f32_e32 v0, 0x3fb8aa3b, v8
	v_exp_f32_e32 v0, v0
	s_waitcnt vmcnt(0)
	v_lshlrev_b32_e32 v1, 16, v4
	v_and_b32_e32 v2, 0xffff0000, v4
	v_lshlrev_b32_e32 v3, 16, v5
	v_and_b32_e32 v4, 0xffff0000, v5
	v_lshlrev_b32_e32 v5, 16, v6
	v_and_b32_e32 v6, 0xffff0000, v6
	v_lshlrev_b32_e32 v8, 16, v7
	v_and_b32_e32 v7, 0xffff0000, v7
	v_mul_f32_e32 v1, v0, v1
	v_mul_f32_e32 v2, v0, v2
	v_mul_f32_e32 v3, v0, v3
	v_mul_f32_e32 v4, v0, v4
	v_mul_f32_e32 v5, v0, v5
	v_mul_f32_e32 v6, v0, v6
	v_mul_f32_e32 v8, v0, v8
	v_mul_f32_e32 v0, v0, v7
	v_cvt_pk_bf16_f32 v30, v1, v2
	v_cvt_pk_bf16_f32 v31, v3, v4
	v_cvt_pk_bf16_f32 v32, v5, v6
	v_cvt_pk_bf16_f32 v33, v8, v0
	global_load_dwordx4 v[72:75], v[48:49], off offset:192
	global_load_dwordx4 v[34:37], v[44:45], off offset:192
	global_load_dwordx4 v[188:191], v[46:47], off offset:192
	ds_read_b32 v38, v123 offset:34816
	v_mfma_f32_16x16x32_bf16 v[8:11], v[144:147], v[30:33], v[68:71]
	s_nop 2
	global_load_dwordx4 v[68:71], v[50:51], off offset:192
	global_load_dwordx4 v[0:3], v[52:53], off offset:192
	v_mfma_f32_16x16x32_bf16 v[152:155], v[152:155], v[30:33], v[58:61]
	v_mfma_f32_16x16x32_bf16 v[4:7], v[168:171], v[30:33], v[54:57]
	v_mfma_f32_16x16x32_bf16 v[44:47], v[172:175], v[30:33], v[62:65]
	s_waitcnt lgkmcnt(0)
	v_mul_f32_e32 v30, 0x3fb8aa3b, v38
	v_exp_f32_e32 v30, v30
	s_waitcnt vmcnt(3)
	v_lshlrev_b32_e32 v31, 16, v34
	v_and_b32_e32 v32, 0xffff0000, v34
	v_lshlrev_b32_e32 v33, 16, v35
	v_and_b32_e32 v34, 0xffff0000, v35
	v_lshlrev_b32_e32 v35, 16, v36
	v_and_b32_e32 v36, 0xffff0000, v36
	v_lshlrev_b32_e32 v38, 16, v37
	v_and_b32_e32 v37, 0xffff0000, v37
	v_mul_f32_e32 v31, v30, v31
	v_mul_f32_e32 v32, v30, v32
	v_mul_f32_e32 v33, v30, v33
	v_mul_f32_e32 v34, v30, v34
	v_mul_f32_e32 v35, v30, v35
	v_mul_f32_e32 v36, v30, v36
	v_mul_f32_e32 v38, v30, v38
	v_mul_f32_e32 v37, v30, v37
	v_cvt_pk_bf16_f32 v30, v31, v32
	v_cvt_pk_bf16_f32 v31, v33, v34
	v_cvt_pk_bf16_f32 v32, v35, v36
	v_cvt_pk_bf16_f32 v33, v38, v37
	s_nop 0
	v_mfma_f32_16x16x32_bf16 v[52:55], v[72:75], v[30:33], v[24:27]
	s_nop 2
	global_load_dwordx4 v[24:27], v[28:29], off offset:192
	s_waitcnt vmcnt(2)
	v_mfma_f32_16x16x32_bf16 v[64:67], v[68:71], v[30:33], v[20:23]
	s_nop 2
	ds_read_b32 v20, v123 offset:34880
	s_waitcnt vmcnt(1)
	v_mfma_f32_16x16x32_bf16 v[60:63], v[0:3], v[30:33], v[16:19]
	s_waitcnt vmcnt(0)
	v_lshlrev_b32_e32 v21, 16, v26
	s_waitcnt lgkmcnt(0)
	v_mul_f32_e32 v16, 0x3fb8aa3b, v20
	v_exp_f32_e32 v16, v16
	v_lshlrev_b32_e32 v17, 16, v24
	v_and_b32_e32 v18, 0xffff0000, v24
	v_lshlrev_b32_e32 v19, 16, v25
	v_and_b32_e32 v20, 0xffff0000, v25
	v_and_b32_e32 v22, 0xffff0000, v26
	v_lshlrev_b32_e32 v23, 16, v27
	v_and_b32_e32 v24, 0xffff0000, v27
	v_mul_f32_e32 v17, v16, v17
	v_mul_f32_e32 v18, v16, v18
	v_mul_f32_e32 v19, v16, v19
	v_mul_f32_e32 v20, v16, v20
	v_mul_f32_e32 v21, v16, v21
	v_mul_f32_e32 v22, v16, v22
	v_mul_f32_e32 v23, v16, v23
	v_mul_f32_e32 v24, v16, v24
	v_cvt_pk_bf16_f32 v16, v17, v18
	v_cvt_pk_bf16_f32 v17, v19, v20
	v_cvt_pk_bf16_f32 v18, v21, v22
	v_cvt_pk_bf16_f32 v19, v23, v24
	global_load_dwordx4 v[20:23], v[14:15], off offset:192
	ds_read_b32 v14, v123 offset:34944
	v_mfma_f32_16x16x32_bf16 v[56:59], v[188:191], v[30:33], v[76:79]
	s_waitcnt lgkmcnt(0)
; __device__ __forceinline__ float silu_f(float x) { return x * __builtin_amdgcn_rcpf(1.0f + __builtin_amdgcn_exp2f(-1.4426950408889634f * x)); }
; __device__ __forceinline__ float bflo(unsigned x) { return __uint_as_float(x << 16); }
; __device__ __forceinline__ float bfhi(unsigned x) { return __uint_as_float(x & 0xffff0000u); }
; __device__ __forceinline__ unsigned pk2(float lo, float hi) { return pg8::cvt_pk_bf16(lo, hi); }
; __device__ __forceinline__ float silu_f(float x) { return x * __builtin_amdgcn_rcpf(1.0f + __builtin_amdgcn_exp2f(-1.4426950408889634f * x)); }
; template <int NMT> __device__ __forceinline__ void ssd_out_item(const int ci, const int mt0, const float* DT, const bf16* XT, const bf16* BN, const bf16* CN, const bf16* HST, const bf16* Z, const float* ssd_norm, ...
;     ...
;         for (int ks = 0; ks < 4; ++ks) {
;             bf16x8 hf[4];
; #pragma unroll
;             for (int nt = 0; nt < 4; ++nt) hf[nt] = *(const bf16x8*)(HST + ((size_t)(ci * 8 + h) * 64 + 16 * nt + fr) * 128 + 32 * ks + 8 * fq);
; #pragma unroll
;             for (int mt = 0; mt < NMT; ++mt) { const int l = 16 * (mt0 + mt) + fr; const float e = __expf(sAcs[h * 64 + l]);
;                 const v4u cw = *(const v4u*)(CN + (size_t)(row0 + l) * 256 + g * 128 + 32 * ks + 8 * fq); v4u o;
; #pragma unroll
;                 for (int j = 0; j < 4; ++j) o[j] = pk2(bflo(cw[j]) * e, bfhi(cw[j]) * e);
;                 const bf16x8 cs = __builtin_bit_cast(bf16x8, o);
; #pragma unroll
;                 for (int nt = 0; nt < 4; ++nt) acc[nt][mt] = __builtin_amdgcn_mfma_f32_16x16x32_bf16(hf[nt], cs, acc[nt][mt], 0, 0, 0); }
;         }
; #pragma unroll
;         for (int mt = 0; mt < NMT; ++mt) { float ss = 0.f;
; #pragma unroll
;             for (int nt = 0; nt < 4; ++nt) { const v2u zr = *(const v2u*)(Z + (size_t)(row0 + 16 * (mt0 + mt) + fr) * 512 + h * 64 + 16 * nt + 4 * fq);
;                 f32x4 y = acc[nt][mt]; y[0] *= silu_f(bflo(zr.x)); y[1] *= silu_f(bfhi(zr.x)); y[2] *= silu_f(bflo(zr.y)); y[3] *= silu_f(bfhi(zr.y)); acc[nt][mt] = y;
;                 ss += (y[0] * y[0] + y[1] * y[1]) + (y[2] * y[2] + y[3] * y[3]); }
;             ss += __shfl_xor(ss, 16); ss += __shfl_xor(ss, 32);
;             if (fq == 0) sSS[h * 64 + 16 * (mt0 + mt) + fr] = ss; }
	v_mul_f32_e32 v14, 0x3fb8aa3b, v14
	v_exp_f32_e32 v14, v14
	v_mfma_f32_16x16x32_bf16 v[48:51], v[188:191], v[16:19], v[148:151]
	s_waitcnt vmcnt(0)
	v_lshlrev_b32_e32 v15, 16, v20
	v_mfma_f32_16x16x32_bf16 v[40:43], v[72:75], v[16:19], v[156:159]
	v_mul_f32_e32 v15, v14, v15
	v_mfma_f32_16x16x32_bf16 v[36:39], v[68:71], v[16:19], v[160:163]
	v_mfma_f32_16x16x32_bf16 v[32:35], v[0:3], v[16:19], v[164:167]
	v_and_b32_e32 v16, 0xffff0000, v20
	v_lshlrev_b32_e32 v17, 16, v21
	v_and_b32_e32 v18, 0xffff0000, v21
	v_lshlrev_b32_e32 v19, 16, v22
	v_and_b32_e32 v20, 0xffff0000, v22
	v_lshlrev_b32_e32 v21, 16, v23
	v_and_b32_e32 v22, 0xffff0000, v23
	v_mul_f32_e32 v16, v14, v16
	v_mul_f32_e32 v17, v14, v17
	v_mul_f32_e32 v18, v14, v18
	v_mul_f32_e32 v19, v14, v19
	v_mul_f32_e32 v20, v14, v20
	v_mul_f32_e32 v21, v14, v21
	v_mul_f32_e32 v22, v14, v22
	v_cvt_pk_bf16_f32 v14, v15, v16
	v_cvt_pk_bf16_f32 v15, v17, v18
	v_cvt_pk_bf16_f32 v16, v19, v20
	v_cvt_pk_bf16_f32 v17, v21, v22
	global_load_dwordx4 v[76:79], v[12:13], off offset:192
	ds_read_b32 v18, v126 offset:34816
	v_lshlrev_b64 v[12:13], 10, v[104:105]
	v_mfma_f32_16x16x32_bf16 v[28:31], v[188:191], v[14:17], v[140:143]
	s_waitcnt vmcnt(0)
	v_lshlrev_b32_e32 v19, 16, v77
	s_nop 0
	v_lshl_add_u64 v[140:141], v[92:93], 0, v[12:13]
	s_waitcnt lgkmcnt(0)
	v_mul_f32_e32 v12, 0x3fb8aa3b, v18
	v_exp_f32_e32 v12, v12
	v_lshlrev_b32_e32 v13, 16, v76
	v_and_b32_e32 v18, 0xffff0000, v76
	v_and_b32_e32 v76, 0xffff0000, v77
	v_lshlrev_b32_e32 v77, 16, v78
	v_and_b32_e32 v78, 0xffff0000, v78
	v_lshlrev_b32_e32 v142, 16, v79
	v_and_b32_e32 v79, 0xffff0000, v79
	v_mul_f32_e32 v143, v12, v76
	v_mul_f32_e32 v144, v12, v77
	v_mul_f32_e32 v78, v12, v78
	v_mul_f32_e32 v142, v12, v142
	v_mul_f32_e32 v13, v12, v13
	v_mul_f32_e32 v18, v12, v18
	v_mul_f32_e32 v19, v12, v19
	v_mul_f32_e32 v12, v12, v79
	v_cvt_pk_bf16_f32 v76, v13, v18
	v_cvt_pk_bf16_f32 v77, v19, v143
	v_cvt_pk_bf16_f32 v78, v144, v78
	v_cvt_pk_bf16_f32 v79, v142, v12
	global_load_dwordx2 v[142:143], v[140:141], off
	global_load_dwordx2 v[144:145], v[140:141], off offset:32
	global_load_dwordx2 v[146:147], v[140:141], off offset:64
	v_mfma_f32_16x16x32_bf16 v[24:27], v[72:75], v[14:17], v[176:179]
	v_mfma_f32_16x16x32_bf16 v[8:11], v[72:75], v[76:79], v[8:11]
	global_load_dwordx2 v[72:73], v[140:141], off offset:96
	s_waitcnt vmcnt(2)
	v_lshlrev_b32_e32 v74, 16, v144
	v_mfma_f32_16x16x32_bf16 v[20:23], v[68:71], v[14:17], v[180:183]
	v_and_b32_e32 v75, 0xffff0000, v144
	v_lshlrev_b32_e32 v140, 16, v145
	v_and_b32_e32 v141, 0xffff0000, v145
	v_mfma_f32_16x16x32_bf16 v[4:7], v[68:71], v[76:79], v[4:7]
	v_lshlrev_b32_e32 v68, 16, v142
	v_and_b32_e32 v69, 0xffff0000, v142
	v_lshlrev_b32_e32 v70, 16, v143
	v_and_b32_e32 v71, 0xffff0000, v143
	v_mfma_f32_16x16x32_bf16 v[16:19], v[0:3], v[14:17], v[184:187]
	s_waitcnt vmcnt(1)
	v_lshlrev_b32_e32 v142, 16, v146
	v_and_b32_e32 v143, 0xffff0000, v146
	v_lshlrev_b32_e32 v144, 16, v147
	v_mfma_f32_16x16x32_bf16 v[12:15], v[188:191], v[76:79], v[152:155]
	v_and_b32_e32 v145, 0xffff0000, v147
	s_waitcnt vmcnt(0)
	v_lshlrev_b32_e32 v146, 16, v72
	v_and_b32_e32 v147, 0xffff0000, v72
	v_lshlrev_b32_e32 v72, 16, v73
	v_and_b32_e32 v73, 0xffff0000, v73
	v_mul_f32_e32 v148, 0xbfb8aa3b, v68
	v_mul_f32_e32 v149, 0xbfb8aa3b, v69
	v_mul_f32_e32 v150, 0xbfb8aa3b, v70
	v_mul_f32_e32 v151, 0xbfb8aa3b, v71
	v_mul_f32_e32 v152, 0xbfb8aa3b, v74
	v_mul_f32_e32 v153, 0xbfb8aa3b, v75
	v_mul_f32_e32 v154, 0xbfb8aa3b, v140
	v_mul_f32_e32 v155, 0xbfb8aa3b, v141
	v_mul_f32_e32 v156, 0xbfb8aa3b, v142
	v_mul_f32_e32 v157, 0xbfb8aa3b, v143
	v_mul_f32_e32 v158, 0xbfb8aa3b, v144
	v_mul_f32_e32 v159, 0xbfb8aa3b, v145
	v_mul_f32_e32 v160, 0xbfb8aa3b, v146
	v_mul_f32_e32 v161, 0xbfb8aa3b, v147
	v_mul_f32_e32 v162, 0xbfb8aa3b, v72
	v_mul_f32_e32 v163, 0xbfb8aa3b, v73
	v_exp_f32_e32 v148, v148
	v_exp_f32_e32 v149, v149
	v_exp_f32_e32 v150, v150
	v_exp_f32_e32 v151, v151
	v_exp_f32_e32 v152, v152
	v_exp_f32_e32 v153, v153
	v_exp_f32_e32 v154, v154
	v_exp_f32_e32 v155, v155
	v_exp_f32_e32 v156, v156
	v_exp_f32_e32 v157, v157
	v_exp_f32_e32 v158, v158
	v_exp_f32_e32 v159, v159
	v_exp_f32_e32 v160, v160
	v_exp_f32_e32 v161, v161
	v_exp_f32_e32 v162, v162
	v_exp_f32_e32 v163, v163
	v_add_f32_e32 v148, 1.0, v148
	v_add_f32_e32 v149, 1.0, v149
	v_add_f32_e32 v150, 1.0, v150
	v_add_f32_e32 v151, 1.0, v151
	v_add_f32_e32 v152, 1.0, v152
	v_add_f32_e32 v153, 1.0, v153
	v_add_f32_e32 v154, 1.0, v154
	v_add_f32_e32 v155, 1.0, v155
	v_add_f32_e32 v156, 1.0, v156
	v_add_f32_e32 v157, 1.0, v157
	v_add_f32_e32 v158, 1.0, v158
	v_add_f32_e32 v159, 1.0, v159
	v_add_f32_e32 v160, 1.0, v160
	v_add_f32_e32 v161, 1.0, v161
	v_add_f32_e32 v162, 1.0, v162
	v_add_f32_e32 v163, 1.0, v163
	v_rcp_f32_e32 v148, v148
	v_rcp_f32_e32 v149, v149
	v_rcp_f32_e32 v150, v150
	v_rcp_f32_e32 v151, v151
	v_rcp_f32_e32 v152, v152
	v_rcp_f32_e32 v153, v153
	v_rcp_f32_e32 v154, v154
	v_rcp_f32_e32 v155, v155
	v_rcp_f32_e32 v156, v156
	v_rcp_f32_e32 v157, v157
	v_rcp_f32_e32 v158, v158
	v_rcp_f32_e32 v159, v159
	v_rcp_f32_e32 v160, v160
	v_rcp_f32_e32 v161, v161
	v_rcp_f32_e32 v162, v162
	v_rcp_f32_e32 v163, v163
	v_pk_mul_f32 v[68:69], v[148:149], v[68:69]
	v_pk_mul_f32 v[70:71], v[150:151], v[70:71]
	v_pk_mul_f32 v[148:149], v[152:153], v[74:75]
	v_pk_mul_f32 v[140:141], v[154:155], v[140:141]
	v_pk_mul_f32 v[142:143], v[156:157], v[142:143]
	v_pk_mul_f32 v[144:145], v[158:159], v[144:145]
	v_pk_mul_f32 v[146:147], v[160:161], v[146:147]
	v_pk_mul_f32 v[150:151], v[162:163], v[72:73]
	v_pk_mul_f32 v[72:73], v[56:57], v[68:69]
	v_pk_mul_f32 v[74:75], v[58:59], v[70:71]
	v_pk_mul_f32 v[68:69], v[52:53], v[148:149]
	v_pk_mul_f32 v[70:71], v[54:55], v[140:141]
	v_pk_mul_f32 v[56:57], v[64:65], v[142:143]
	v_pk_mul_f32 v[58:59], v[66:67], v[144:145]
	v_pk_mul_f32 v[52:53], v[60:61], v[146:147]
	v_pk_mul_f32 v[54:55], v[62:63], v[150:151]
	v_pk_mul_f32 v[140:141], v[56:57], v[56:57]
	v_pk_mul_f32 v[142:143], v[58:59], v[58:59]
	v_mul_f32_e32 v66, v70, v70
	v_fma_f32 v66, v71, v71, v66
	v_mul_f32_e32 v64, v68, v68
	v_fma_f32 v64, v69, v69, v64
	v_mul_f32_e32 v62, v74, v74
	v_fma_f32 v62, v75, v75, v62
	v_mul_f32_e32 v60, v72, v72
	v_fma_f32 v60, v73, v73, v60
	v_pk_mul_f32 v[144:145], v[52:53], v[52:53]
	v_pk_mul_f32 v[146:147], v[54:55], v[54:55]
	v_add_f32_e32 v61, v142, v143
	v_add_f32_e32 v63, v140, v141
	v_add_f32_e32 v64, v64, v66
	v_add_f32_e32 v60, v60, v62
	v_add_f32_e32 v65, v146, v147
	v_add_f32_e32 v67, v144, v145
	v_add_f32_e32 v61, v63, v61
	v_add_f32_e32 v60, v60, v64
	v_add_f32_e32 v60, v60, v61
	v_add_f32_e32 v61, v67, v65
	v_add_f32_e32 v60, v60, v61
	ds_bpermute_b32 v61, v130, v60
	v_mfma_f32_16x16x32_bf16 v[0:3], v[0:3], v[76:79], v[44:47]
	s_waitcnt lgkmcnt(0)
	v_add_f32_e32 v60, v60, v61
	ds_bpermute_b32 v61, v131, v60
	s_and_saveexec_b64 s[60:61], s[8:9]
	s_cbranch_execz .LBB0_1161
	s_waitcnt lgkmcnt(0)
	v_add_f32_e32 v44, v60, v61
	ds_write_b32 v132, v44 offset:38912
; __device__ __forceinline__ float silu_f(float x) { return x * __builtin_amdgcn_rcpf(1.0f + __builtin_amdgcn_exp2f(-1.4426950408889634f * x)); }
; __device__ __forceinline__ float bflo(unsigned x) { return __uint_as_float(x << 16); }
; __device__ __forceinline__ float bfhi(unsigned x) { return __uint_as_float(x & 0xffff0000u); }
; __device__ __forceinline__ float silu_f(float x) { return x * __builtin_amdgcn_rcpf(1.0f + __builtin_amdgcn_exp2f(-1.4426950408889634f * x)); }
; template <int NMT> __device__ __forceinline__ void ssd_out_item(const int ci, const int mt0, const float* DT, const bf16* XT, const bf16* BN, const bf16* CN, const bf16* HST, const bf16* Z, const float* ssd_norm, ...
;     ...
;         for (int mt = 0; mt < NMT; ++mt) { float ss = 0.f;
; #pragma unroll
;             for (int nt = 0; nt < 4; ++nt) { const v2u zr = *(const v2u*)(Z + (size_t)(row0 + 16 * (mt0 + mt) + fr) * 512 + h * 64 + 16 * nt + 4 * fq);
;                 f32x4 y = acc[nt][mt]; y[0] *= silu_f(bflo(zr.x)); y[1] *= silu_f(bfhi(zr.x)); y[2] *= silu_f(bflo(zr.y)); y[3] *= silu_f(bfhi(zr.y)); acc[nt][mt] = y;
;                 ss += (y[0] * y[0] + y[1] * y[1]) + (y[2] * y[2] + y[3] * y[3]); }
;             ss += __shfl_xor(ss, 16); ss += __shfl_xor(ss, 32);
;             if (fq == 0) sSS[h * 64 + 16 * (mt0 + mt) + fr] = ss; }
.LBB0_1161:
	s_or_b64 exec, exec, s[60:61]
	v_lshlrev_b64 v[44:45], 10, v[102:103]
	v_lshl_add_u64 v[76:77], v[92:93], 0, v[44:45]
	global_load_dwordx2 v[46:47], v[76:77], off
	s_waitcnt vmcnt(0)
	v_lshlrev_b32_e32 v44, 16, v46
	v_and_b32_e32 v45, 0xffff0000, v46
	v_mul_f32_e32 v46, 0xbfb8aa3b, v44
	v_exp_f32_e32 v46, v46
	s_nop 0
	v_add_f32_e32 v46, 1.0, v46
	v_rcp_f32_e32 v60, v46
	v_mul_f32_e32 v46, 0xbfb8aa3b, v45
	v_exp_f32_e32 v46, v46
	s_nop 0
	v_add_f32_e32 v46, 1.0, v46
	s_waitcnt lgkmcnt(0)
	v_rcp_f32_e32 v61, v46
	v_lshlrev_b32_e32 v46, 16, v47
	v_and_b32_e32 v47, 0xffff0000, v47
	v_pk_mul_f32 v[44:45], v[60:61], v[44:45]
	global_load_dwordx2 v[60:61], v[76:77], off offset:32
	v_pk_mul_f32 v[44:45], v[48:49], v[44:45]
	v_mul_f32_e32 v48, 0xbfb8aa3b, v46
	v_mul_f32_e32 v49, 0xbfb8aa3b, v47
	v_exp_f32_e32 v48, v48
	v_exp_f32_e32 v49, v49
	v_add_f32_e32 v48, 1.0, v48
	v_add_f32_e32 v49, 1.0, v49
	v_rcp_f32_e32 v48, v48
	v_rcp_f32_e32 v49, v49
	s_waitcnt vmcnt(0)
	v_lshlrev_b32_e32 v62, 16, v60
	v_and_b32_e32 v63, 0xffff0000, v60
	v_mul_f32_e32 v60, 0xbfb8aa3b, v62
	v_exp_f32_e32 v60, v60
	v_pk_mul_f32 v[46:47], v[48:49], v[46:47]
	v_pk_mul_f32 v[46:47], v[50:51], v[46:47]
	v_add_f32_e32 v60, 1.0, v60
	v_rcp_f32_e32 v64, v60
	v_mul_f32_e32 v60, 0xbfb8aa3b, v63
	v_exp_f32_e32 v60, v60
	v_pk_mul_f32 v[50:51], v[46:47], v[46:47]
	v_mul_f32_e32 v48, v44, v44
	v_fma_f32 v48, v45, v45, v48
	v_add_f32_e32 v50, v50, v51
	v_add_f32_e32 v60, 1.0, v60
	v_rcp_f32_e32 v65, v60
	v_lshlrev_b32_e32 v60, 16, v61
	v_and_b32_e32 v61, 0xffff0000, v61
	v_add_f32_e32 v48, v48, v50
	v_pk_mul_f32 v[62:63], v[64:65], v[62:63]
	global_load_dwordx2 v[64:65], v[76:77], off offset:64
	v_pk_mul_f32 v[40:41], v[40:41], v[62:63]
	global_load_dwordx2 v[76:77], v[76:77], off offset:96
	v_mul_f32_e32 v62, 0xbfb8aa3b, v60
	v_mul_f32_e32 v63, 0xbfb8aa3b, v61
	v_exp_f32_e32 v62, v62
	v_exp_f32_e32 v63, v63
	v_add_f32_e32 v62, 1.0, v62
	v_add_f32_e32 v63, 1.0, v63
	v_rcp_f32_e32 v62, v62
	v_rcp_f32_e32 v63, v63
	s_waitcnt vmcnt(1)
	v_lshlrev_b32_e32 v66, 16, v64
	v_and_b32_e32 v67, 0xffff0000, v64
	v_mul_f32_e32 v64, 0xbfb8aa3b, v66
	v_exp_f32_e32 v64, v64
	v_pk_mul_f32 v[60:61], v[62:63], v[60:61]
	v_add_f32_e32 v64, 1.0, v64
	v_rcp_f32_e32 v78, v64
	v_mul_f32_e32 v64, 0xbfb8aa3b, v67
	v_exp_f32_e32 v64, v64
	v_pk_mul_f32 v[42:43], v[42:43], v[60:61]
	v_pk_mul_f32 v[60:61], v[40:41], v[40:41]
	v_pk_mul_f32 v[62:63], v[42:43], v[42:43]
	v_add_f32_e32 v64, 1.0, v64
	v_rcp_f32_e32 v79, v64
	v_lshlrev_b32_e32 v64, 16, v65
	v_and_b32_e32 v65, 0xffff0000, v65
	v_add_f32_e32 v62, v62, v63
	v_pk_mul_f32 v[66:67], v[78:79], v[66:67]
	s_waitcnt vmcnt(0)
	v_lshlrev_b32_e32 v78, 16, v76
	v_and_b32_e32 v79, 0xffff0000, v76
	v_mul_f32_e32 v76, 0xbfb8aa3b, v78
	v_exp_f32_e32 v76, v76
	v_pk_mul_f32 v[36:37], v[36:37], v[66:67]
	v_mul_f32_e32 v66, 0xbfb8aa3b, v64
	v_mul_f32_e32 v67, 0xbfb8aa3b, v65
	v_add_f32_e32 v76, 1.0, v76
	v_rcp_f32_e32 v140, v76
	v_mul_f32_e32 v76, 0xbfb8aa3b, v79
	v_exp_f32_e32 v76, v76
	v_exp_f32_e32 v66, v66
	v_exp_f32_e32 v67, v67
	v_add_f32_e32 v60, v60, v61
	v_add_f32_e32 v76, 1.0, v76
	v_rcp_f32_e32 v141, v76
	v_lshlrev_b32_e32 v76, 16, v77
	v_and_b32_e32 v77, 0xffff0000, v77
	v_add_f32_e32 v66, 1.0, v66
	v_pk_mul_f32 v[78:79], v[140:141], v[78:79]
	v_add_f32_e32 v67, 1.0, v67
	v_pk_mul_f32 v[32:33], v[32:33], v[78:79]
	v_mul_f32_e32 v78, 0xbfb8aa3b, v76
	v_mul_f32_e32 v79, 0xbfb8aa3b, v77
	v_exp_f32_e32 v78, v78
	v_exp_f32_e32 v79, v79
	v_rcp_f32_e32 v66, v66
	v_rcp_f32_e32 v67, v67
	v_add_f32_e32 v78, 1.0, v78
	v_add_f32_e32 v79, 1.0, v79
	v_rcp_f32_e32 v78, v78
	v_rcp_f32_e32 v79, v79
	v_pk_mul_f32 v[64:65], v[66:67], v[64:65]
	v_add_f32_e32 v60, v60, v62
	v_pk_mul_f32 v[38:39], v[38:39], v[64:65]
	v_pk_mul_f32 v[64:65], v[36:37], v[36:37]
	v_pk_mul_f32 v[66:67], v[38:39], v[38:39]
	v_pk_mul_f32 v[76:77], v[78:79], v[76:77]
	v_add_f32_e32 v49, v66, v67
	v_pk_mul_f32 v[34:35], v[34:35], v[76:77]
	v_add_f32_e32 v50, v64, v65
	v_pk_mul_f32 v[76:77], v[32:33], v[32:33]
	v_pk_mul_f32 v[78:79], v[34:35], v[34:35]
	v_add_f32_e32 v48, v48, v60
	v_add_f32_e32 v49, v50, v49
	v_add_f32_e32 v48, v48, v49
	v_add_f32_e32 v49, v78, v79
	v_add_f32_e32 v50, v76, v77
	v_add_f32_e32 v49, v50, v49
	v_add_f32_e32 v48, v48, v49
	ds_bpermute_b32 v49, v130, v48
	s_waitcnt lgkmcnt(0)
	v_add_f32_e32 v48, v48, v49
	ds_bpermute_b32 v49, v131, v48
	s_and_saveexec_b64 s[60:61], s[8:9]
	s_cbranch_execz .LBB0_1163
	s_waitcnt lgkmcnt(0)
	v_add_f32_e32 v48, v48, v49
	ds_write_b32 v132, v48 offset:38976
; __device__ __forceinline__ float silu_f(float x) { return x * __builtin_amdgcn_rcpf(1.0f + __builtin_amdgcn_exp2f(-1.4426950408889634f * x)); }
; __device__ __forceinline__ float bflo(unsigned x) { return __uint_as_float(x << 16); }
; __device__ __forceinline__ float bfhi(unsigned x) { return __uint_as_float(x & 0xffff0000u); }
; __device__ __forceinline__ float silu_f(float x) { return x * __builtin_amdgcn_rcpf(1.0f + __builtin_amdgcn_exp2f(-1.4426950408889634f * x)); }
; template <int NMT> __device__ __forceinline__ void ssd_out_item(const int ci, const int mt0, const float* DT, const bf16* XT, const bf16* BN, const bf16* CN, const bf16* HST, const bf16* Z, const float* ssd_norm, ...
;     ...
;         for (int mt = 0; mt < NMT; ++mt) { float ss = 0.f;
; #pragma unroll
;             for (int nt = 0; nt < 4; ++nt) { const v2u zr = *(const v2u*)(Z + (size_t)(row0 + 16 * (mt0 + mt) + fr) * 512 + h * 64 + 16 * nt + 4 * fq);
;                 f32x4 y = acc[nt][mt]; y[0] *= silu_f(bflo(zr.x)); y[1] *= silu_f(bfhi(zr.x)); y[2] *= silu_f(bflo(zr.y)); y[3] *= silu_f(bfhi(zr.y)); acc[nt][mt] = y;
;                 ss += (y[0] * y[0] + y[1] * y[1]) + (y[2] * y[2] + y[3] * y[3]); }
;             ss += __shfl_xor(ss, 16); ss += __shfl_xor(ss, 32);
;             if (fq == 0) sSS[h * 64 + 16 * (mt0 + mt) + fr] = ss; }
.LBB0_1163:
	s_or_b64 exec, exec, s[60:61]
	s_waitcnt lgkmcnt(0)
	v_lshlrev_b64 v[48:49], 10, v[100:101]
	v_lshl_add_u64 v[76:77], v[92:93], 0, v[48:49]
	global_load_dwordx2 v[48:49], v[76:77], off
	s_waitcnt vmcnt(0)
	v_lshlrev_b32_e32 v50, 16, v48
	v_and_b32_e32 v51, 0xffff0000, v48
	v_mul_f32_e32 v48, 0xbfb8aa3b, v50
	v_exp_f32_e32 v48, v48
	s_nop 0
	v_add_f32_e32 v48, 1.0, v48
	v_rcp_f32_e32 v60, v48
	v_mul_f32_e32 v48, 0xbfb8aa3b, v51
	v_exp_f32_e32 v48, v48
	s_nop 0
	v_add_f32_e32 v48, 1.0, v48
	v_rcp_f32_e32 v61, v48
	v_lshlrev_b32_e32 v48, 16, v49
	v_and_b32_e32 v49, 0xffff0000, v49
	v_pk_mul_f32 v[50:51], v[60:61], v[50:51]
	global_load_dwordx2 v[60:61], v[76:77], off offset:32
	v_pk_mul_f32 v[28:29], v[28:29], v[50:51]
	v_mul_f32_e32 v50, 0xbfb8aa3b, v48
	v_mul_f32_e32 v51, 0xbfb8aa3b, v49
	v_exp_f32_e32 v50, v50
	v_exp_f32_e32 v51, v51
	v_add_f32_e32 v50, 1.0, v50
	v_add_f32_e32 v51, 1.0, v51
	v_rcp_f32_e32 v50, v50
	v_rcp_f32_e32 v51, v51
	s_waitcnt vmcnt(0)
	v_lshlrev_b32_e32 v62, 16, v60
	v_and_b32_e32 v63, 0xffff0000, v60
	v_mul_f32_e32 v60, 0xbfb8aa3b, v62
	v_exp_f32_e32 v60, v60
	v_pk_mul_f32 v[48:49], v[50:51], v[48:49]
	v_add_f32_e32 v60, 1.0, v60
	v_rcp_f32_e32 v64, v60
	v_mul_f32_e32 v60, 0xbfb8aa3b, v63
	v_exp_f32_e32 v60, v60
	v_pk_mul_f32 v[30:31], v[30:31], v[48:49]
	v_pk_mul_f32 v[50:51], v[30:31], v[30:31]
	v_add_f32_e32 v60, 1.0, v60
	v_rcp_f32_e32 v65, v60
	v_lshlrev_b32_e32 v60, 16, v61
	v_and_b32_e32 v61, 0xffff0000, v61
	v_add_f32_e32 v50, v50, v51
	v_pk_mul_f32 v[62:63], v[64:65], v[62:63]
	global_load_dwordx2 v[64:65], v[76:77], off offset:64
	v_pk_mul_f32 v[24:25], v[24:25], v[62:63]
	global_load_dwordx2 v[76:77], v[76:77], off offset:96
	v_mul_f32_e32 v62, 0xbfb8aa3b, v60
	v_mul_f32_e32 v63, 0xbfb8aa3b, v61
	v_exp_f32_e32 v62, v62
	v_exp_f32_e32 v63, v63
	v_mul_f32_e32 v48, v28, v28
	v_fma_f32 v48, v29, v29, v48
	v_add_f32_e32 v48, v48, v50
	v_add_f32_e32 v62, 1.0, v62
	v_add_f32_e32 v63, 1.0, v63
	v_rcp_f32_e32 v62, v62
	v_rcp_f32_e32 v63, v63
	s_waitcnt vmcnt(1)
	v_lshlrev_b32_e32 v66, 16, v64
	v_and_b32_e32 v67, 0xffff0000, v64
	v_mul_f32_e32 v64, 0xbfb8aa3b, v66
	v_exp_f32_e32 v64, v64
	v_pk_mul_f32 v[60:61], v[62:63], v[60:61]
	v_add_f32_e32 v64, 1.0, v64
	v_rcp_f32_e32 v78, v64
	v_mul_f32_e32 v64, 0xbfb8aa3b, v67
	v_exp_f32_e32 v64, v64
	v_pk_mul_f32 v[26:27], v[26:27], v[60:61]
	v_pk_mul_f32 v[60:61], v[24:25], v[24:25]
	v_pk_mul_f32 v[62:63], v[26:27], v[26:27]
	v_add_f32_e32 v64, 1.0, v64
	v_rcp_f32_e32 v79, v64
	v_lshlrev_b32_e32 v64, 16, v65
	v_and_b32_e32 v65, 0xffff0000, v65
	v_add_f32_e32 v62, v62, v63
	v_pk_mul_f32 v[66:67], v[78:79], v[66:67]
	s_waitcnt vmcnt(0)
	v_lshlrev_b32_e32 v78, 16, v76
	v_and_b32_e32 v79, 0xffff0000, v76
	v_mul_f32_e32 v76, 0xbfb8aa3b, v78
	v_exp_f32_e32 v76, v76
	v_pk_mul_f32 v[20:21], v[20:21], v[66:67]
	v_mul_f32_e32 v66, 0xbfb8aa3b, v64
	v_mul_f32_e32 v67, 0xbfb8aa3b, v65
	v_add_f32_e32 v76, 1.0, v76
	v_rcp_f32_e32 v140, v76
	v_mul_f32_e32 v76, 0xbfb8aa3b, v79
	v_exp_f32_e32 v76, v76
	v_exp_f32_e32 v66, v66
	v_exp_f32_e32 v67, v67
	v_add_f32_e32 v60, v60, v61
	v_add_f32_e32 v76, 1.0, v76
	v_rcp_f32_e32 v141, v76
	v_lshlrev_b32_e32 v76, 16, v77
	v_and_b32_e32 v77, 0xffff0000, v77
	v_add_f32_e32 v66, 1.0, v66
	v_pk_mul_f32 v[78:79], v[140:141], v[78:79]
	v_add_f32_e32 v67, 1.0, v67
	v_pk_mul_f32 v[16:17], v[16:17], v[78:79]
	v_mul_f32_e32 v78, 0xbfb8aa3b, v76
	v_mul_f32_e32 v79, 0xbfb8aa3b, v77
	v_exp_f32_e32 v78, v78
	v_exp_f32_e32 v79, v79
	v_rcp_f32_e32 v66, v66
	v_rcp_f32_e32 v67, v67
	v_add_f32_e32 v78, 1.0, v78
	v_add_f32_e32 v79, 1.0, v79
	v_rcp_f32_e32 v78, v78
	v_rcp_f32_e32 v79, v79
	v_pk_mul_f32 v[64:65], v[66:67], v[64:65]
	v_add_f32_e32 v60, v60, v62
	v_pk_mul_f32 v[22:23], v[22:23], v[64:65]
	v_pk_mul_f32 v[64:65], v[20:21], v[20:21]
	v_pk_mul_f32 v[66:67], v[22:23], v[22:23]
	v_pk_mul_f32 v[76:77], v[78:79], v[76:77]
	v_add_f32_e32 v49, v66, v67
	v_pk_mul_f32 v[18:19], v[18:19], v[76:77]
	v_add_f32_e32 v50, v64, v65
	v_pk_mul_f32 v[76:77], v[16:17], v[16:17]
	v_pk_mul_f32 v[78:79], v[18:19], v[18:19]
	v_add_f32_e32 v48, v48, v60
	v_add_f32_e32 v49, v50, v49
	v_add_f32_e32 v48, v48, v49
	v_add_f32_e32 v49, v78, v79
	v_add_f32_e32 v50, v76, v77
	v_add_f32_e32 v49, v50, v49
	v_add_f32_e32 v48, v48, v49
	ds_bpermute_b32 v49, v130, v48
	s_waitcnt lgkmcnt(0)
	v_add_f32_e32 v48, v48, v49
	ds_bpermute_b32 v49, v131, v48
	s_and_saveexec_b64 s[60:61], s[8:9]
	s_cbranch_execz .LBB0_1165
	s_waitcnt lgkmcnt(0)
	v_add_f32_e32 v48, v48, v49
	ds_write_b32 v132, v48 offset:39040
; __device__ __forceinline__ float silu_f(float x) { return x * __builtin_amdgcn_rcpf(1.0f + __builtin_amdgcn_exp2f(-1.4426950408889634f * x)); }
; __device__ __forceinline__ float bflo(unsigned x) { return __uint_as_float(x << 16); }
; __device__ __forceinline__ float bfhi(unsigned x) { return __uint_as_float(x & 0xffff0000u); }
; __device__ __forceinline__ float silu_f(float x) { return x * __builtin_amdgcn_rcpf(1.0f + __builtin_amdgcn_exp2f(-1.4426950408889634f * x)); }
; template <int NMT> __device__ __forceinline__ void ssd_out_item(const int ci, const int mt0, const float* DT, const bf16* XT, const bf16* BN, const bf16* CN, const bf16* HST, const bf16* Z, const float* ssd_norm, ...
;     ...
;         for (int mt = 0; mt < NMT; ++mt) { float ss = 0.f;
; #pragma unroll
;             for (int nt = 0; nt < 4; ++nt) { const v2u zr = *(const v2u*)(Z + (size_t)(row0 + 16 * (mt0 + mt) + fr) * 512 + h * 64 + 16 * nt + 4 * fq);
;                 f32x4 y = acc[nt][mt]; y[0] *= silu_f(bflo(zr.x)); y[1] *= silu_f(bfhi(zr.x)); y[2] *= silu_f(bflo(zr.y)); y[3] *= silu_f(bfhi(zr.y)); acc[nt][mt] = y;
;                 ss += (y[0] * y[0] + y[1] * y[1]) + (y[2] * y[2] + y[3] * y[3]); }
;             ss += __shfl_xor(ss, 16); ss += __shfl_xor(ss, 32);
;             if (fq == 0) sSS[h * 64 + 16 * (mt0 + mt) + fr] = ss; }
.LBB0_1165:
	s_or_b64 exec, exec, s[60:61]
	s_waitcnt lgkmcnt(0)
	v_lshlrev_b64 v[48:49], 10, v[108:109]
	v_lshl_add_u64 v[76:77], v[92:93], 0, v[48:49]
	global_load_dwordx2 v[48:49], v[76:77], off
	s_waitcnt vmcnt(0)
	v_lshlrev_b32_e32 v50, 16, v48
	v_and_b32_e32 v51, 0xffff0000, v48
	v_mul_f32_e32 v48, 0xbfb8aa3b, v50
	v_exp_f32_e32 v48, v48
	s_nop 0
	v_add_f32_e32 v48, 1.0, v48
	v_rcp_f32_e32 v60, v48
	v_mul_f32_e32 v48, 0xbfb8aa3b, v51
	v_exp_f32_e32 v48, v48
	s_nop 0
	v_add_f32_e32 v48, 1.0, v48
	v_rcp_f32_e32 v61, v48
	v_lshlrev_b32_e32 v48, 16, v49
	v_and_b32_e32 v49, 0xffff0000, v49
	v_pk_mul_f32 v[50:51], v[60:61], v[50:51]
	global_load_dwordx2 v[60:61], v[76:77], off offset:32
	v_pk_mul_f32 v[12:13], v[12:13], v[50:51]
	v_mul_f32_e32 v50, 0xbfb8aa3b, v48
	v_mul_f32_e32 v51, 0xbfb8aa3b, v49
	v_exp_f32_e32 v50, v50
	v_exp_f32_e32 v51, v51
	v_add_f32_e32 v50, 1.0, v50
	v_add_f32_e32 v51, 1.0, v51
	v_rcp_f32_e32 v50, v50
	v_rcp_f32_e32 v51, v51
	s_waitcnt vmcnt(0)
	v_lshlrev_b32_e32 v62, 16, v60
	v_and_b32_e32 v63, 0xffff0000, v60
	v_mul_f32_e32 v60, 0xbfb8aa3b, v62
	v_exp_f32_e32 v60, v60
	v_pk_mul_f32 v[48:49], v[50:51], v[48:49]
	v_add_f32_e32 v60, 1.0, v60
	v_rcp_f32_e32 v64, v60
	v_mul_f32_e32 v60, 0xbfb8aa3b, v63
	v_exp_f32_e32 v60, v60
	v_pk_mul_f32 v[14:15], v[14:15], v[48:49]
	v_pk_mul_f32 v[50:51], v[14:15], v[14:15]
	v_add_f32_e32 v60, 1.0, v60
	v_rcp_f32_e32 v65, v60
	v_lshlrev_b32_e32 v60, 16, v61
	v_and_b32_e32 v61, 0xffff0000, v61
	v_add_f32_e32 v50, v50, v51
	v_pk_mul_f32 v[62:63], v[64:65], v[62:63]
	global_load_dwordx2 v[64:65], v[76:77], off offset:64
	v_pk_mul_f32 v[8:9], v[8:9], v[62:63]
	global_load_dwordx2 v[76:77], v[76:77], off offset:96
	v_mul_f32_e32 v62, 0xbfb8aa3b, v60
	v_mul_f32_e32 v63, 0xbfb8aa3b, v61
	v_exp_f32_e32 v62, v62
	v_exp_f32_e32 v63, v63
	v_mul_f32_e32 v48, v12, v12
	v_fma_f32 v48, v13, v13, v48
	v_add_f32_e32 v48, v48, v50
	v_add_f32_e32 v62, 1.0, v62
	v_add_f32_e32 v63, 1.0, v63
	v_rcp_f32_e32 v62, v62
	v_rcp_f32_e32 v63, v63
	s_waitcnt vmcnt(1)
	v_lshlrev_b32_e32 v66, 16, v64
	v_and_b32_e32 v67, 0xffff0000, v64
	v_mul_f32_e32 v64, 0xbfb8aa3b, v66
	v_exp_f32_e32 v64, v64
	v_pk_mul_f32 v[60:61], v[62:63], v[60:61]
	v_add_f32_e32 v64, 1.0, v64
	v_rcp_f32_e32 v78, v64
	v_mul_f32_e32 v64, 0xbfb8aa3b, v67
	v_exp_f32_e32 v64, v64
	v_pk_mul_f32 v[10:11], v[10:11], v[60:61]
	v_pk_mul_f32 v[60:61], v[8:9], v[8:9]
	v_pk_mul_f32 v[62:63], v[10:11], v[10:11]
	v_add_f32_e32 v64, 1.0, v64
	v_rcp_f32_e32 v79, v64
	v_lshlrev_b32_e32 v64, 16, v65
	v_and_b32_e32 v65, 0xffff0000, v65
	v_add_f32_e32 v62, v62, v63
	v_pk_mul_f32 v[66:67], v[78:79], v[66:67]
	s_waitcnt vmcnt(0)
	v_lshlrev_b32_e32 v78, 16, v76
	v_and_b32_e32 v79, 0xffff0000, v76
	v_mul_f32_e32 v76, 0xbfb8aa3b, v78
	v_exp_f32_e32 v76, v76
	v_pk_mul_f32 v[4:5], v[4:5], v[66:67]
	v_mul_f32_e32 v66, 0xbfb8aa3b, v64
	v_mul_f32_e32 v67, 0xbfb8aa3b, v65
	v_add_f32_e32 v76, 1.0, v76
	v_rcp_f32_e32 v108, v76
	v_mul_f32_e32 v76, 0xbfb8aa3b, v79
	v_exp_f32_e32 v76, v76
	v_exp_f32_e32 v66, v66
	v_exp_f32_e32 v67, v67
	v_add_f32_e32 v60, v60, v61
	v_add_f32_e32 v76, 1.0, v76
	v_rcp_f32_e32 v109, v76
	v_lshlrev_b32_e32 v76, 16, v77
	v_and_b32_e32 v77, 0xffff0000, v77
	v_add_f32_e32 v66, 1.0, v66
	v_pk_mul_f32 v[78:79], v[108:109], v[78:79]
	v_add_f32_e32 v67, 1.0, v67
	v_pk_mul_f32 v[0:1], v[0:1], v[78:79]
	v_mul_f32_e32 v78, 0xbfb8aa3b, v76
	v_mul_f32_e32 v79, 0xbfb8aa3b, v77
	v_exp_f32_e32 v78, v78
	v_exp_f32_e32 v79, v79
	v_rcp_f32_e32 v66, v66
	v_rcp_f32_e32 v67, v67
	v_add_f32_e32 v78, 1.0, v78
	v_add_f32_e32 v79, 1.0, v79
	v_rcp_f32_e32 v78, v78
	v_rcp_f32_e32 v79, v79
	v_pk_mul_f32 v[64:65], v[66:67], v[64:65]
	v_add_f32_e32 v60, v60, v62
	v_pk_mul_f32 v[6:7], v[6:7], v[64:65]
	v_pk_mul_f32 v[64:65], v[4:5], v[4:5]
	v_pk_mul_f32 v[66:67], v[6:7], v[6:7]
	v_pk_mul_f32 v[76:77], v[78:79], v[76:77]
	v_add_f32_e32 v49, v66, v67
	v_pk_mul_f32 v[2:3], v[2:3], v[76:77]
	v_add_f32_e32 v50, v64, v65
	v_pk_mul_f32 v[76:77], v[0:1], v[0:1]
	v_pk_mul_f32 v[78:79], v[2:3], v[2:3]
	v_add_f32_e32 v48, v48, v60
	v_add_f32_e32 v49, v50, v49
	v_add_f32_e32 v48, v48, v49
	v_add_f32_e32 v49, v78, v79
	v_add_f32_e32 v50, v76, v77
	v_add_f32_e32 v49, v50, v49
	v_add_f32_e32 v48, v48, v49
	ds_bpermute_b32 v49, v130, v48
	s_waitcnt lgkmcnt(0)
	v_add_f32_e32 v48, v48, v49
	ds_bpermute_b32 v49, v131, v48
	s_and_saveexec_b64 s[60:61], s[8:9]
	s_cbranch_execz .LBB0_1158
	s_waitcnt lgkmcnt(0)
	v_add_f32_e32 v48, v48, v49
	ds_write_b32 v132, v48 offset:39104
	s_branch .LBB0_1158

; #define LAS __attribute__((address_space(3)))
; __device__ __forceinline__ unsigned pk2(float lo, float hi) { return pg8::cvt_pk_bf16(lo, hi); }
; template <int NMT> __device__ __forceinline__ void ssd_out_item(const int ci, const int mt0, const float* DT, const bf16* XT, const bf16* BN, const bf16* CN, const bf16* HST, const bf16* Z, const float* ssd_norm, ...
;     ...
;         __syncthreads();
;         f32x4 acc[4][NMT];
; #pragma unroll
;         for (int nt = 0; nt < 4; ++nt)
; #pragma unroll
;             for (int mt = 0; mt < NMT; ++mt) acc[nt][mt] = (f32x4){0.f, 0.f, 0.f, 0.f};
; #pragma unroll
;         for (int ks = 0; ks < 2; ++ks) {
;             bf16x8 xf[4];
; #pragma unroll
;             for (int nt = 0; nt < 4; ++nt) xf[nt] = *(const bf16x8*)(XT + ((size_t)(ci * 8 + h) * 64 + 16 * nt + fr) * 64 + 32 * ks + 8 * fq);
;             const int s0 = 32 * ks + 8 * fq;
;             const f32x4 as0 = *(const LAS f32x4*)(sAcs + h * 64 + s0), as1 = *(const LAS f32x4*)(sAcs + h * 64 + s0 + 4), d0 = *(const LAS f32x4*)(sDt + h * 64 + s0), d1 = *(const LAS f32x4*)(sDt + h * 64 + s0 + 4);
; #pragma unroll
;             for (int mt = 0; mt < NMT; ++mt) { const int l = 16 * (mt0 + mt) + fr; const float al = sAcs[h * 64 + l];
;                 const f32x4 c0 = *(const LAS f32x4*)(sCB + (g * 64 + l) * 68 + s0), c1 = *(const LAS f32x4*)(sCB + (g * 64 + l) * 68 + s0 + 4);
;                 float mv[8];
; #pragma unroll
;                 for (int j = 0; j < 4; ++j) { mv[j] = (s0 + j <= l) ? c0[j] * __expf(fminf(al - as0[j], 0.f)) * d0[j] : 0.f; mv[4 + j] = (s0 + 4 + j <= l) ? c1[j] * __expf(fminf(al - as1[j], 0.f)) * d1[j] : 0.f; }
; #pragma unroll
;                 for (int j = 0; j < 8; ++j) if (s0 + j == l) mv[j] += Dh;
;                 v4u mw; mw.x = pk2(mv[0], mv[1]); mw.y = pk2(mv[2], mv[3]); mw.z = pk2(mv[4], mv[5]); mw.w = pk2(mv[6], mv[7]);
;                 const bf16x8 mf = __builtin_bit_cast(bf16x8, mw);
; #pragma unroll
;                 for (int nt = 0; nt < 4; ++nt) acc[nt][mt] = __builtin_amdgcn_mfma_f32_16x16x32_bf16(xf[nt], mf, acc[nt][mt], 0, 0, 0); }
.LBB0_1172:
	s_lshl_b32 s14, s14, 3
	s_add_i32 s14, s14, s58
	s_ashr_i32 s15, s14, 31
	s_lshl_b64 s[14:15], s[14:15], 6
	v_or_b32_e32 v38, s16, v63
	v_mov_b32_e32 v37, s15
	v_or_b32_e32 v36, s14, v80
	v_mul_lo_u32 v38, v38, s18
	v_add_u32_e32 v112, 0, v38
	v_lshlrev_b64 v[38:39], 7, v[36:37]
	v_lshl_add_u64 v[48:49], v[14:15], 0, v[38:39]
	v_or_b32_e32 v38, 16, v36
	v_mov_b32_e32 v39, s15
	v_lshlrev_b64 v[40:41], 7, v[38:39]
	v_lshl_add_u64 v[102:103], v[14:15], 0, v[40:41]
	v_or_b32_e32 v40, 32, v36
	v_mov_b32_e32 v41, s15
	v_lshlrev_b64 v[42:43], 7, v[40:41]
	v_lshl_add_u64 v[104:105], v[14:15], 0, v[42:43]
	v_or_b32_e32 v42, 48, v36
	v_mov_b32_e32 v43, s15
	v_lshl_add_u32 v120, v63, 2, s17
	v_lshlrev_b64 v[68:69], 7, v[42:43]
	v_lshl_add_u32 v98, v0, 2, v112
	s_waitcnt lgkmcnt(0)
	s_barrier
	global_load_dwordx4 v[44:47], v[48:49], off
	global_load_dwordx4 v[64:67], v[102:103], off
	v_lshl_add_u64 v[106:107], v[14:15], 0, v[68:69]
	ds_read_b32 v108, v120 offset:34816
	ds_read_b128 v[68:71], v59 offset:34816
	ds_read_b128 v[72:75], v59 offset:34832
	ds_read_b128 v[76:79], v59 offset:36864
	ds_read_b128 v[82:85], v98
	global_load_dwordx4 v[86:89], v[104:105], off
	global_load_dwordx4 v[90:93], v[106:107], off
	s_waitcnt lgkmcnt(3)
	v_sub_f32_e32 v68, v108, v68
	v_min_f32_e32 v68, 0, v68
	v_mul_f32_e32 v68, 0x3fb8aa3b, v68
	v_sub_f32_e32 v69, v108, v69
	v_exp_f32_e32 v68, v68
	v_min_f32_e32 v69, 0, v69
	v_mul_f32_e32 v69, 0x3fb8aa3b, v69
	v_exp_f32_e32 v69, v69
	s_waitcnt lgkmcnt(0)
	v_mul_f32_e32 v68, v82, v68
	v_mul_f32_e32 v68, v76, v68
	v_cmp_le_u32_e32 vcc, v0, v63
	ds_read_b128 v[94:97], v59 offset:36880
	ds_read_b128 v[98:101], v98 offset:16
	v_cndmask_b32_e32 v76, 0, v68, vcc
	v_sub_f32_e32 v68, v108, v72
	v_mul_f32_e32 v72, v83, v69
	v_sub_f32_e32 v69, v108, v73
	v_min_f32_e32 v68, 0, v68
	v_min_f32_e32 v69, 0, v69
	v_mul_f32_e32 v68, 0x3fb8aa3b, v68
	v_mul_f32_e32 v69, 0x3fb8aa3b, v69
	v_exp_f32_e32 v68, v68
	v_exp_f32_e32 v69, v69
	v_mul_f32_e32 v72, v77, v72
	v_cmp_lt_u32_e32 vcc, v0, v63
	v_lshlrev_b64 v[36:37], 8, v[36:37]
	s_waitcnt lgkmcnt(0)
	v_pk_mul_f32 v[68:69], v[98:99], v[68:69]
	v_cndmask_b32_e32 v72, 0, v72, vcc
	v_pk_mul_f32 v[68:69], v[94:95], v[68:69]
	v_cmp_le_u32_e32 vcc, v1, v63
	v_lshlrev_b64 v[40:41], 8, v[40:41]
	s_nop 0
	v_cndmask_b32_e32 v73, 0, v69, vcc
	v_cmp_le_u32_e32 vcc, v16, v63
	v_sub_f32_e32 v69, v108, v71
	v_min_f32_e32 v69, 0, v69
	v_cndmask_b32_e32 v77, 0, v68, vcc
	v_sub_f32_e32 v68, v108, v70
	v_min_f32_e32 v68, 0, v68
	v_mul_f32_e32 v68, 0x3fb8aa3b, v68
	v_mul_f32_e32 v69, 0x3fb8aa3b, v69
	v_exp_f32_e32 v68, v68
	v_sub_f32_e32 v70, v108, v74
	v_exp_f32_e32 v69, v69
	v_sub_f32_e32 v71, v108, v75
	v_min_f32_e32 v70, 0, v70
	v_min_f32_e32 v71, 0, v71
	v_mul_f32_e32 v70, 0x3fb8aa3b, v70
	v_mul_f32_e32 v71, 0x3fb8aa3b, v71
	v_exp_f32_e32 v70, v70
	v_exp_f32_e32 v71, v71
	v_pk_mul_f32 v[68:69], v[84:85], v[68:69]
	v_cmp_le_u32_e32 vcc, v7, v63
	v_pk_mul_f32 v[68:69], v[78:79], v[68:69]
	s_nop 0
	v_cndmask_b32_e32 v74, 0, v69, vcc
	v_cmp_le_u32_e32 vcc, v18, v63
	s_nop 1
	v_cndmask_b32_e32 v75, 0, v68, vcc
	v_pk_mul_f32 v[68:69], v[100:101], v[70:71]
	v_cmp_le_u32_e32 vcc, v17, v63
	v_pk_mul_f32 v[68:69], v[96:97], v[68:69]
	v_add_f32_e32 v70, v81, v76
	v_cndmask_b32_e32 v69, 0, v69, vcc
	v_cmp_le_u32_e32 vcc, v20, v63
	v_add_f32_e32 v71, v81, v72
	s_nop 0
	v_cndmask_b32_e32 v68, 0, v68, vcc
	v_cmp_eq_u32_e32 vcc, v0, v63
	s_nop 1
	v_cndmask_b32_e32 v70, v76, v70, vcc
	v_cmp_eq_u32_e32 vcc, v60, v63
	v_add_f32_e32 v76, v81, v73
	s_nop 0
	v_cndmask_b32_e32 v71, v72, v71, vcc
	v_add_f32_e32 v72, v81, v75
	v_cmp_eq_u32_e32 vcc, v18, v63
	s_nop 1
	v_cndmask_b32_e32 v72, v75, v72, vcc
	v_add_f32_e32 v75, v81, v74
	v_cmp_eq_u32_e32 vcc, v7, v63
	s_nop 1
	v_cndmask_b32_e32 v74, v74, v75, vcc
	v_add_f32_e32 v75, v81, v77
	v_cmp_eq_u32_e32 vcc, v16, v63
	s_nop 1
	v_cndmask_b32_e32 v75, v77, v75, vcc
	v_cmp_eq_u32_e32 vcc, v1, v63
	s_nop 1
	v_cndmask_b32_e32 v73, v73, v76, vcc
	v_add_f32_e32 v76, v81, v68
	v_cmp_eq_u32_e32 vcc, v20, v63
	s_nop 1
	v_cndmask_b32_e32 v76, v68, v76, vcc
	v_add_f32_e32 v68, v81, v69
	v_cmp_eq_u32_e32 vcc, v17, v63
	s_nop 1
	v_cndmask_b32_e32 v77, v69, v68, vcc
	v_cvt_pk_bf16_f32 v68, v70, v71
	v_cvt_pk_bf16_f32 v69, v72, v74
	v_cvt_pk_bf16_f32 v70, v75, v73
	v_cvt_pk_bf16_f32 v71, v76, v77
	v_cmp_le_u32_e32 vcc, v19, v63
	s_waitcnt vmcnt(3)
	v_mfma_f32_16x16x32_bf16 v[44:47], v[44:47], v[68:71], 0
	s_waitcnt vmcnt(2)
	v_mfma_f32_16x16x32_bf16 v[64:67], v[64:67], v[68:71], 0
	s_waitcnt vmcnt(1)
	v_mfma_f32_16x16x32_bf16 v[72:75], v[86:89], v[68:71], 0
	s_waitcnt vmcnt(0)
	v_mfma_f32_16x16x32_bf16 v[68:71], v[90:93], v[68:71], 0
	global_load_dwordx4 v[76:79], v[48:49], off offset:64
	global_load_dwordx4 v[82:85], v[102:103], off offset:64
	global_load_dwordx4 v[86:89], v[104:105], off offset:64
	global_load_dwordx4 v[90:93], v[106:107], off offset:64
	ds_read_b128 v[94:97], v61 offset:34816
	ds_read_b128 v[98:101], v61 offset:34832
	ds_read_b32 v121, v120 offset:34816
	ds_read_b128 v[102:105], v61 offset:36864
	ds_read_b128 v[106:109], v61 offset:36880
	v_lshl_add_u32 v48, v22, 2, v112
	ds_read_b128 v[112:115], v48
	ds_read_b128 v[116:119], v48 offset:16
	s_waitcnt lgkmcnt(4)
	v_sub_f32_e32 v48, v121, v94
	v_sub_f32_e32 v49, v121, v95
	v_min_f32_e32 v48, 0, v48
	v_min_f32_e32 v49, 0, v49
	v_mul_f32_e32 v48, 0x3fb8aa3b, v48
	v_mul_f32_e32 v49, 0x3fb8aa3b, v49
	v_exp_f32_e32 v48, v48
	v_sub_f32_e32 v94, v121, v98
	v_exp_f32_e32 v49, v49
	v_sub_f32_e32 v95, v121, v99
	v_min_f32_e32 v94, 0, v94
	v_min_f32_e32 v95, 0, v95
	v_mul_f32_e32 v94, 0x3fb8aa3b, v94
	v_mul_f32_e32 v95, 0x3fb8aa3b, v95
	v_exp_f32_e32 v94, v94
	v_exp_f32_e32 v95, v95
	s_waitcnt lgkmcnt(1)
; #define LAS __attribute__((address_space(3)))
; template <int NMT> __device__ __forceinline__ void ssd_out_item(const int ci, const int mt0, const float* DT, const bf16* XT, const bf16* BN, const bf16* CN, const bf16* HST, const bf16* Z, const float* ssd_norm, ...
;     ...
;         for (int ks = 0; ks < 2; ++ks) {
;             bf16x8 xf[4];
; #pragma unroll
;             for (int nt = 0; nt < 4; ++nt) xf[nt] = *(const bf16x8*)(XT + ((size_t)(ci * 8 + h) * 64 + 16 * nt + fr) * 64 + 32 * ks + 8 * fq);
;             const int s0 = 32 * ks + 8 * fq;
;             const f32x4 as0 = *(const LAS f32x4*)(sAcs + h * 64 + s0), as1 = *(const LAS f32x4*)(sAcs + h * 64 + s0 + 4), d0 = *(const LAS f32x4*)(sDt + h * 64 + s0), d1 = *(const LAS f32x4*)(sDt + h * 64 + s0 + 4);
; #pragma unroll
;             for (int mt = 0; mt < NMT; ++mt) { const int l = 16 * (mt0 + mt) + fr; const float al = sAcs[h * 64 + l];
;                 const f32x4 c0 = *(const LAS f32x4*)(sCB + (g * 64 + l) * 68 + s0), c1 = *(const LAS f32x4*)(sCB + (g * 64 + l) * 68 + s0 + 4);
;                 float mv[8];
; #pragma unroll
;                 for (int j = 0; j < 4; ++j) { mv[j] = (s0 + j <= l) ? c0[j] * __expf(fminf(al - as0[j], 0.f)) * d0[j] : 0.f; mv[4 + j] = (s0 + 4 + j <= l) ? c1[j] * __expf(fminf(al - as1[j], 0.f)) * d1[j] : 0.f; }
; #pragma unroll
;                 for (int j = 0; j < 8; ++j) if (s0 + j == l) mv[j] += Dh;
;                 v4u mw; mw.x = pk2(mv[0], mv[1]); mw.y = pk2(mv[2], mv[3]); mw.z = pk2(mv[4], mv[5]); mw.w = pk2(mv[6], mv[7]);
;                 const bf16x8 mf = __builtin_bit_cast(bf16x8, mw);
; #pragma unroll
;                 for (int nt = 0; nt < 4; ++nt) acc[nt][mt] = __builtin_amdgcn_mfma_f32_16x16x32_bf16(xf[nt], mf, acc[nt][mt], 0, 0, 0); }
;         }
; #pragma unroll
;         for (int ks = 0; ks < 4; ++ks) {
;             bf16x8 hf[4];
; #pragma unroll
;             for (int nt = 0; nt < 4; ++nt) hf[nt] = *(const bf16x8*)(HST + ((size_t)(ci * 8 + h) * 64 + 16 * nt + fr) * 128 + 32 * ks + 8 * fq);
; #pragma unroll
;             for (int mt = 0; mt < NMT; ++mt) { const int l = 16 * (mt0 + mt) + fr; const float e = __expf(sAcs[h * 64 + l]);
;                 const v4u cw = *(const v4u*)(CN + (size_t)(row0 + l) * 256 + g * 128 + 32 * ks + 8 * fq); v4u o;
; #pragma unroll
;                 for (int j = 0; j < 4; ++j) o[j] = pk2(bflo(cw[j]) * e, bfhi(cw[j]) * e);
	v_pk_mul_f32 v[48:49], v[112:113], v[48:49]
	s_nop 0
	v_pk_mul_f32 v[48:49], v[102:103], v[48:49]
	s_nop 0
	v_cndmask_b32_e32 v98, 0, v49, vcc
	v_cmp_le_u32_e32 vcc, v22, v63
	s_nop 1
	v_cndmask_b32_e32 v99, 0, v48, vcc
	s_waitcnt lgkmcnt(0)
	v_pk_mul_f32 v[48:49], v[116:117], v[94:95]
	v_cmp_le_u32_e32 vcc, v21, v63
	v_pk_mul_f32 v[48:49], v[106:107], v[48:49]
	v_sub_f32_e32 v94, v121, v100
	v_cndmask_b32_e32 v102, 0, v49, vcc
	v_cmp_le_u32_e32 vcc, v24, v63
	v_sub_f32_e32 v49, v121, v97
	v_min_f32_e32 v49, 0, v49
	v_cndmask_b32_e32 v103, 0, v48, vcc
	v_sub_f32_e32 v48, v121, v96
	v_min_f32_e32 v48, 0, v48
	v_mul_f32_e32 v48, 0x3fb8aa3b, v48
	v_mul_f32_e32 v49, 0x3fb8aa3b, v49
	v_exp_f32_e32 v48, v48
	v_exp_f32_e32 v49, v49
	v_sub_f32_e32 v95, v121, v101
	v_min_f32_e32 v94, 0, v94
	v_min_f32_e32 v95, 0, v95
	v_mul_f32_e32 v94, 0x3fb8aa3b, v94
	v_mul_f32_e32 v95, 0x3fb8aa3b, v95
	v_exp_f32_e32 v94, v94
	v_exp_f32_e32 v95, v95
	v_pk_mul_f32 v[48:49], v[114:115], v[48:49]
	v_cmp_le_u32_e32 vcc, v23, v63
	v_pk_mul_f32 v[48:49], v[104:105], v[48:49]
	v_lshl_add_u64 v[104:105], v[30:31], 0, v[40:41]
	v_cndmask_b32_e32 v96, 0, v49, vcc
	v_cmp_le_u32_e32 vcc, v26, v63
	v_lshlrev_b64 v[40:41], 8, v[42:43]
	v_lshl_add_u64 v[106:107], v[30:31], 0, v[40:41]
	v_cndmask_b32_e32 v97, 0, v48, vcc
	v_pk_mul_f32 v[48:49], v[118:119], v[94:95]
	v_cmp_le_u32_e32 vcc, v25, v63
	v_pk_mul_f32 v[48:49], v[108:109], v[48:49]
	v_add_f32_e32 v94, v81, v99
	v_cndmask_b32_e32 v49, 0, v49, vcc
	v_cmp_le_u32_e32 vcc, v28, v63
	v_add_f32_e32 v95, v81, v98
	s_nop 0
	v_cndmask_b32_e32 v48, 0, v48, vcc
	v_cmp_eq_u32_e32 vcc, v22, v63
	v_add_f32_e32 v100, v81, v48
	s_nop 0
	v_cndmask_b32_e32 v94, v99, v94, vcc
	v_cmp_eq_u32_e32 vcc, v19, v63
	v_add_f32_e32 v99, v81, v102
	s_nop 0
	v_cndmask_b32_e32 v95, v98, v95, vcc
	v_add_f32_e32 v98, v81, v97
	v_cmp_eq_u32_e32 vcc, v26, v63
	v_cvt_pk_bf16_f32 v94, v94, v95
	s_nop 1
	v_cndmask_b32_e32 v97, v97, v98, vcc
	v_add_f32_e32 v98, v81, v96
	v_cmp_eq_u32_e32 vcc, v23, v63
	s_nop 1
	v_cndmask_b32_e32 v96, v96, v98, vcc
	v_add_f32_e32 v98, v81, v103
	v_cmp_eq_u32_e32 vcc, v24, v63
	v_cvt_pk_bf16_f32 v95, v97, v96
	s_nop 1
	v_cndmask_b32_e32 v98, v103, v98, vcc
	v_cmp_eq_u32_e32 vcc, v21, v63
	s_nop 1
	v_cndmask_b32_e32 v99, v102, v99, vcc
	v_cmp_eq_u32_e32 vcc, v28, v63
	v_cvt_pk_bf16_f32 v96, v98, v99
	s_nop 1
	v_cndmask_b32_e32 v48, v48, v100, vcc
	v_add_f32_e32 v100, v81, v49
	v_cmp_eq_u32_e32 vcc, v25, v63
	s_nop 1
	v_cndmask_b32_e32 v49, v49, v100, vcc
	v_cvt_pk_bf16_f32 v97, v48, v49
	v_lshl_add_u64 v[48:49], v[30:31], 0, v[36:37]
	s_waitcnt vmcnt(3)
	v_mfma_f32_16x16x32_bf16 v[44:47], v[76:79], v[94:97], v[44:47]
	global_load_dwordx4 v[76:79], v[34:35], off
	v_lshlrev_b64 v[36:37], 8, v[38:39]
	v_lshl_add_u64 v[102:103], v[30:31], 0, v[36:37]
	s_waitcnt vmcnt(3)
	v_mfma_f32_16x16x32_bf16 v[64:67], v[82:85], v[94:97], v[64:67]
	global_load_dwordx4 v[36:39], v[48:49], off
	global_load_dwordx4 v[82:85], v[102:103], off
	s_waitcnt vmcnt(4)
	v_mfma_f32_16x16x32_bf16 v[72:75], v[86:89], v[94:97], v[72:75]
	ds_read_b32 v86, v120 offset:34816
	s_waitcnt lgkmcnt(0)
	v_mul_f32_e32 v40, 0x3fb8aa3b, v86
	s_waitcnt vmcnt(3)
	v_mfma_f32_16x16x32_bf16 v[68:71], v[90:93], v[94:97], v[68:71]
	v_exp_f32_e32 v90, v40
	global_load_dwordx4 v[40:43], v[104:105], off
	global_load_dwordx4 v[86:89], v[106:107], off
	s_waitcnt vmcnt(4)
	v_lshlrev_b32_e32 v91, 16, v76
	v_and_b32_e32 v76, 0xffff0000, v76
	v_mul_f32_e32 v91, v90, v91
	v_mul_f32_e32 v76, v90, v76
	v_cvt_pk_bf16_f32 v76, v91, v76
	v_lshlrev_b32_e32 v91, 16, v77
	v_and_b32_e32 v77, 0xffff0000, v77
	v_mul_f32_e32 v91, v90, v91
	v_mul_f32_e32 v77, v90, v77
	v_cvt_pk_bf16_f32 v77, v91, v77
	v_lshlrev_b32_e32 v91, 16, v78
	v_and_b32_e32 v78, 0xffff0000, v78
	v_mul_f32_e32 v91, v90, v91
	v_mul_f32_e32 v78, v90, v78
	v_cvt_pk_bf16_f32 v78, v91, v78
	v_lshlrev_b32_e32 v91, 16, v79
	v_and_b32_e32 v79, 0xffff0000, v79
	v_mul_f32_e32 v91, v90, v91
	v_mul_f32_e32 v79, v90, v79
	v_cvt_pk_bf16_f32 v79, v91, v79
	global_load_dwordx4 v[90:93], v[34:35], off offset:64
	s_waitcnt vmcnt(3)
	v_mfma_f32_16x16x32_bf16 v[64:67], v[82:85], v[76:79], v[64:67]
	ds_read_b32 v82, v120 offset:34816
	s_waitcnt lgkmcnt(0)
	v_mul_f32_e32 v82, 0x3fb8aa3b, v82
	s_waitcnt vmcnt(2)
	v_mfma_f32_16x16x32_bf16 v[40:43], v[40:43], v[76:79], v[72:75]
	v_exp_f32_e32 v98, v82
	s_nop 1
	global_load_dwordx4 v[72:75], v[102:103], off offset:64
	v_mfma_f32_16x16x32_bf16 v[36:39], v[36:39], v[76:79], v[44:47]
	s_nop 2
	global_load_dwordx4 v[44:47], v[48:49], off offset:64
	global_load_dwordx4 v[82:85], v[104:105], off offset:64
	global_load_dwordx4 v[94:97], v[106:107], off offset:64
	s_waitcnt vmcnt(5)
	v_mfma_f32_16x16x32_bf16 v[68:71], v[86:89], v[76:79], v[68:71]
	s_waitcnt vmcnt(4)
	v_lshlrev_b32_e32 v99, 16, v90
	v_and_b32_e32 v90, 0xffff0000, v90
	v_mul_f32_e32 v99, v98, v99
	v_mul_f32_e32 v90, v98, v90
	v_cvt_pk_bf16_f32 v90, v99, v90
	v_lshlrev_b32_e32 v99, 16, v91
	v_and_b32_e32 v91, 0xffff0000, v91
	v_mul_f32_e32 v99, v98, v99
	v_mul_f32_e32 v91, v98, v91
	v_cvt_pk_bf16_f32 v91, v99, v91
	v_lshlrev_b32_e32 v99, 16, v92
	v_and_b32_e32 v92, 0xffff0000, v92
	v_mul_f32_e32 v99, v98, v99
	v_mul_f32_e32 v92, v98, v92
	v_cvt_pk_bf16_f32 v92, v99, v92
	v_lshlrev_b32_e32 v99, 16, v93
	v_and_b32_e32 v93, 0xffff0000, v93
	v_mul_f32_e32 v99, v98, v99
	v_mul_f32_e32 v93, v98, v93
	v_cvt_pk_bf16_f32 v93, v99, v93
	global_load_dwordx4 v[98:101], v[34:35], off offset:128
	global_load_dwordx4 v[76:79], v[48:49], off offset:128
	s_waitcnt vmcnt(5)
	v_mfma_f32_16x16x32_bf16 v[64:67], v[72:75], v[90:93], v[64:67]
	ds_read_b32 v72, v120 offset:34816
	s_waitcnt lgkmcnt(0)
; __device__ __forceinline__ float bflo(unsigned x) { return __uint_as_float(x << 16); }
; __device__ __forceinline__ float bfhi(unsigned x) { return __uint_as_float(x & 0xffff0000u); }
; __device__ __forceinline__ unsigned pk2(float lo, float hi) { return pg8::cvt_pk_bf16(lo, hi); }
; template <int NMT> __device__ __forceinline__ void ssd_out_item(const int ci, const int mt0, const float* DT, const bf16* XT, const bf16* BN, const bf16* CN, const bf16* HST, const bf16* Z, const float* ssd_norm, ...
;     ...
;         for (int ks = 0; ks < 4; ++ks) {
;             bf16x8 hf[4];
; #pragma unroll
;             for (int nt = 0; nt < 4; ++nt) hf[nt] = *(const bf16x8*)(HST + ((size_t)(ci * 8 + h) * 64 + 16 * nt + fr) * 128 + 32 * ks + 8 * fq);
; #pragma unroll
;             for (int mt = 0; mt < NMT; ++mt) { const int l = 16 * (mt0 + mt) + fr; const float e = __expf(sAcs[h * 64 + l]);
;                 const v4u cw = *(const v4u*)(CN + (size_t)(row0 + l) * 256 + g * 128 + 32 * ks + 8 * fq); v4u o;
; #pragma unroll
;                 for (int j = 0; j < 4; ++j) o[j] = pk2(bflo(cw[j]) * e, bfhi(cw[j]) * e);
;                 const bf16x8 cs = __builtin_bit_cast(bf16x8, o);
; #pragma unroll
;                 for (int nt = 0; nt < 4; ++nt) acc[nt][mt] = __builtin_amdgcn_mfma_f32_16x16x32_bf16(hf[nt], cs, acc[nt][mt], 0, 0, 0); }
;         }
; #pragma unroll
;         for (int mt = 0; mt < NMT; ++mt) { float ss = 0.f;
; #pragma unroll
;             for (int nt = 0; nt < 4; ++nt) { const v2u zr = *(const v2u*)(Z + (size_t)(row0 + 16 * (mt0 + mt) + fr) * 512 + h * 64 + 16 * nt + 4 * fq);
	v_mul_f32_e32 v72, 0x3fb8aa3b, v72
	v_exp_f32_e32 v89, v72
	s_waitcnt vmcnt(4)
	v_mfma_f32_16x16x32_bf16 v[36:39], v[44:47], v[90:93], v[36:39]
	global_load_dwordx4 v[44:47], v[102:103], off offset:128
	s_waitcnt vmcnt(2)
	v_lshlrev_b32_e32 v86, 16, v98
	v_and_b32_e32 v87, 0xffff0000, v98
	v_mul_f32_e32 v86, v89, v86
	v_mul_f32_e32 v87, v89, v87
	v_mfma_f32_16x16x32_bf16 v[40:43], v[82:85], v[90:93], v[40:43]
	global_load_dwordx4 v[72:75], v[104:105], off offset:128
	global_load_dwordx4 v[82:85], v[106:107], off offset:128
	v_cvt_pk_bf16_f32 v86, v86, v87
	v_lshlrev_b32_e32 v87, 16, v99
	v_and_b32_e32 v88, 0xffff0000, v99
	v_mul_f32_e32 v87, v89, v87
	v_mul_f32_e32 v88, v89, v88
	v_cvt_pk_bf16_f32 v87, v87, v88
	v_lshlrev_b32_e32 v88, 16, v100
	v_and_b32_e32 v98, 0xffff0000, v100
	v_mul_f32_e32 v88, v89, v88
	v_mul_f32_e32 v98, v89, v98
	v_cvt_pk_bf16_f32 v88, v88, v98
	v_lshlrev_b32_e32 v98, 16, v101
	v_and_b32_e32 v99, 0xffff0000, v101
	v_mul_f32_e32 v98, v89, v98
	v_mul_f32_e32 v89, v89, v99
	v_cvt_pk_bf16_f32 v89, v98, v89
	global_load_dwordx4 v[98:101], v[34:35], off offset:192
	v_mfma_f32_16x16x32_bf16 v[68:71], v[94:97], v[90:93], v[68:71]
	global_load_dwordx4 v[90:93], v[48:49], off offset:192
	ds_read_b32 v94, v120 offset:34816
	s_waitcnt vmcnt(5)
	v_mfma_f32_16x16x32_bf16 v[34:37], v[76:79], v[86:89], v[36:39]
	global_load_dwordx4 v[76:79], v[102:103], off offset:192
	s_waitcnt vmcnt(4)
	v_mfma_f32_16x16x32_bf16 v[38:41], v[72:75], v[86:89], v[40:43]
	s_nop 2
	v_lshlrev_b64 v[42:43], 10, v[32:33]
	v_lshl_add_u64 v[48:49], v[8:9], 0, v[42:43]
	s_waitcnt lgkmcnt(0)
	v_mul_f32_e32 v42, 0x3fb8aa3b, v94
	v_exp_f32_e32 v42, v42
	v_mfma_f32_16x16x32_bf16 v[44:47], v[44:47], v[86:89], v[64:67]
	global_load_dwordx4 v[72:75], v[106:107], off offset:192
	s_waitcnt vmcnt(3)
	v_lshlrev_b32_e32 v43, 16, v98
	global_load_dwordx4 v[64:67], v[104:105], off offset:192
	v_mfma_f32_16x16x32_bf16 v[68:71], v[82:85], v[86:89], v[68:71]
	v_and_b32_e32 v82, 0xffff0000, v98
	v_lshlrev_b32_e32 v83, 16, v99
	v_and_b32_e32 v84, 0xffff0000, v99
	v_lshlrev_b32_e32 v85, 16, v100
	v_and_b32_e32 v86, 0xffff0000, v100
	v_lshlrev_b32_e32 v87, 16, v101
	v_and_b32_e32 v88, 0xffff0000, v101
	v_mul_f32_e32 v82, v42, v82
	v_mul_f32_e32 v83, v42, v83
	v_mul_f32_e32 v84, v42, v84
	v_mul_f32_e32 v85, v42, v85
	v_mul_f32_e32 v86, v42, v86
	v_mul_f32_e32 v87, v42, v87
	v_mul_f32_e32 v43, v42, v43
	v_mul_f32_e32 v42, v42, v88
	v_cvt_pk_bf16_f32 v82, v43, v82
	v_cvt_pk_bf16_f32 v83, v83, v84
	v_cvt_pk_bf16_f32 v84, v85, v86
	v_cvt_pk_bf16_f32 v85, v87, v42
	global_load_dwordx2 v[86:87], v[48:49], off
	global_load_dwordx2 v[88:89], v[48:49], off offset:32
	s_waitcnt vmcnt(4)
	v_mfma_f32_16x16x32_bf16 v[42:45], v[76:79], v[82:85], v[44:47]
	global_load_dwordx2 v[76:77], v[48:49], off offset:96
	s_waitcnt vmcnt(0)
; __device__ __forceinline__ float silu_f(float x) { return x * __builtin_amdgcn_rcpf(1.0f + __builtin_amdgcn_exp2f(-1.4426950408889634f * x)); }
; __device__ __forceinline__ float bflo(unsigned x) { return __uint_as_float(x << 16); }
; __device__ __forceinline__ float bfhi(unsigned x) { return __uint_as_float(x & 0xffff0000u); }
; __device__ __forceinline__ float silu_f(float x) { return x * __builtin_amdgcn_rcpf(1.0f + __builtin_amdgcn_exp2f(-1.4426950408889634f * x)); }
; template <int NMT> __device__ __forceinline__ void ssd_out_item(const int ci, const int mt0, const float* DT, const bf16* XT, const bf16* BN, const bf16* CN, const bf16* HST, const bf16* Z, const float* ssd_norm, ...
;     ...
;         for (int mt = 0; mt < NMT; ++mt) { float ss = 0.f;
; #pragma unroll
;             for (int nt = 0; nt < 4; ++nt) { const v2u zr = *(const v2u*)(Z + (size_t)(row0 + 16 * (mt0 + mt) + fr) * 512 + h * 64 + 16 * nt + 4 * fq);
;                 f32x4 y = acc[nt][mt]; y[0] *= silu_f(bflo(zr.x)); y[1] *= silu_f(bfhi(zr.x)); y[2] *= silu_f(bflo(zr.y)); y[3] *= silu_f(bfhi(zr.y)); acc[nt][mt] = y;
;                 ss += (y[0] * y[0] + y[1] * y[1]) + (y[2] * y[2] + y[3] * y[3]); }
;             ss += __shfl_xor(ss, 16); ss += __shfl_xor(ss, 32);
;             if (fq == 0) sSS[h * 64 + 16 * (mt0 + mt) + fr] = ss; }
	v_lshlrev_b32_e32 v78, 16, v76
	global_load_dwordx2 v[46:47], v[48:49], off offset:64
	v_mfma_f32_16x16x32_bf16 v[38:41], v[64:67], v[82:85], v[38:41]
	v_lshlrev_b32_e32 v48, 16, v86
	v_and_b32_e32 v49, 0xffff0000, v86
	v_and_b32_e32 v79, 0xffff0000, v76
	v_mfma_f32_16x16x32_bf16 v[64:67], v[72:75], v[82:85], v[68:71]
	v_mul_f32_e32 v76, 0xbfb8aa3b, v48
	v_exp_f32_e32 v76, v76
	v_lshlrev_b32_e32 v72, 16, v89
	v_lshlrev_b32_e32 v68, 16, v87
	v_and_b32_e32 v69, 0xffff0000, v87
	v_mfma_f32_16x16x32_bf16 v[34:37], v[90:93], v[82:85], v[34:37]
	v_lshlrev_b32_e32 v70, 16, v88
	v_mul_f32_e32 v82, 0xbfb8aa3b, v49
	v_mul_f32_e32 v83, 0xbfb8aa3b, v68
	v_mul_f32_e32 v84, 0xbfb8aa3b, v69
	v_mul_f32_e32 v85, 0xbfb8aa3b, v70
	v_exp_f32_e32 v82, v82
	v_exp_f32_e32 v83, v83
	v_exp_f32_e32 v84, v84
	v_mul_f32_e32 v93, 0xbfb8aa3b, v78
	v_exp_f32_e32 v85, v85
	v_exp_f32_e32 v93, v93
	v_add_f32_e32 v76, 1.0, v76
	v_add_f32_e32 v95, 1.0, v82
	v_add_f32_e32 v96, 1.0, v83
	v_add_f32_e32 v97, 1.0, v84
	v_add_f32_e32 v98, 1.0, v85
	v_rcp_f32_e32 v82, v76
	v_rcp_f32_e32 v83, v95
	v_rcp_f32_e32 v84, v96
	v_rcp_f32_e32 v85, v97
	v_add_f32_e32 v106, 1.0, v93
	v_and_b32_e32 v71, 0xffff0000, v88
	v_and_b32_e32 v73, 0xffff0000, v89
	v_pk_mul_f32 v[48:49], v[82:83], v[48:49]
	v_pk_mul_f32 v[68:69], v[84:85], v[68:69]
	v_mul_f32_e32 v86, 0xbfb8aa3b, v71
	v_mul_f32_e32 v87, 0xbfb8aa3b, v72
	v_mul_f32_e32 v88, 0xbfb8aa3b, v73
	v_exp_f32_e32 v86, v86
	v_exp_f32_e32 v87, v87
	v_exp_f32_e32 v88, v88
	v_mul_f32_e32 v94, 0xbfb8aa3b, v79
	v_exp_f32_e32 v94, v94
	v_add_f32_e32 v99, 1.0, v86
	v_add_f32_e32 v100, 1.0, v87
	v_add_f32_e32 v101, 1.0, v88
	v_rcp_f32_e32 v86, v98
	v_rcp_f32_e32 v87, v99
	v_rcp_f32_e32 v88, v100
	v_add_f32_e32 v94, 1.0, v94
	v_rcp_f32_e32 v76, v106
	v_pk_mul_f32 v[70:71], v[86:87], v[70:71]
	s_waitcnt vmcnt(0)
	v_lshlrev_b32_e32 v74, 16, v46
	v_and_b32_e32 v75, 0xffff0000, v46
	v_lshlrev_b32_e32 v46, 16, v47
	v_and_b32_e32 v47, 0xffff0000, v47
	v_mul_f32_e32 v91, 0xbfb8aa3b, v46
	v_mul_f32_e32 v92, 0xbfb8aa3b, v47
	v_exp_f32_e32 v91, v91
	v_exp_f32_e32 v92, v92
	v_mul_f32_e32 v89, 0xbfb8aa3b, v74
	v_mul_f32_e32 v90, 0xbfb8aa3b, v75
	v_add_f32_e32 v104, 1.0, v91
	v_add_f32_e32 v105, 1.0, v92
	v_rcp_f32_e32 v92, v104
	v_rcp_f32_e32 v93, v105
	v_exp_f32_e32 v89, v89
	v_exp_f32_e32 v90, v90
	v_pk_mul_f32 v[42:43], v[42:43], v[70:71]
	v_pk_mul_f32 v[82:83], v[92:93], v[46:47]
	v_pk_mul_f32 v[46:47], v[34:35], v[48:49]
	v_pk_mul_f32 v[48:49], v[36:37], v[68:69]
	v_lshlrev_b32_e32 v36, 16, v77
	v_and_b32_e32 v37, 0xffff0000, v77
	v_mul_f32_e32 v34, 0xbfb8aa3b, v36
	v_exp_f32_e32 v34, v34
	v_mul_f32_e32 v35, 0xbfb8aa3b, v37
	v_exp_f32_e32 v35, v35
	v_add_f32_e32 v102, 1.0, v89
	v_add_f32_e32 v103, 1.0, v90
	v_rcp_f32_e32 v89, v101
	v_add_f32_e32 v34, 1.0, v34
	v_rcp_f32_e32 v90, v102
	v_rcp_f32_e32 v91, v103
	v_rcp_f32_e32 v84, v34
	v_add_f32_e32 v34, 1.0, v35
	v_rcp_f32_e32 v77, v94
	v_rcp_f32_e32 v85, v34
	v_pk_mul_f32 v[72:73], v[88:89], v[72:73]
	v_pk_mul_f32 v[74:75], v[90:91], v[74:75]
	v_pk_mul_f32 v[44:45], v[44:45], v[72:73]
	v_pk_mul_f32 v[38:39], v[38:39], v[74:75]
	v_pk_mul_f32 v[40:41], v[40:41], v[82:83]
	v_pk_mul_f32 v[70:71], v[48:49], v[48:49]
	v_pk_mul_f32 v[72:73], v[42:43], v[42:43]
	v_pk_mul_f32 v[74:75], v[44:45], v[44:45]
	v_pk_mul_f32 v[34:35], v[76:77], v[78:79]
	v_pk_mul_f32 v[36:37], v[84:85], v[36:37]
	v_pk_mul_f32 v[82:83], v[38:39], v[38:39]
	v_pk_mul_f32 v[86:87], v[40:41], v[40:41]
	v_pk_mul_f32 v[34:35], v[64:65], v[34:35]
	v_pk_mul_f32 v[36:37], v[66:67], v[36:37]
	v_add_f32_e32 v74, v74, v75
	v_add_f32_e32 v72, v72, v73
	v_add_f32_e32 v70, v70, v71
	v_mul_f32_e32 v68, v46, v46
	v_fma_f32 v68, v47, v47, v68
	v_pk_mul_f32 v[66:67], v[36:37], v[36:37]
	v_add_f32_e32 v72, v72, v74
	v_add_f32_e32 v68, v68, v70
	v_add_f32_e32 v69, v86, v87
	v_add_f32_e32 v70, v82, v83
	v_add_f32_e32 v68, v68, v72
	v_add_f32_e32 v69, v70, v69
	v_add_f32_e32 v66, v66, v67
	v_mul_f32_e32 v64, v34, v34
	v_fma_f32 v64, v35, v35, v64
	v_add_f32_e32 v68, v68, v69
	v_add_f32_e32 v64, v64, v66
	v_add_f32_e32 v64, v68, v64
	ds_bpermute_b32 v65, v55, v64
	s_waitcnt lgkmcnt(0)
	v_add_f32_e32 v64, v64, v65
	ds_bpermute_b32 v65, v56, v64
	s_and_saveexec_b64 s[14:15], s[8:9]
	s_cbranch_execz .LBB0_1169
	v_lshl_add_u32 v66, s21, 6, v57
	s_waitcnt lgkmcnt(0)
	v_add_f32_e32 v64, v64, v65
	ds_write_b32 v66, v64 offset:38912
	s_branch .LBB0_1169
